# hot loop heads (attention tile loop, scan loop) and GEMM peeled-trip entries pinned to 64-byte boundaries; on top of v118
# baseline (speedup 1.0000x reference)
;     __device__ bool next(int i, Unit& u) const { if (!so.next(i >> 1, u)) return false; u.sel = i & 1; return true; }
; #define PG8_STAGE(bufoff, gbase, voff) do { _Pragma("unroll") for (int _i = 0; _i < 2; ++_i) \
;         __builtin_amdgcn_global_load_lds((const unsigned*)((const char*)(gbase) + (voff)[_i]), (PG8_LAS unsigned*)(lds + (bufoff) + ldsw + _i * 8192), 16, 0, 0); } while (0)
; #define PG8_LDA(dst, b, h) do { _Pragma("unroll") for (int m = 0; m < 4; ++m) _Pragma("unroll") for (int k = 0; k < 2; ++k) dst[m][k] = *(const PG8_LAS bf16x8*)(lds + PG8_SA(b, h) + aoff + m * 2048 + k * 1024); } while (0)
; #define PG8_LDB(dst, b, h) do { _Pragma("unroll") for (int n = 0; n < 2; ++n) _Pragma("unroll") for (int k = 0; k < 2; ++k) dst[n][k] = *(const PG8_LAS bf16x8*)(lds + PG8_SB(b, h) + boff + n * 2048 + k * 1024); } while (0)
; #define PG8_MMA(ai, bj, At, Bt) do { __builtin_amdgcn_s_setprio(1); _Pragma("unroll") for (int m = 0; m < 4; ++m) _Pragma("unroll") for (int n = 0; n < 2; ++n) _Pragma("unroll") for (int k = 0; k < 2; ++k) \
;         acc[ai][bj][m][n] = __builtin_amdgcn_mfma_f32_16x16x32_bf16(Bt[n][k], At[m][k], acc[ai][bj][m][n], 0, 0, 0); __builtin_amdgcn_s_setprio(0); } while (0)
; template <class Epi, class Sched, bool ALIGN_EPI = false, bool SP2 = false>
; __device__ __forceinline__ void gemm_phase(PG8_LAS unsigned char* lds, const Gemm g, const Sched& S, const Epi& E) {
;     ...
;         const bool has_next = S.next(ui + 1, nxt);
;         const char* nA = has_next ? (const char*)(nxt.sel ? g.A2 : g.A) + (size_t)nxt.pm * tstep : cA; const char* nB = has_next ? (const char*)(nxt.sel ? g.Bt2 : g.Bt) + (size_t)nxt.pn * tstep : cB;
;         for (int t = 0; t < nt; t += 2) {
;             const bool last = (t == nt - 2);
;             const char* a1 = cA + (size_t)(t + 1) * kstep;
;             const char* a2 = last ? nA : cA + (size_t)(t + 2) * kstep; const char* b2 = last ? nB : cB + (size_t)(t + 2) * kstep;
;             const char* a3 = a2 + kstep; const char* b3 = b2 + kstep;
;             if (last && has_next) S.a_ready(nxt);
;             if constexpr (SP2) {
;             PG8_LDB(B0, 0, 0); PG8_LDB(B1, 0, 1); PG8_SCHED; PG8_LDA(At, 0, 0); PG8_STAGE(PG8_SA(1, 1), a1 + hstep, voffA);
;             PG8_WAIT_V(8); PG8_WAIT_L(0); PG8_BAR; PG8_MMA(0, 0, At, B0); PG8_MMA(0, 1, At, B1); PG8_BAR; PG8_SCHED;
.Lcz_go_216:
	v_mov_b32_e32 v1, 0
	s_cmp_eq_u32 s48, 0x100
	s_cselect_b32 s100, 1, 0
	s_cmp_eq_u32 s49, 26
	s_cselect_b32 s101, s32, 0
	s_or_b32 s100, s100, s101
	s_add_u32 s0, s72, 0x80
	s_addc_u32 s1, s73, 0
	s_add_u32 s61, s6, 0x100
	s_addc_u32 s72, s7, 0
	s_mov_b32 s6, 0
	.p2alignl 6, 3212836864
	ds_read_b128 v[130:133], v178
	ds_read_b128 v[134:137], v178 offset:1024
	ds_read_b128 v[138:141], v178 offset:2048
	ds_read_b128 v[142:145], v178 offset:3072
	ds_read_b128 v[168:171], v179
	ds_read_b128 v[172:175], v179 offset:1024
	ds_read_b128 v[182:185], v179 offset:2048
	ds_read_b128 v[186:189], v179 offset:3072
	s_add_i32 s73, s6, 2
	s_add_u32 vcc_lo, s0, 0x80
	s_addc_u32 s7, s1, 0
	s_cmp_eq_u32 s92, s6
	s_cselect_b32 s6, s62, vcc_lo
	s_cselect_b32 s7, s63, s7
	s_cselect_b32 vcc_hi, s71, s72
	s_cselect_b32 vcc_lo, s70, s61
	v_lshl_add_u64 v[198:199], s[0:1], 0, v[160:161]
	s_add_i32 m0, s77, 0xc000
	ds_read_b128 v[190:193], v180
	ds_read_b128 v[194:197], v180 offset:1024
	ds_read_b128 v[202:205], v180 offset:2048
	ds_read_b128 v[206:209], v180 offset:3072
	ds_read_b128 v[210:213], v180 offset:4096
	ds_read_b128 v[214:217], v180 offset:5120
	ds_read_b128 v[218:221], v180 offset:6144
	ds_read_b128 v[222:225], v180 offset:7168
	global_load_lds_dwordx4 v[198:199], off
	v_lshl_add_u64 v[198:199], s[0:1], 0, v[162:163]
	s_add_i32 m0, s77, 0xe000
	s_nop 0
	global_load_lds_dwordx4 v[198:199], off
	s_waitcnt vmcnt(8)
	s_waitcnt lgkmcnt(0)
	s_barrier
	s_setprio 1
	s_waitcnt lgkmcnt(0)
	s_bitcmp1_b32 s100, 1
	s_cbranch_scc1 .Lcz_z0_216
	v_mfma_f32_16x16x32_bf16 v[126:129], v[130:133], v[190:193], 0
	v_mfma_f32_16x16x32_bf16 v[122:125], v[138:141], v[190:193], 0
	v_mfma_f32_16x16x32_bf16 v[110:113], v[130:133], v[202:205], 0
	v_mfma_f32_16x16x32_bf16 v[106:109], v[138:141], v[202:205], 0
	v_mfma_f32_16x16x32_bf16 v[94:97], v[130:133], v[210:213], 0
	v_mfma_f32_16x16x32_bf16 v[90:93], v[138:141], v[210:213], 0
	v_mfma_f32_16x16x32_bf16 v[78:81], v[130:133], v[218:221], 0
	v_mfma_f32_16x16x32_bf16 v[74:77], v[138:141], v[218:221], 0
	v_mfma_f32_16x16x32_bf16 v[126:129], v[134:137], v[194:197], v[126:129]
	v_mfma_f32_16x16x32_bf16 v[122:125], v[142:145], v[194:197], v[122:125]
	v_mfma_f32_16x16x32_bf16 v[110:113], v[134:137], v[206:209], v[110:113]
	v_mfma_f32_16x16x32_bf16 v[106:109], v[142:145], v[206:209], v[106:109]
	v_mfma_f32_16x16x32_bf16 v[94:97], v[134:137], v[214:217], v[94:97]
	v_mfma_f32_16x16x32_bf16 v[90:93], v[142:145], v[214:217], v[90:93]
	v_mfma_f32_16x16x32_bf16 v[78:81], v[134:137], v[222:225], v[78:81]
	v_mfma_f32_16x16x32_bf16 v[74:77], v[142:145], v[222:225], v[74:77]
	s_setprio 0
	s_setprio 1
	v_mfma_f32_16x16x32_bf16 v[118:121], v[168:171], v[190:193], 0
	v_mfma_f32_16x16x32_bf16 v[114:117], v[182:185], v[190:193], 0
	v_mfma_f32_16x16x32_bf16 v[102:105], v[168:171], v[202:205], 0
	v_mfma_f32_16x16x32_bf16 v[98:101], v[182:185], v[202:205], 0
	v_mfma_f32_16x16x32_bf16 v[86:89], v[168:171], v[210:213], 0
	v_mfma_f32_16x16x32_bf16 v[82:85], v[182:185], v[210:213], 0
	v_mfma_f32_16x16x32_bf16 v[70:73], v[168:171], v[218:221], 0
	v_mfma_f32_16x16x32_bf16 v[66:69], v[182:185], v[218:221], 0
	v_mfma_f32_16x16x32_bf16 v[118:121], v[172:175], v[194:197], v[118:121]
	v_mfma_f32_16x16x32_bf16 v[114:117], v[186:189], v[194:197], v[114:117]
	v_mfma_f32_16x16x32_bf16 v[102:105], v[172:175], v[206:209], v[102:105]
	v_mfma_f32_16x16x32_bf16 v[98:101], v[186:189], v[206:209], v[98:101]
	v_mfma_f32_16x16x32_bf16 v[86:89], v[172:175], v[214:217], v[86:89]
	v_mfma_f32_16x16x32_bf16 v[82:85], v[186:189], v[214:217], v[82:85]
	v_mfma_f32_16x16x32_bf16 v[70:73], v[172:175], v[222:225], v[70:73]
	v_mfma_f32_16x16x32_bf16 v[66:69], v[186:189], v[222:225], v[66:69]

; __device__ __forceinline__ void scan_gate(const LAS unsigned char* raw, ScanSt& st, LAS unsigned char* buf, float lb, int w, int l16, int g) {
;     ...
;     for (int j = 0; j < 4; ++j) { const float x = bf2f(rf[j]); const float sg = __builtin_amdgcn_rcpf(1.0f + __builtin_amdgcn_exp2f(-x * L2E));
;         const float f = lb + (1.0f - lb) * sg; kk[j] = (1.0f - lb) * (1.0f - sg); run += __builtin_amdgcn_logf(f); cs[j] = run; qv[j] = bf2f(rq[j]); }
;     const float T = run, t1 = __shfl_xor(T, 16), t2 = __shfl_xor(T, 32), t3 = __shfl_xor(t1, 32);
;     const float E = g == 0 ? 0.f : (g == 1 ? t1 : (g == 2 ? (t2 + t3) : (t1 + t2 + t3))), blast = (T + t1) + (t2 + t3);
;     float qd[4], ki[4], ks[4]; const float dec = __builtin_amdgcn_exp2f(blast);
;     float fq_[4], ib[4];
; #pragma unroll
;     for (int j = 0; j < 4; ++j) { const float bj = E + cs[j]; qd[j] = qv[j] * __builtin_amdgcn_exp2f(bj); fq_[j] = 1.0f - kk[j]; }
;     ib[3] = __builtin_amdgcn_exp2f(-(E + cs[3])); ib[2] = ib[3] * fq_[3]; ib[1] = ib[2] * fq_[2]; ib[0] = ib[1] * fq_[1];
; #pragma unroll
;     for (int j = 0; j < 4; ++j) { ki[j] = kk[j] * ib[j]; ks[j] = ki[j] * dec; }
;     const int colb = (16 * w + l16) * 2;
;     const unsigned q01 = cvtpk(qd[0], qd[1]), q23 = cvtpk(qd[2], qd[3]), k01 = cvtpk(ki[0], ki[1]), k23 = cvtpk(ki[2], ki[3]);
;     LAS unsigned char* qp = buf + SC_QD + (4 * g) * SC_RS + colb; LAS unsigned char* kp = buf + SC_KI + (4 * g) * SC_RS + colb;
;     *(LAS unsigned short*)(qp) = (unsigned short)(q01 & 0xffffu); *(LAS unsigned short*)(qp + SC_RS) = (unsigned short)(q01 >> 16);
;     *(LAS unsigned short*)(qp + 2 * SC_RS) = (unsigned short)(q23 & 0xffffu); *(LAS unsigned short*)(qp + 3 * SC_RS) = (unsigned short)(q23 >> 16);
;     *(LAS unsigned short*)(kp) = (unsigned short)(k01 & 0xffffu); *(LAS unsigned short*)(kp + SC_RS) = (unsigned short)(k01 >> 16);
;     *(LAS unsigned short*)(kp + 2 * SC_RS) = (unsigned short)(k23 & 0xffffu); *(LAS unsigned short*)(kp + 3 * SC_RS) = (unsigned short)(k23 >> 16);
;     *(LAS u32x2*)(buf + SC_KST + (16 * w + l16) * 32 + 8 * g) = (u32x2){cvtpk(ks[0], ks[1]), cvtpk(ks[2], ks[3])};
;     if (g == 0) *(LAS float*)(buf + SC_DEC + (16 * w + l16) * 4) = dec;
;     st.vf = __builtin_bit_cast(s16x4, (u32x2){rv[0] | (rv[1] << 16), rv[2] | (rv[3] << 16)});
; #pragma unroll
;     for (int j = 0; j < 4; ++j) st.gv[j] = bf2f(rg[j]);
.LBB0_381:
	s_or_b64 exec, exec, s[56:57]
	v_lshlrev_b32_e32 v32, 16, v24
	v_lshlrev_b32_e32 v24, 16, v0
	v_add_f32_e32 v0, v29, v30
	v_exp_f32_e32 v34, v0
	v_add_f32_e32 v0, v28, v30
	v_exp_f32_e32 v35, v0
	v_add_f32_e32 v0, v27, v30
	s_waitcnt lgkmcnt(0)
	v_pk_add_f32 v[18:19], v[12:13], v[18:19]
	v_exp_f32_e32 v12, v0
	v_add_f32_e32 v0, v13, v30
	v_exp_f32_e32 v13, v0
	v_lshlrev_b32_e32 v25, 16, v25
	v_pk_add_f32 v[14:15], v[14:15], 1.0 op_sel_hi:[1,0] neg_lo:[1,0] neg_hi:[1,0]
	v_pk_add_f32 v[16:17], v[16:17], 1.0 op_sel_hi:[1,0] neg_lo:[1,0] neg_hi:[1,0]
	v_pk_mul_f32 v[12:13], v[12:13], v[24:25]
	v_exp_f32_e64 v25, -v0
	v_pk_mul_f32 v[14:15], v[126:127], v[14:15] op_sel_hi:[0,1]
	v_sub_f32_e32 v24, 1.0, v15
	v_add_f32_e32 v0, v18, v19
	v_pk_mul_f32 v[16:17], v[126:127], v[16:17] op_sel_hi:[0,1]
	v_sub_f32_e32 v29, 1.0, v14
	v_exp_f32_e32 v0, v0
	v_mul_f32_e32 v24, v24, v25
	v_sub_f32_e32 v28, 1.0, v17
	v_mul_f32_e32 v19, v29, v24
	v_lshlrev_b32_e32 v33, 16, v26
	v_mul_f32_e32 v18, v28, v19
	v_pk_mul_f32 v[26:27], v[34:35], v[32:33]
	v_pk_mul_f32 v[16:17], v[16:17], v[18:19]
	v_pk_mul_f32 v[14:15], v[14:15], v[24:25]
	v_pk_mul_f32 v[18:19], v[0:1], v[16:17] op_sel_hi:[0,1]
	v_pk_mul_f32 v[24:25], v[0:1], v[14:15] op_sel_hi:[0,1]
	v_cvt_pk_bf16_f32 v26, v26, v27
	v_cvt_pk_bf16_f32 v12, v12, v13
	v_cvt_pk_bf16_f32 v13, v16, v17
	v_add_u32_e32 v163, v144, v143
	v_cvt_pk_bf16_f32 v14, v14, v15
	ds_write_b16 v163, v26
	ds_write_b16_d16_hi v163, v26 offset:272
	ds_write_b16 v163, v12 offset:544
	ds_write_b16_d16_hi v163, v12 offset:816
	ds_write_b16 v163, v13 offset:4352
	ds_write_b16_d16_hi v163, v13 offset:4624
	ds_write_b16 v163, v14 offset:4896
	ds_write_b16_d16_hi v163, v14 offset:5168
	v_cvt_pk_bf16_f32 v12, v18, v19
	v_cvt_pk_bf16_f32 v13, v24, v25
	v_add_u32_e32 v164, v145, v146
	ds_write_b64 v164, v[12:13] offset:8704
	s_and_saveexec_b64 s[56:57], s[0:1]
	ds_write_b32 v155, v0 offset:12800
	s_or_b64 exec, exec, s[56:57]
	v_lshlrev_b32_e32 v0, 16, v22
	v_or_b32_sdwa v130, v0, v20 dst_sel:DWORD dst_unused:UNUSED_PAD src0_sel:DWORD src1_sel:WORD_0
	v_lshlrev_b32_e32 v0, 16, v23
	v_or_b32_sdwa v131, v0, v21 dst_sel:DWORD dst_unused:UNUSED_PAD src0_sel:DWORD src1_sel:WORD_0
	v_xor_b32_e32 v0, 1, v105
	v_cmp_lt_i32_e32 vcc, v0, v153
	v_mov_b32_e32 v13, s55
	v_or_b32_e32 v12, s54, v114
	v_cndmask_b32_e32 v0, v105, v0, vcc
	v_lshlrev_b32_e32 v165, 2, v0
	v_xor_b32_e32 v0, 2, v105
	v_cmp_lt_i32_e32 vcc, v0, v153
	v_lshl_add_u64 v[2:3], v[2:3], 1, s[38:39]
	v_lshlrev_b64 v[12:13], 11, v[12:13]
	v_cndmask_b32_e32 v0, v105, v0, vcc
	v_lshlrev_b32_e32 v166, 2, v0
	v_xor_b32_e32 v0, 4, v105
	v_cmp_lt_i32_e32 vcc, v0, v153
	s_waitcnt lgkmcnt(0)
	s_barrier
	v_lshl_add_u64 v[128:129], v[2:3], 0, v[12:13]
	v_mov_b32_e32 v2, v1
	v_cndmask_b32_e32 v0, v105, v0, vcc
	v_lshlrev_b32_e32 v167, 2, v0
	v_xor_b32_e32 v0, 8, v105
	v_cmp_lt_i32_e32 vcc, v0, v153
	v_mov_b32_e32 v3, v1
	v_mov_b32_e32 v20, 0
	v_cndmask_b32_e32 v0, v105, v0, vcc
	v_lshlrev_b32_e32 v168, 2, v0
	v_mov_b32_e32 v0, v1
	v_mov_b64_e32 v[102:103], v[2:3]
	v_mov_b32_e32 v127, v126
	s_mov_b32 s49, 0
	v_mov_b64_e32 v[100:101], v[0:1]
	v_mov_b32_e32 v21, v20
	v_mov_b32_e32 v22, v20
	v_mov_b32_e32 v23, v20
	v_mov_b32_e32 v28, v20
	v_mov_b32_e32 v29, v20
	v_mov_b32_e32 v30, v20
	v_mov_b32_e32 v31, v20
	v_mov_b32_e32 v24, v20
	v_mov_b32_e32 v25, v20
	v_mov_b32_e32 v26, v20
	v_mov_b32_e32 v27, v20
	v_mov_b32_e32 v32, v20
	v_mov_b32_e32 v33, v20
	v_mov_b32_e32 v34, v20
	v_mov_b32_e32 v35, v20
	v_mov_b32_e32 v36, v20
	v_mov_b32_e32 v37, v20
	v_mov_b32_e32 v38, v20
	v_mov_b32_e32 v39, v20
	v_mov_b32_e32 v40, v20
	v_mov_b32_e32 v41, v20
	v_mov_b32_e32 v42, v20
	v_mov_b32_e32 v43, v20
	v_mov_b32_e32 v44, v20
	v_mov_b32_e32 v45, v20
	v_mov_b32_e32 v46, v20
	v_mov_b32_e32 v47, v20
	v_mov_b32_e32 v48, v20
	v_mov_b32_e32 v49, v20
	v_mov_b32_e32 v50, v20
	v_mov_b32_e32 v51, v20
	.p2alignl 6, 3212836864

; #define PG8_STAGE(bufoff, gbase, voff) do { _Pragma("unroll") for (int _i = 0; _i < 2; ++_i) \
;         __builtin_amdgcn_global_load_lds((const unsigned*)((const char*)(gbase) + (voff)[_i]), (PG8_LAS unsigned*)(lds + (bufoff) + ldsw + _i * 8192), 16, 0, 0); } while (0)
; #define PG8_LDA(dst, b, h) do { _Pragma("unroll") for (int m = 0; m < 4; ++m) _Pragma("unroll") for (int k = 0; k < 2; ++k) dst[m][k] = *(const PG8_LAS bf16x8*)(lds + PG8_SA(b, h) + aoff + m * 2048 + k * 1024); } while (0)
; #define PG8_LDB(dst, b, h) do { _Pragma("unroll") for (int n = 0; n < 2; ++n) _Pragma("unroll") for (int k = 0; k < 2; ++k) dst[n][k] = *(const PG8_LAS bf16x8*)(lds + PG8_SB(b, h) + boff + n * 2048 + k * 1024); } while (0)
; #define PG8_MMA(ai, bj, At, Bt) do { __builtin_amdgcn_s_setprio(1); _Pragma("unroll") for (int m = 0; m < 4; ++m) _Pragma("unroll") for (int n = 0; n < 2; ++n) _Pragma("unroll") for (int k = 0; k < 2; ++k) \
;         acc[ai][bj][m][n] = __builtin_amdgcn_mfma_f32_16x16x32_bf16(Bt[n][k], At[m][k], acc[ai][bj][m][n], 0, 0, 0); __builtin_amdgcn_s_setprio(0); } while (0)
; #define PG8_WAIT_V(n) asm volatile("s_waitcnt vmcnt(" #n ")" ::: "memory")
; #define PG8_WAIT_L(n) asm volatile("s_waitcnt lgkmcnt(" #n ")" ::: "memory")
; #define PG8_BAR __builtin_amdgcn_s_barrier()
; #define PG8_SCHED __builtin_amdgcn_sched_barrier(0)
; template <class Epi, class Sched, bool ALIGN_EPI = false, bool SP2 = false>
; __device__ __forceinline__ void gemm_phase(PG8_LAS unsigned char* lds, const Gemm g, const Sched& S, const Epi& E) {
;     ...
;             PG8_LDB(B0, 0, 0); PG8_LDB(B1, 0, 1); PG8_SCHED; PG8_LDA(At, 0, 0); PG8_STAGE(PG8_SA(1, 1), a1 + hstep, voffA);
;             PG8_WAIT_V(8); PG8_WAIT_L(0); PG8_BAR; PG8_MMA(0, 0, At, B0); PG8_MMA(0, 1, At, B1); PG8_BAR; PG8_SCHED;
;             PG8_LDA(At, 0, 1); PG8_STAGE(PG8_SB(0, 0), b2, voffB); PG8_STAGE(PG8_SB(0, 1), b2 + hstep, voffB); PG8_STAGE(PG8_SA(0, 0), a2, voffA);
;             PG8_WAIT_V(8); PG8_WAIT_L(0); PG8_BAR; PG8_MMA(1, 0, At, B0); PG8_MMA(1, 1, At, B1); PG8_BAR; PG8_SCHED;
.Lcz_go_460:
	s_add_u32 s0, s62, 0x80
	s_addc_u32 s1, s63, 0
	s_add_u32 s62, s60, 0x100
	s_addc_u32 s63, s61, 0
	s_mov_b32 s60, 0
	.p2alignl 6, 3212836864
	ds_read_b128 v[146:149], v154
	ds_read_b128 v[158:161], v154 offset:1024
	ds_read_b128 v[162:165], v154 offset:2048
	ds_read_b128 v[166:169], v154 offset:3072
	ds_read_b128 v[170:173], v155
	ds_read_b128 v[174:177], v155 offset:1024
	ds_read_b128 v[178:181], v155 offset:2048
	ds_read_b128 v[182:185], v155 offset:3072
	s_add_i32 s97, s60, 2
	s_add_u32 s16, s0, 0x80
	s_addc_u32 s17, s1, 0
	s_cmp_eq_u32 s80, s60
	s_cselect_b32 s60, s56, s16
	s_cselect_b32 s61, s57, s17
	s_cselect_b32 vcc_hi, s59, s63
	s_cselect_b32 vcc_lo, s58, s62
	v_lshl_add_u64 v[150:151], s[0:1], 0, v[138:139]
	s_add_i32 m0, s72, 0xc000
	ds_read_b128 v[186:189], v156
	ds_read_b128 v[190:193], v156 offset:1024
	ds_read_b128 v[194:197], v156 offset:2048
	ds_read_b128 v[202:205], v156 offset:3072
	ds_read_b128 v[206:209], v156 offset:4096
	ds_read_b128 v[210:213], v156 offset:5120
	ds_read_b128 v[214:217], v156 offset:6144
	ds_read_b128 v[218:221], v156 offset:7168
	global_load_lds_dwordx4 v[150:151], off
	v_lshl_add_u64 v[150:151], s[0:1], 0, v[140:141]
	s_add_i32 m0, s72, 0xe000
	s_nop 0
	global_load_lds_dwordx4 v[150:151], off
	s_waitcnt vmcnt(8)
	s_waitcnt lgkmcnt(0)
	s_barrier
	s_setprio 1
	s_waitcnt lgkmcnt(0)
	v_mfma_f32_16x16x32_bf16 v[120:123], v[146:149], v[186:189], 0
	v_mfma_f32_16x16x32_bf16 v[124:127], v[162:165], v[186:189], 0
	v_mfma_f32_16x16x32_bf16 v[108:111], v[146:149], v[194:197], 0
	v_mfma_f32_16x16x32_bf16 v[104:107], v[162:165], v[194:197], 0
	v_mfma_f32_16x16x32_bf16 v[92:95], v[146:149], v[206:209], 0
	v_mfma_f32_16x16x32_bf16 v[88:91], v[162:165], v[206:209], 0
	v_mfma_f32_16x16x32_bf16 v[76:79], v[146:149], v[214:217], 0
	v_mfma_f32_16x16x32_bf16 v[72:75], v[162:165], v[214:217], 0
	v_mfma_f32_16x16x32_bf16 v[120:123], v[158:161], v[190:193], v[120:123]
	v_mfma_f32_16x16x32_bf16 v[124:127], v[166:169], v[190:193], v[124:127]
	v_mfma_f32_16x16x32_bf16 v[108:111], v[158:161], v[202:205], v[108:111]
	v_mfma_f32_16x16x32_bf16 v[104:107], v[166:169], v[202:205], v[104:107]
	v_mfma_f32_16x16x32_bf16 v[92:95], v[158:161], v[210:213], v[92:95]
	v_mfma_f32_16x16x32_bf16 v[88:91], v[166:169], v[210:213], v[88:91]
	v_mfma_f32_16x16x32_bf16 v[76:79], v[158:161], v[218:221], v[76:79]
	v_mfma_f32_16x16x32_bf16 v[72:75], v[166:169], v[218:221], v[72:75]
	s_setprio 0
	s_setprio 1
	v_mfma_f32_16x16x32_bf16 v[116:119], v[170:173], v[186:189], 0
	v_mfma_f32_16x16x32_bf16 v[112:115], v[178:181], v[186:189], 0
	v_mfma_f32_16x16x32_bf16 v[100:103], v[170:173], v[194:197], 0
	v_mfma_f32_16x16x32_bf16 v[96:99], v[178:181], v[194:197], 0
	v_mfma_f32_16x16x32_bf16 v[84:87], v[170:173], v[206:209], 0
	v_mfma_f32_16x16x32_bf16 v[80:83], v[178:181], v[206:209], 0
	v_mfma_f32_16x16x32_bf16 v[68:71], v[170:173], v[214:217], 0
	v_mfma_f32_16x16x32_bf16 v[64:67], v[178:181], v[214:217], 0
	v_mfma_f32_16x16x32_bf16 v[116:119], v[174:177], v[190:193], v[116:119]
	v_mfma_f32_16x16x32_bf16 v[112:115], v[182:185], v[190:193], v[112:115]
	v_mfma_f32_16x16x32_bf16 v[100:103], v[174:177], v[202:205], v[100:103]
	v_mfma_f32_16x16x32_bf16 v[96:99], v[182:185], v[202:205], v[96:99]
	v_mfma_f32_16x16x32_bf16 v[84:87], v[174:177], v[210:213], v[84:87]
	v_mfma_f32_16x16x32_bf16 v[80:83], v[182:185], v[210:213], v[80:83]
	v_mfma_f32_16x16x32_bf16 v[68:71], v[174:177], v[218:221], v[68:71]
	v_mfma_f32_16x16x32_bf16 v[64:67], v[182:185], v[218:221], v[64:67]
	s_setprio 0
	s_barrier
	s_add_i32 s16, s83, s49
	v_lshl_add_u64 v[150:151], vcc, 0, v[132:133]
	s_mov_b32 m0, s16
	ds_read_b128 v[186:189], v156 offset:16384
	ds_read_b128 v[190:193], v156 offset:17408
	ds_read_b128 v[194:197], v156 offset:18432
	ds_read_b128 v[202:205], v156 offset:19456
	ds_read_b128 v[206:209], v156 offset:20480
	ds_read_b128 v[210:213], v156 offset:21504
	ds_read_b128 v[214:217], v156 offset:22528
	ds_read_b128 v[218:221], v156 offset:23552
	global_load_lds_dwordx4 v[150:151], off
	s_add_i32 m0, s16, 0x2000
	v_lshl_add_u64 v[198:199], vcc, 0, v[128:129]
	s_add_u32 vcc_lo, vcc_lo, s8
	s_addc_u32 vcc_hi, vcc_hi, s9
	s_add_i32 s16, s84, s49
	global_load_lds_dwordx4 v[198:199], off
	v_lshl_add_u64 v[222:223], vcc, 0, v[132:133]
	s_mov_b32 m0, s16
	v_lshl_add_u64 v[224:225], vcc, 0, v[128:129]
	global_load_lds_dwordx4 v[222:223], off
	s_add_i32 m0, s16, 0x2000
	v_lshl_add_u64 v[226:227], s[60:61], 0, v[134:135]
	global_load_lds_dwordx4 v[224:225], off
	s_mov_b32 m0, s72
	v_lshl_add_u64 v[228:229], s[60:61], 0, v[130:131]
	global_load_lds_dwordx4 v[226:227], off
	s_mov_b32 m0, s73
	s_nop 0
	global_load_lds_dwordx4 v[228:229], off
	s_waitcnt vmcnt(8)
	s_waitcnt lgkmcnt(0)
	s_barrier
; #define PG8_STAGE(bufoff, gbase, voff) do { _Pragma("unroll") for (int _i = 0; _i < 2; ++_i) \
;         __builtin_amdgcn_global_load_lds((const unsigned*)((const char*)(gbase) + (voff)[_i]), (PG8_LAS unsigned*)(lds + (bufoff) + ldsw + _i * 8192), 16, 0, 0); } while (0)
; #define PG8_LDA(dst, b, h) do { _Pragma("unroll") for (int m = 0; m < 4; ++m) _Pragma("unroll") for (int k = 0; k < 2; ++k) dst[m][k] = *(const PG8_LAS bf16x8*)(lds + PG8_SA(b, h) + aoff + m * 2048 + k * 1024); } while (0)
; #define PG8_LDB(dst, b, h) do { _Pragma("unroll") for (int n = 0; n < 2; ++n) _Pragma("unroll") for (int k = 0; k < 2; ++k) dst[n][k] = *(const PG8_LAS bf16x8*)(lds + PG8_SB(b, h) + boff + n * 2048 + k * 1024); } while (0)
; #define PG8_MMA(ai, bj, At, Bt) do { __builtin_amdgcn_s_setprio(1); _Pragma("unroll") for (int m = 0; m < 4; ++m) _Pragma("unroll") for (int n = 0; n < 2; ++n) _Pragma("unroll") for (int k = 0; k < 2; ++k) \
;         acc[ai][bj][m][n] = __builtin_amdgcn_mfma_f32_16x16x32_bf16(Bt[n][k], At[m][k], acc[ai][bj][m][n], 0, 0, 0); __builtin_amdgcn_s_setprio(0); } while (0)
; #define PG8_WAIT_V(n) asm volatile("s_waitcnt vmcnt(" #n ")" ::: "memory")
; #define PG8_WAIT_L(n) asm volatile("s_waitcnt lgkmcnt(" #n ")" ::: "memory")
; #define PG8_BAR __builtin_amdgcn_s_barrier()
; #define PG8_SCHED __builtin_amdgcn_sched_barrier(0)
; template <class Epi, class Sched, bool ALIGN_EPI = false, bool SP2 = false>
; __device__ __forceinline__ void gemm_phase(PG8_LAS unsigned char* lds, const Gemm g, const Sched& S, const Epi& E) {
;     ...
;             PG8_WAIT_V(8); PG8_WAIT_L(0); PG8_BAR; PG8_MMA(1, 0, At, B0); PG8_MMA(1, 1, At, B1); PG8_BAR; PG8_SCHED;
;             PG8_LDB(B0, 1, 0); PG8_LDB(B1, 1, 1); PG8_SCHED; PG8_LDA(At, 1, 0); PG8_STAGE(PG8_SA(0, 1), a2 + hstep, voffA);
;             PG8_WAIT_V(8); PG8_WAIT_L(0); PG8_BAR; PG8_MMA(0, 0, At, B0); PG8_MMA(0, 1, At, B1); PG8_BAR; PG8_SCHED;
	s_setprio 1
	s_waitcnt lgkmcnt(0)
	v_mfma_f32_16x16x32_bf16 v[60:63], v[146:149], v[186:189], 0
	v_mfma_f32_16x16x32_bf16 v[56:59], v[162:165], v[186:189], 0
	v_mfma_f32_16x16x32_bf16 v[44:47], v[146:149], v[194:197], 0
	v_mfma_f32_16x16x32_bf16 v[40:43], v[162:165], v[194:197], 0
	v_mfma_f32_16x16x32_bf16 v[28:31], v[146:149], v[206:209], 0
	v_mfma_f32_16x16x32_bf16 v[24:27], v[162:165], v[206:209], 0
	v_mfma_f32_16x16x32_bf16 v[12:15], v[146:149], v[214:217], 0
	v_mfma_f32_16x16x32_bf16 v[8:11], v[162:165], v[214:217], 0
	v_mfma_f32_16x16x32_bf16 v[60:63], v[158:161], v[190:193], v[60:63]
	v_mfma_f32_16x16x32_bf16 v[56:59], v[166:169], v[190:193], v[56:59]
	v_mfma_f32_16x16x32_bf16 v[44:47], v[158:161], v[202:205], v[44:47]
	v_mfma_f32_16x16x32_bf16 v[40:43], v[166:169], v[202:205], v[40:43]
	v_mfma_f32_16x16x32_bf16 v[28:31], v[158:161], v[210:213], v[28:31]
	v_mfma_f32_16x16x32_bf16 v[24:27], v[166:169], v[210:213], v[24:27]
	v_mfma_f32_16x16x32_bf16 v[12:15], v[158:161], v[218:221], v[12:15]
	v_mfma_f32_16x16x32_bf16 v[8:11], v[166:169], v[218:221], v[8:11]
	s_setprio 0
	s_setprio 1
	v_mfma_f32_16x16x32_bf16 v[52:55], v[170:173], v[186:189], 0
	v_mfma_f32_16x16x32_bf16 v[48:51], v[178:181], v[186:189], 0
	v_mfma_f32_16x16x32_bf16 v[36:39], v[170:173], v[194:197], 0
	v_mfma_f32_16x16x32_bf16 v[32:35], v[178:181], v[194:197], 0
	v_mfma_f32_16x16x32_bf16 v[20:23], v[170:173], v[206:209], 0
	v_mfma_f32_16x16x32_bf16 v[16:19], v[178:181], v[206:209], 0
	v_mfma_f32_16x16x32_bf16 v[4:7], v[170:173], v[214:217], 0
	v_mfma_f32_16x16x32_bf16 v[0:3], v[178:181], v[214:217], 0
	v_mfma_f32_16x16x32_bf16 v[52:55], v[174:177], v[190:193], v[52:55]
	v_mfma_f32_16x16x32_bf16 v[48:51], v[182:185], v[190:193], v[48:51]
	v_mfma_f32_16x16x32_bf16 v[36:39], v[174:177], v[202:205], v[36:39]
	v_mfma_f32_16x16x32_bf16 v[32:35], v[182:185], v[202:205], v[32:35]
	v_mfma_f32_16x16x32_bf16 v[20:23], v[174:177], v[210:213], v[20:23]
	v_mfma_f32_16x16x32_bf16 v[16:19], v[182:185], v[210:213], v[16:19]
	v_mfma_f32_16x16x32_bf16 v[4:7], v[174:177], v[218:221], v[4:7]
	v_mfma_f32_16x16x32_bf16 v[0:3], v[182:185], v[218:221], v[0:3]
	s_setprio 0
	s_barrier
	s_add_i32 s16, 0, 0x18000
	s_add_i32 s17, 0, 0x1c000
	v_add_u32_e32 v166, s16, v153
	v_add_u32_e32 v182, s17, v153
	ds_read_b128 v[146:149], v166
	ds_read_b128 v[158:161], v166 offset:1024
	ds_read_b128 v[162:165], v166 offset:2048
	ds_read_b128 v[166:169], v166 offset:3072
	ds_read_b128 v[170:173], v182
	ds_read_b128 v[174:177], v182 offset:1024
	ds_read_b128 v[178:181], v182 offset:2048
	ds_read_b128 v[182:185], v182 offset:3072
	s_add_u32 s60, s60, s8
	s_addc_u32 s61, s61, s9
	s_mov_b32 m0, s74
	v_lshl_add_u64 v[230:231], s[60:61], 0, v[134:135]
	ds_read_b128 v[186:189], v156 offset:32768
	ds_read_b128 v[190:193], v156 offset:33792
	ds_read_b128 v[194:197], v156 offset:34816
	ds_read_b128 v[202:205], v156 offset:35840
	ds_read_b128 v[206:209], v156 offset:36864
	ds_read_b128 v[210:213], v156 offset:37888
	ds_read_b128 v[214:217], v156 offset:38912
	ds_read_b128 v[218:221], v156 offset:39936
	global_load_lds_dwordx4 v[230:231], off
	v_lshl_add_u64 v[230:231], s[60:61], 0, v[130:131]
	s_mov_b32 m0, s75
	s_nop 0
	global_load_lds_dwordx4 v[230:231], off
	s_waitcnt vmcnt(8)
	s_waitcnt lgkmcnt(0)
	s_barrier
	s_setprio 1
	s_waitcnt lgkmcnt(0)
	v_mfma_f32_16x16x32_bf16 v[120:123], v[146:149], v[186:189], v[120:123]
	v_mfma_f32_16x16x32_bf16 v[124:127], v[162:165], v[186:189], v[124:127]
	v_mfma_f32_16x16x32_bf16 v[108:111], v[146:149], v[194:197], v[108:111]
	v_mfma_f32_16x16x32_bf16 v[104:107], v[162:165], v[194:197], v[104:107]
	v_mfma_f32_16x16x32_bf16 v[92:95], v[146:149], v[206:209], v[92:95]
	v_mfma_f32_16x16x32_bf16 v[88:91], v[162:165], v[206:209], v[88:91]
	v_mfma_f32_16x16x32_bf16 v[76:79], v[146:149], v[214:217], v[76:79]
	v_mfma_f32_16x16x32_bf16 v[72:75], v[162:165], v[214:217], v[72:75]
	v_mfma_f32_16x16x32_bf16 v[120:123], v[158:161], v[190:193], v[120:123]
	v_mfma_f32_16x16x32_bf16 v[124:127], v[166:169], v[190:193], v[124:127]
	v_mfma_f32_16x16x32_bf16 v[108:111], v[158:161], v[202:205], v[108:111]
	v_mfma_f32_16x16x32_bf16 v[104:107], v[166:169], v[202:205], v[104:107]
	v_mfma_f32_16x16x32_bf16 v[92:95], v[158:161], v[210:213], v[92:95]
	v_mfma_f32_16x16x32_bf16 v[88:91], v[166:169], v[210:213], v[88:91]
	v_mfma_f32_16x16x32_bf16 v[76:79], v[158:161], v[218:221], v[76:79]
	v_mfma_f32_16x16x32_bf16 v[72:75], v[166:169], v[218:221], v[72:75]
	s_setprio 0
	s_setprio 1
	v_mfma_f32_16x16x32_bf16 v[116:119], v[170:173], v[186:189], v[116:119]
	v_mfma_f32_16x16x32_bf16 v[112:115], v[178:181], v[186:189], v[112:115]
	v_mfma_f32_16x16x32_bf16 v[100:103], v[170:173], v[194:197], v[100:103]
	v_mfma_f32_16x16x32_bf16 v[96:99], v[178:181], v[194:197], v[96:99]
	v_mfma_f32_16x16x32_bf16 v[84:87], v[170:173], v[206:209], v[84:87]
	v_mfma_f32_16x16x32_bf16 v[80:83], v[178:181], v[206:209], v[80:83]
	v_mfma_f32_16x16x32_bf16 v[68:71], v[170:173], v[214:217], v[68:71]
	v_mfma_f32_16x16x32_bf16 v[64:67], v[178:181], v[214:217], v[64:67]
	v_mfma_f32_16x16x32_bf16 v[116:119], v[174:177], v[190:193], v[116:119]
	v_mfma_f32_16x16x32_bf16 v[112:115], v[182:185], v[190:193], v[112:115]
	v_mfma_f32_16x16x32_bf16 v[100:103], v[174:177], v[202:205], v[100:103]
	v_mfma_f32_16x16x32_bf16 v[96:99], v[182:185], v[202:205], v[96:99]
	v_mfma_f32_16x16x32_bf16 v[84:87], v[174:177], v[210:213], v[84:87]
	v_mfma_f32_16x16x32_bf16 v[80:83], v[182:185], v[210:213], v[80:83]
	v_mfma_f32_16x16x32_bf16 v[68:71], v[174:177], v[218:221], v[68:71]
	v_mfma_f32_16x16x32_bf16 v[64:67], v[182:185], v[218:221], v[64:67]
	s_setprio 0
	s_barrier
; #define PG8_STAGE(bufoff, gbase, voff) do { _Pragma("unroll") for (int _i = 0; _i < 2; ++_i) \
;         __builtin_amdgcn_global_load_lds((const unsigned*)((const char*)(gbase) + (voff)[_i]), (PG8_LAS unsigned*)(lds + (bufoff) + ldsw + _i * 8192), 16, 0, 0); } while (0)
; #define PG8_LDA(dst, b, h) do { _Pragma("unroll") for (int m = 0; m < 4; ++m) _Pragma("unroll") for (int k = 0; k < 2; ++k) dst[m][k] = *(const PG8_LAS bf16x8*)(lds + PG8_SA(b, h) + aoff + m * 2048 + k * 1024); } while (0)
; #define PG8_MMA(ai, bj, At, Bt) do { __builtin_amdgcn_s_setprio(1); _Pragma("unroll") for (int m = 0; m < 4; ++m) _Pragma("unroll") for (int n = 0; n < 2; ++n) _Pragma("unroll") for (int k = 0; k < 2; ++k) \
;         acc[ai][bj][m][n] = __builtin_amdgcn_mfma_f32_16x16x32_bf16(Bt[n][k], At[m][k], acc[ai][bj][m][n], 0, 0, 0); __builtin_amdgcn_s_setprio(0); } while (0)
; #define PG8_WAIT_V(n) asm volatile("s_waitcnt vmcnt(" #n ")" ::: "memory")
; #define PG8_WAIT_L(n) asm volatile("s_waitcnt lgkmcnt(" #n ")" ::: "memory")
; #define PG8_BAR __builtin_amdgcn_s_barrier()
; #define PG8_SCHED __builtin_amdgcn_sched_barrier(0)
; template <class Epi, class Sched, bool ALIGN_EPI = false, bool SP2 = false>
; __device__ __forceinline__ void gemm_phase(PG8_LAS unsigned char* lds, const Gemm g, const Sched& S, const Epi& E) {
;     ...
;         for (int t = 0; t < nt; t += 2) {
;             const bool last = (t == nt - 2);
;             const char* a1 = cA + (size_t)(t + 1) * kstep;
;             const char* a2 = last ? nA : cA + (size_t)(t + 2) * kstep; const char* b2 = last ? nB : cB + (size_t)(t + 2) * kstep;
;             const char* a3 = a2 + kstep; const char* b3 = b2 + kstep;
;     ...
;             PG8_LDA(At, 1, 1); PG8_STAGE(PG8_SB(1, 0), b3, voffB); PG8_STAGE(PG8_SB(1, 1), b3 + hstep, voffB); PG8_STAGE(PG8_SA(1, 0), a3, voffA);
;             PG8_WAIT_V(8); PG8_WAIT_L(0); PG8_BAR; PG8_MMA(1, 0, At, B0); PG8_MMA(1, 1, At, B1); PG8_BAR; PG8_SCHED;
	s_add_i32 s16, s16, s49
	v_lshl_add_u64 v[150:151], v[150:151], 0, s[14:15]
	s_mov_b32 m0, s16
	ds_read_b128 v[186:189], v156 offset:49152
	ds_read_b128 v[190:193], v156 offset:50176
	ds_read_b128 v[194:197], v156 offset:51200
	ds_read_b128 v[202:205], v156 offset:52224
	ds_read_b128 v[206:209], v156 offset:53248
	ds_read_b128 v[210:213], v156 offset:54272
	ds_read_b128 v[214:217], v156 offset:55296
	ds_read_b128 v[218:221], v156 offset:56320
	global_load_lds_dwordx4 v[150:151], off
	v_lshl_add_u64 v[150:151], v[198:199], 0, s[14:15]
	s_add_i32 m0, s16, 0x2000
	s_add_i32 s16, s17, s49
	global_load_lds_dwordx4 v[150:151], off
	v_lshl_add_u64 v[150:151], v[222:223], 0, s[14:15]
	s_mov_b32 m0, s16
	s_nop 0
	global_load_lds_dwordx4 v[150:151], off
	v_lshl_add_u64 v[150:151], v[224:225], 0, s[14:15]
	s_add_i32 m0, s16, 0x2000
	s_nop 0
	global_load_lds_dwordx4 v[150:151], off
	v_lshl_add_u64 v[150:151], v[226:227], 0, s[14:15]
	s_mov_b32 m0, s77
	s_nop 0
	global_load_lds_dwordx4 v[150:151], off
	v_lshl_add_u64 v[150:151], v[228:229], 0, s[14:15]
	s_mov_b32 m0, s78
	s_nop 0
	global_load_lds_dwordx4 v[150:151], off
	s_waitcnt vmcnt(8)
	s_waitcnt lgkmcnt(0)
	s_barrier
	s_setprio 1
	s_waitcnt lgkmcnt(0)
	v_mfma_f32_16x16x32_bf16 v[60:63], v[146:149], v[186:189], v[60:63]
	v_mfma_f32_16x16x32_bf16 v[56:59], v[162:165], v[186:189], v[56:59]
	v_mfma_f32_16x16x32_bf16 v[44:47], v[146:149], v[194:197], v[44:47]
	v_mfma_f32_16x16x32_bf16 v[40:43], v[162:165], v[194:197], v[40:43]
	v_mfma_f32_16x16x32_bf16 v[28:31], v[146:149], v[206:209], v[28:31]
	v_mfma_f32_16x16x32_bf16 v[24:27], v[162:165], v[206:209], v[24:27]
	v_mfma_f32_16x16x32_bf16 v[12:15], v[146:149], v[214:217], v[12:15]
	v_mfma_f32_16x16x32_bf16 v[8:11], v[162:165], v[214:217], v[8:11]
	v_mfma_f32_16x16x32_bf16 v[60:63], v[158:161], v[190:193], v[60:63]
	v_mfma_f32_16x16x32_bf16 v[56:59], v[166:169], v[190:193], v[56:59]
	v_mfma_f32_16x16x32_bf16 v[44:47], v[158:161], v[202:205], v[44:47]
	v_mfma_f32_16x16x32_bf16 v[40:43], v[166:169], v[202:205], v[40:43]
	v_mfma_f32_16x16x32_bf16 v[28:31], v[158:161], v[210:213], v[28:31]
	v_mfma_f32_16x16x32_bf16 v[24:27], v[166:169], v[210:213], v[24:27]
	v_mfma_f32_16x16x32_bf16 v[12:15], v[158:161], v[218:221], v[12:15]
	v_mfma_f32_16x16x32_bf16 v[8:11], v[166:169], v[218:221], v[8:11]
	s_setprio 0
	s_setprio 1
	v_mfma_f32_16x16x32_bf16 v[52:55], v[170:173], v[186:189], v[52:55]
	v_mfma_f32_16x16x32_bf16 v[48:51], v[178:181], v[186:189], v[48:51]
	v_mfma_f32_16x16x32_bf16 v[36:39], v[170:173], v[194:197], v[36:39]
	v_mfma_f32_16x16x32_bf16 v[32:35], v[178:181], v[194:197], v[32:35]
	v_mfma_f32_16x16x32_bf16 v[20:23], v[170:173], v[206:209], v[20:23]
	v_mfma_f32_16x16x32_bf16 v[16:19], v[178:181], v[206:209], v[16:19]
	v_mfma_f32_16x16x32_bf16 v[4:7], v[170:173], v[214:217], v[4:7]
	v_mfma_f32_16x16x32_bf16 v[0:3], v[178:181], v[214:217], v[0:3]
	v_mfma_f32_16x16x32_bf16 v[52:55], v[174:177], v[190:193], v[52:55]
	v_mfma_f32_16x16x32_bf16 v[48:51], v[182:185], v[190:193], v[48:51]
	v_mfma_f32_16x16x32_bf16 v[36:39], v[174:177], v[202:205], v[36:39]
	v_mfma_f32_16x16x32_bf16 v[32:35], v[182:185], v[202:205], v[32:35]
	v_mfma_f32_16x16x32_bf16 v[20:23], v[174:177], v[210:213], v[20:23]
	v_mfma_f32_16x16x32_bf16 v[16:19], v[182:185], v[210:213], v[16:19]
	v_mfma_f32_16x16x32_bf16 v[4:7], v[174:177], v[218:221], v[4:7]
	v_mfma_f32_16x16x32_bf16 v[0:3], v[182:185], v[218:221], v[0:3]
	s_setprio 0
	s_barrier
	s_add_u32 s0, s0, 0x100
	s_addc_u32 s1, s1, 0
	s_add_u32 s62, s62, 0x100
	s_addc_u32 s63, s63, 0
	s_cmp_ge_i32 s97, s79
	s_mov_b32 s60, s97
	s_cbranch_scc1 .LBB0_461

; #define PG8_STAGE(bufoff, gbase, voff) do { _Pragma("unroll") for (int _i = 0; _i < 2; ++_i) \
;         __builtin_amdgcn_global_load_lds((const unsigned*)((const char*)(gbase) + (voff)[_i]), (PG8_LAS unsigned*)(lds + (bufoff) + ldsw + _i * 8192), 16, 0, 0); } while (0)
; #define PG8_LDA(dst, b, h) do { _Pragma("unroll") for (int m = 0; m < 4; ++m) _Pragma("unroll") for (int k = 0; k < 2; ++k) dst[m][k] = *(const PG8_LAS bf16x8*)(lds + PG8_SA(b, h) + aoff + m * 2048 + k * 1024); } while (0)
; #define PG8_LDB(dst, b, h) do { _Pragma("unroll") for (int n = 0; n < 2; ++n) _Pragma("unroll") for (int k = 0; k < 2; ++k) dst[n][k] = *(const PG8_LAS bf16x8*)(lds + PG8_SB(b, h) + boff + n * 2048 + k * 1024); } while (0)
; #define PG8_MMA(ai, bj, At, Bt) do { __builtin_amdgcn_s_setprio(1); _Pragma("unroll") for (int m = 0; m < 4; ++m) _Pragma("unroll") for (int n = 0; n < 2; ++n) _Pragma("unroll") for (int k = 0; k < 2; ++k) \
;         acc[ai][bj][m][n] = __builtin_amdgcn_mfma_f32_16x16x32_bf16(Bt[n][k], At[m][k], acc[ai][bj][m][n], 0, 0, 0); __builtin_amdgcn_s_setprio(0); } while (0)
; #define PG8_WAIT_V(n) asm volatile("s_waitcnt vmcnt(" #n ")" ::: "memory")
; #define PG8_WAIT_L(n) asm volatile("s_waitcnt lgkmcnt(" #n ")" ::: "memory")
; #define PG8_BAR __builtin_amdgcn_s_barrier()
; #define PG8_SCHED __builtin_amdgcn_sched_barrier(0)
; template <class Epi, class Sched, bool ALIGN_EPI = false, bool SP2 = false>
; __device__ __forceinline__ void gemm_phase(PG8_LAS unsigned char* lds, const Gemm g, const Sched& S, const Epi& E) {
;     ...
;             PG8_LDB(B0, 0, 0); PG8_LDB(B1, 0, 1); PG8_SCHED; PG8_LDA(At, 0, 0); PG8_STAGE(PG8_SA(1, 1), a1 + hstep, voffA);
;             PG8_WAIT_V(8); PG8_WAIT_L(0); PG8_BAR; PG8_MMA(0, 0, At, B0); PG8_MMA(0, 1, At, B1); PG8_BAR; PG8_SCHED;
;             PG8_LDA(At, 0, 1); PG8_STAGE(PG8_SB(0, 0), b2, voffB); PG8_STAGE(PG8_SB(0, 1), b2 + hstep, voffB); PG8_STAGE(PG8_SA(0, 0), a2, voffA);
;             PG8_WAIT_V(8); PG8_WAIT_L(0); PG8_BAR; PG8_MMA(1, 0, At, B0); PG8_MMA(1, 1, At, B1); PG8_BAR; PG8_SCHED;
.Lcz_go_535:
	s_add_u32 s58, s58, 0x80
	s_addc_u32 s59, s59, 0
	s_add_u32 s95, s60, 0x100
	s_addc_u32 s96, s61, 0
	s_mov_b32 s60, 0
	.p2alignl 6, 3212836864
	ds_read_b128 v[128:131], v166
	ds_read_b128 v[156:159], v166 offset:1024
	ds_read_b128 v[160:163], v166 offset:2048
	ds_read_b128 v[170:173], v166 offset:3072
	ds_read_b128 v[174:177], v167
	ds_read_b128 v[178:181], v167 offset:1024
	ds_read_b128 v[182:185], v167 offset:2048
	ds_read_b128 v[186:189], v167 offset:3072
	s_add_i32 s97, s60, 2
	s_add_u32 s16, s58, 0x80
	s_addc_u32 s17, s59, 0
	s_cmp_eq_u32 s76, s60
	s_cselect_b32 s60, s0, s16
	s_cselect_b32 s61, s1, s17
	s_cselect_b32 vcc_hi, s57, s96
	s_cselect_b32 vcc_lo, s56, s95
	v_lshl_add_u64 v[198:199], s[58:59], 0, v[148:149]
	s_add_i32 m0, s62, 0xc000
	ds_read_b128 v[190:193], v168
	ds_read_b128 v[194:197], v168 offset:1024
	ds_read_b128 v[202:205], v168 offset:2048
	ds_read_b128 v[206:209], v168 offset:3072
	ds_read_b128 v[210:213], v168 offset:4096
	ds_read_b128 v[214:217], v168 offset:5120
	ds_read_b128 v[218:221], v168 offset:6144
	ds_read_b128 v[222:225], v168 offset:7168
	global_load_lds_dwordx4 v[198:199], off
	v_lshl_add_u64 v[198:199], s[58:59], 0, v[150:151]
	s_add_i32 m0, s62, 0xe000
	s_nop 0
	global_load_lds_dwordx4 v[198:199], off
	s_waitcnt vmcnt(8)
	s_waitcnt lgkmcnt(0)
	s_barrier
	s_setprio 1
	s_waitcnt lgkmcnt(0)
	v_mfma_f32_16x16x32_bf16 v[120:123], v[128:131], v[190:193], 0
	v_mfma_f32_16x16x32_bf16 v[124:127], v[160:163], v[190:193], 0
	v_mfma_f32_16x16x32_bf16 v[108:111], v[128:131], v[202:205], 0
	v_mfma_f32_16x16x32_bf16 v[104:107], v[160:163], v[202:205], 0
	v_mfma_f32_16x16x32_bf16 v[92:95], v[128:131], v[210:213], 0
	v_mfma_f32_16x16x32_bf16 v[88:91], v[160:163], v[210:213], 0
	v_mfma_f32_16x16x32_bf16 v[76:79], v[128:131], v[218:221], 0
	v_mfma_f32_16x16x32_bf16 v[72:75], v[160:163], v[218:221], 0
	v_mfma_f32_16x16x32_bf16 v[120:123], v[156:159], v[194:197], v[120:123]
	v_mfma_f32_16x16x32_bf16 v[124:127], v[170:173], v[194:197], v[124:127]
	v_mfma_f32_16x16x32_bf16 v[108:111], v[156:159], v[206:209], v[108:111]
	v_mfma_f32_16x16x32_bf16 v[104:107], v[170:173], v[206:209], v[104:107]
	v_mfma_f32_16x16x32_bf16 v[92:95], v[156:159], v[214:217], v[92:95]
	v_mfma_f32_16x16x32_bf16 v[88:91], v[170:173], v[214:217], v[88:91]
	v_mfma_f32_16x16x32_bf16 v[76:79], v[156:159], v[222:225], v[76:79]
	v_mfma_f32_16x16x32_bf16 v[72:75], v[170:173], v[222:225], v[72:75]
	s_setprio 0
	s_setprio 1
	v_mfma_f32_16x16x32_bf16 v[116:119], v[174:177], v[190:193], 0
	v_mfma_f32_16x16x32_bf16 v[112:115], v[182:185], v[190:193], 0
	v_mfma_f32_16x16x32_bf16 v[100:103], v[174:177], v[202:205], 0
	v_mfma_f32_16x16x32_bf16 v[96:99], v[182:185], v[202:205], 0
	v_mfma_f32_16x16x32_bf16 v[84:87], v[174:177], v[210:213], 0
	v_mfma_f32_16x16x32_bf16 v[80:83], v[182:185], v[210:213], 0
	v_mfma_f32_16x16x32_bf16 v[68:71], v[174:177], v[218:221], 0
	v_mfma_f32_16x16x32_bf16 v[64:67], v[182:185], v[218:221], 0
	v_mfma_f32_16x16x32_bf16 v[116:119], v[178:181], v[194:197], v[116:119]
	v_mfma_f32_16x16x32_bf16 v[112:115], v[186:189], v[194:197], v[112:115]
	v_mfma_f32_16x16x32_bf16 v[100:103], v[178:181], v[206:209], v[100:103]
	v_mfma_f32_16x16x32_bf16 v[96:99], v[186:189], v[206:209], v[96:99]
	v_mfma_f32_16x16x32_bf16 v[84:87], v[178:181], v[214:217], v[84:87]
	v_mfma_f32_16x16x32_bf16 v[80:83], v[186:189], v[214:217], v[80:83]
	v_mfma_f32_16x16x32_bf16 v[68:71], v[178:181], v[222:225], v[68:71]
	v_mfma_f32_16x16x32_bf16 v[64:67], v[186:189], v[222:225], v[64:67]
	s_setprio 0
	s_barrier
	s_add_i32 s16, s79, s49
	v_lshl_add_u64 v[198:199], vcc, 0, v[134:135]
	s_mov_b32 m0, s16
	ds_read_b128 v[190:193], v168 offset:16384
	ds_read_b128 v[194:197], v168 offset:17408
	ds_read_b128 v[202:205], v168 offset:18432
	ds_read_b128 v[206:209], v168 offset:19456
	ds_read_b128 v[210:213], v168 offset:20480
	ds_read_b128 v[214:217], v168 offset:21504
	ds_read_b128 v[218:221], v168 offset:22528
	ds_read_b128 v[222:225], v168 offset:23552
	global_load_lds_dwordx4 v[198:199], off
	s_add_i32 m0, s16, 0x2000
	v_lshl_add_u64 v[226:227], vcc, 0, v[138:139]
	s_add_u32 vcc_lo, vcc_lo, s8
	s_addc_u32 vcc_hi, vcc_hi, s9
	s_add_i32 s16, s80, s49
	global_load_lds_dwordx4 v[226:227], off
	v_lshl_add_u64 v[228:229], vcc, 0, v[134:135]
	s_mov_b32 m0, s16
	v_lshl_add_u64 v[230:231], vcc, 0, v[138:139]
	global_load_lds_dwordx4 v[228:229], off
	s_add_i32 m0, s16, 0x2000
	v_lshl_add_u64 v[232:233], s[60:61], 0, v[132:133]
	global_load_lds_dwordx4 v[230:231], off
	s_mov_b32 m0, s62
	v_lshl_add_u64 v[236:237], s[60:61], 0, v[136:137]
	global_load_lds_dwordx4 v[232:233], off
	s_mov_b32 m0, s63
	s_nop 0
	global_load_lds_dwordx4 v[236:237], off
	s_waitcnt vmcnt(8)
	s_waitcnt lgkmcnt(0)
	s_barrier
; #define PG8_STAGE(bufoff, gbase, voff) do { _Pragma("unroll") for (int _i = 0; _i < 2; ++_i) \
;         __builtin_amdgcn_global_load_lds((const unsigned*)((const char*)(gbase) + (voff)[_i]), (PG8_LAS unsigned*)(lds + (bufoff) + ldsw + _i * 8192), 16, 0, 0); } while (0)
; #define PG8_LDA(dst, b, h) do { _Pragma("unroll") for (int m = 0; m < 4; ++m) _Pragma("unroll") for (int k = 0; k < 2; ++k) dst[m][k] = *(const PG8_LAS bf16x8*)(lds + PG8_SA(b, h) + aoff + m * 2048 + k * 1024); } while (0)
; #define PG8_LDB(dst, b, h) do { _Pragma("unroll") for (int n = 0; n < 2; ++n) _Pragma("unroll") for (int k = 0; k < 2; ++k) dst[n][k] = *(const PG8_LAS bf16x8*)(lds + PG8_SB(b, h) + boff + n * 2048 + k * 1024); } while (0)
; #define PG8_MMA(ai, bj, At, Bt) do { __builtin_amdgcn_s_setprio(1); _Pragma("unroll") for (int m = 0; m < 4; ++m) _Pragma("unroll") for (int n = 0; n < 2; ++n) _Pragma("unroll") for (int k = 0; k < 2; ++k) \
;         acc[ai][bj][m][n] = __builtin_amdgcn_mfma_f32_16x16x32_bf16(Bt[n][k], At[m][k], acc[ai][bj][m][n], 0, 0, 0); __builtin_amdgcn_s_setprio(0); } while (0)
; #define PG8_WAIT_V(n) asm volatile("s_waitcnt vmcnt(" #n ")" ::: "memory")
; #define PG8_WAIT_L(n) asm volatile("s_waitcnt lgkmcnt(" #n ")" ::: "memory")
; #define PG8_BAR __builtin_amdgcn_s_barrier()
; #define PG8_SCHED __builtin_amdgcn_sched_barrier(0)
; template <class Epi, class Sched, bool ALIGN_EPI = false, bool SP2 = false>
; __device__ __forceinline__ void gemm_phase(PG8_LAS unsigned char* lds, const Gemm g, const Sched& S, const Epi& E) {
;     ...
;             PG8_WAIT_V(8); PG8_WAIT_L(0); PG8_BAR; PG8_MMA(1, 0, At, B0); PG8_MMA(1, 1, At, B1); PG8_BAR; PG8_SCHED;
;             PG8_LDB(B0, 1, 0); PG8_LDB(B1, 1, 1); PG8_SCHED; PG8_LDA(At, 1, 0); PG8_STAGE(PG8_SA(0, 1), a2 + hstep, voffA);
;             PG8_WAIT_V(8); PG8_WAIT_L(0); PG8_BAR; PG8_MMA(0, 0, At, B0); PG8_MMA(0, 1, At, B1); PG8_BAR; PG8_SCHED;
	s_setprio 1
	s_waitcnt lgkmcnt(0)
	v_mfma_f32_16x16x32_bf16 v[60:63], v[128:131], v[190:193], 0
	v_mfma_f32_16x16x32_bf16 v[56:59], v[160:163], v[190:193], 0
	v_mfma_f32_16x16x32_bf16 v[44:47], v[128:131], v[202:205], 0
	v_mfma_f32_16x16x32_bf16 v[40:43], v[160:163], v[202:205], 0
	v_mfma_f32_16x16x32_bf16 v[28:31], v[128:131], v[210:213], 0
	v_mfma_f32_16x16x32_bf16 v[24:27], v[160:163], v[210:213], 0
	v_mfma_f32_16x16x32_bf16 v[12:15], v[128:131], v[218:221], 0
	v_mfma_f32_16x16x32_bf16 v[8:11], v[160:163], v[218:221], 0
	v_mfma_f32_16x16x32_bf16 v[60:63], v[156:159], v[194:197], v[60:63]
	v_mfma_f32_16x16x32_bf16 v[56:59], v[170:173], v[194:197], v[56:59]
	v_mfma_f32_16x16x32_bf16 v[44:47], v[156:159], v[206:209], v[44:47]
	v_mfma_f32_16x16x32_bf16 v[40:43], v[170:173], v[206:209], v[40:43]
	v_mfma_f32_16x16x32_bf16 v[28:31], v[156:159], v[214:217], v[28:31]
	v_mfma_f32_16x16x32_bf16 v[24:27], v[170:173], v[214:217], v[24:27]
	v_mfma_f32_16x16x32_bf16 v[12:15], v[156:159], v[222:225], v[12:15]
	v_mfma_f32_16x16x32_bf16 v[8:11], v[170:173], v[222:225], v[8:11]
	s_setprio 0
	s_setprio 1
	v_mfma_f32_16x16x32_bf16 v[52:55], v[174:177], v[190:193], 0
	v_mfma_f32_16x16x32_bf16 v[48:51], v[182:185], v[190:193], 0
	v_mfma_f32_16x16x32_bf16 v[36:39], v[174:177], v[202:205], 0
	v_mfma_f32_16x16x32_bf16 v[32:35], v[182:185], v[202:205], 0
	v_mfma_f32_16x16x32_bf16 v[20:23], v[174:177], v[210:213], 0
	v_mfma_f32_16x16x32_bf16 v[16:19], v[182:185], v[210:213], 0
	v_mfma_f32_16x16x32_bf16 v[4:7], v[174:177], v[218:221], 0
	v_mfma_f32_16x16x32_bf16 v[0:3], v[182:185], v[218:221], 0
	v_mfma_f32_16x16x32_bf16 v[52:55], v[178:181], v[194:197], v[52:55]
	v_mfma_f32_16x16x32_bf16 v[48:51], v[186:189], v[194:197], v[48:51]
	v_mfma_f32_16x16x32_bf16 v[36:39], v[178:181], v[206:209], v[36:39]
	v_mfma_f32_16x16x32_bf16 v[32:35], v[186:189], v[206:209], v[32:35]
	v_mfma_f32_16x16x32_bf16 v[20:23], v[178:181], v[214:217], v[20:23]
	v_mfma_f32_16x16x32_bf16 v[16:19], v[186:189], v[214:217], v[16:19]
	v_mfma_f32_16x16x32_bf16 v[4:7], v[178:181], v[222:225], v[4:7]
	v_mfma_f32_16x16x32_bf16 v[0:3], v[186:189], v[222:225], v[0:3]
	s_setprio 0
	s_barrier
	s_add_i32 s16, 0, 0x18000
	v_add_u32_e32 v140, s16, v165
	s_add_i32 s17, 0, 0x1c000
	ds_read_b128 v[128:131], v140
	ds_read_b128 v[156:159], v140 offset:1024
	ds_read_b128 v[160:163], v140 offset:2048
	ds_read_b128 v[170:173], v140 offset:3072
	v_add_u32_e32 v140, s17, v165
	ds_read_b128 v[174:177], v140
	ds_read_b128 v[178:181], v140 offset:1024
	ds_read_b128 v[182:185], v140 offset:2048
	ds_read_b128 v[186:189], v140 offset:3072
	s_add_u32 s60, s60, s8
	s_addc_u32 s61, s61, s9
	s_mov_b32 m0, s70
	v_lshl_add_u64 v[238:239], s[60:61], 0, v[132:133]
	ds_read_b128 v[190:193], v168 offset:32768
	ds_read_b128 v[194:197], v168 offset:33792
	ds_read_b128 v[202:205], v168 offset:34816
	ds_read_b128 v[206:209], v168 offset:35840
	ds_read_b128 v[210:213], v168 offset:36864
	ds_read_b128 v[214:217], v168 offset:37888
	ds_read_b128 v[218:221], v168 offset:38912
	ds_read_b128 v[222:225], v168 offset:39936
	global_load_lds_dwordx4 v[238:239], off
	v_lshl_add_u64 v[238:239], s[60:61], 0, v[136:137]
	s_mov_b32 m0, s71
	s_nop 0
	global_load_lds_dwordx4 v[238:239], off
	s_waitcnt vmcnt(8)
	s_waitcnt lgkmcnt(0)
	s_barrier
	s_setprio 1
	s_waitcnt lgkmcnt(0)
	v_mfma_f32_16x16x32_bf16 v[120:123], v[128:131], v[190:193], v[120:123]
	v_mfma_f32_16x16x32_bf16 v[124:127], v[160:163], v[190:193], v[124:127]
	v_mfma_f32_16x16x32_bf16 v[108:111], v[128:131], v[202:205], v[108:111]
	v_mfma_f32_16x16x32_bf16 v[104:107], v[160:163], v[202:205], v[104:107]
	v_mfma_f32_16x16x32_bf16 v[92:95], v[128:131], v[210:213], v[92:95]
	v_mfma_f32_16x16x32_bf16 v[88:91], v[160:163], v[210:213], v[88:91]
	v_mfma_f32_16x16x32_bf16 v[76:79], v[128:131], v[218:221], v[76:79]
	v_mfma_f32_16x16x32_bf16 v[72:75], v[160:163], v[218:221], v[72:75]
	v_mfma_f32_16x16x32_bf16 v[120:123], v[156:159], v[194:197], v[120:123]
	v_mfma_f32_16x16x32_bf16 v[124:127], v[170:173], v[194:197], v[124:127]
	v_mfma_f32_16x16x32_bf16 v[108:111], v[156:159], v[206:209], v[108:111]
	v_mfma_f32_16x16x32_bf16 v[104:107], v[170:173], v[206:209], v[104:107]
	v_mfma_f32_16x16x32_bf16 v[92:95], v[156:159], v[214:217], v[92:95]
	v_mfma_f32_16x16x32_bf16 v[88:91], v[170:173], v[214:217], v[88:91]
	v_mfma_f32_16x16x32_bf16 v[76:79], v[156:159], v[222:225], v[76:79]
	v_mfma_f32_16x16x32_bf16 v[72:75], v[170:173], v[222:225], v[72:75]
	s_setprio 0
	s_setprio 1
	v_mfma_f32_16x16x32_bf16 v[116:119], v[174:177], v[190:193], v[116:119]
	v_mfma_f32_16x16x32_bf16 v[112:115], v[182:185], v[190:193], v[112:115]
	v_mfma_f32_16x16x32_bf16 v[100:103], v[174:177], v[202:205], v[100:103]
	v_mfma_f32_16x16x32_bf16 v[96:99], v[182:185], v[202:205], v[96:99]
	v_mfma_f32_16x16x32_bf16 v[84:87], v[174:177], v[210:213], v[84:87]
	v_mfma_f32_16x16x32_bf16 v[80:83], v[182:185], v[210:213], v[80:83]
	v_mfma_f32_16x16x32_bf16 v[68:71], v[174:177], v[218:221], v[68:71]
	v_mfma_f32_16x16x32_bf16 v[64:67], v[182:185], v[218:221], v[64:67]
	v_mfma_f32_16x16x32_bf16 v[116:119], v[178:181], v[194:197], v[116:119]
	v_mfma_f32_16x16x32_bf16 v[112:115], v[186:189], v[194:197], v[112:115]
	v_mfma_f32_16x16x32_bf16 v[100:103], v[178:181], v[206:209], v[100:103]
	v_mfma_f32_16x16x32_bf16 v[96:99], v[186:189], v[206:209], v[96:99]
	v_mfma_f32_16x16x32_bf16 v[84:87], v[178:181], v[214:217], v[84:87]
	v_mfma_f32_16x16x32_bf16 v[80:83], v[186:189], v[214:217], v[80:83]
	v_mfma_f32_16x16x32_bf16 v[68:71], v[178:181], v[222:225], v[68:71]
	v_mfma_f32_16x16x32_bf16 v[64:67], v[186:189], v[222:225], v[64:67]
	s_setprio 0
	s_barrier
; #define PG8_STAGE(bufoff, gbase, voff) do { _Pragma("unroll") for (int _i = 0; _i < 2; ++_i) \
;         __builtin_amdgcn_global_load_lds((const unsigned*)((const char*)(gbase) + (voff)[_i]), (PG8_LAS unsigned*)(lds + (bufoff) + ldsw + _i * 8192), 16, 0, 0); } while (0)
; #define PG8_LDA(dst, b, h) do { _Pragma("unroll") for (int m = 0; m < 4; ++m) _Pragma("unroll") for (int k = 0; k < 2; ++k) dst[m][k] = *(const PG8_LAS bf16x8*)(lds + PG8_SA(b, h) + aoff + m * 2048 + k * 1024); } while (0)
; #define PG8_MMA(ai, bj, At, Bt) do { __builtin_amdgcn_s_setprio(1); _Pragma("unroll") for (int m = 0; m < 4; ++m) _Pragma("unroll") for (int n = 0; n < 2; ++n) _Pragma("unroll") for (int k = 0; k < 2; ++k) \
;         acc[ai][bj][m][n] = __builtin_amdgcn_mfma_f32_16x16x32_bf16(Bt[n][k], At[m][k], acc[ai][bj][m][n], 0, 0, 0); __builtin_amdgcn_s_setprio(0); } while (0)
; #define PG8_WAIT_V(n) asm volatile("s_waitcnt vmcnt(" #n ")" ::: "memory")
; #define PG8_WAIT_L(n) asm volatile("s_waitcnt lgkmcnt(" #n ")" ::: "memory")
; #define PG8_BAR __builtin_amdgcn_s_barrier()
; #define PG8_SCHED __builtin_amdgcn_sched_barrier(0)
; template <class Epi, class Sched, bool ALIGN_EPI = false, bool SP2 = false>
; __device__ __forceinline__ void gemm_phase(PG8_LAS unsigned char* lds, const Gemm g, const Sched& S, const Epi& E) {
;     ...
;         for (int t = 0; t < nt; t += 2) {
;             const bool last = (t == nt - 2);
;             const char* a1 = cA + (size_t)(t + 1) * kstep;
;             const char* a2 = last ? nA : cA + (size_t)(t + 2) * kstep; const char* b2 = last ? nB : cB + (size_t)(t + 2) * kstep;
;             const char* a3 = a2 + kstep; const char* b3 = b2 + kstep;
;     ...
;             PG8_LDA(At, 1, 1); PG8_STAGE(PG8_SB(1, 0), b3, voffB); PG8_STAGE(PG8_SB(1, 1), b3 + hstep, voffB); PG8_STAGE(PG8_SA(1, 0), a3, voffA);
;             PG8_WAIT_V(8); PG8_WAIT_L(0); PG8_BAR; PG8_MMA(1, 0, At, B0); PG8_MMA(1, 1, At, B1); PG8_BAR; PG8_SCHED;
	s_add_i32 s16, s16, s49
	v_lshl_add_u64 v[198:199], v[198:199], 0, s[42:43]
	s_mov_b32 m0, s16
	ds_read_b128 v[190:193], v168 offset:49152
	ds_read_b128 v[194:197], v168 offset:50176
	ds_read_b128 v[202:205], v168 offset:51200
	ds_read_b128 v[206:209], v168 offset:52224
	ds_read_b128 v[210:213], v168 offset:53248
	ds_read_b128 v[214:217], v168 offset:54272
	ds_read_b128 v[218:221], v168 offset:55296
	ds_read_b128 v[222:225], v168 offset:56320
	global_load_lds_dwordx4 v[198:199], off
	v_lshl_add_u64 v[198:199], v[226:227], 0, s[42:43]
	s_add_i32 m0, s16, 0x2000
	s_add_i32 s16, s17, s49
	global_load_lds_dwordx4 v[198:199], off
	v_lshl_add_u64 v[198:199], v[228:229], 0, s[42:43]
	s_mov_b32 m0, s16
	s_nop 0
	global_load_lds_dwordx4 v[198:199], off
	v_lshl_add_u64 v[198:199], v[230:231], 0, s[42:43]
	s_add_i32 m0, s16, 0x2000
	s_nop 0
	global_load_lds_dwordx4 v[198:199], off
	v_lshl_add_u64 v[198:199], v[232:233], 0, s[42:43]
	s_mov_b32 m0, s72
	s_nop 0
	global_load_lds_dwordx4 v[198:199], off
	v_lshl_add_u64 v[198:199], v[236:237], 0, s[42:43]
	s_mov_b32 m0, s73
	s_nop 0
	global_load_lds_dwordx4 v[198:199], off
	s_waitcnt vmcnt(8)
	s_waitcnt lgkmcnt(0)
	s_barrier
	s_setprio 1
	s_waitcnt lgkmcnt(0)
	v_mfma_f32_16x16x32_bf16 v[60:63], v[128:131], v[190:193], v[60:63]
	v_mfma_f32_16x16x32_bf16 v[56:59], v[160:163], v[190:193], v[56:59]
	v_mfma_f32_16x16x32_bf16 v[44:47], v[128:131], v[202:205], v[44:47]
	v_mfma_f32_16x16x32_bf16 v[40:43], v[160:163], v[202:205], v[40:43]
	v_mfma_f32_16x16x32_bf16 v[28:31], v[128:131], v[210:213], v[28:31]
	v_mfma_f32_16x16x32_bf16 v[24:27], v[160:163], v[210:213], v[24:27]
	v_mfma_f32_16x16x32_bf16 v[12:15], v[128:131], v[218:221], v[12:15]
	v_mfma_f32_16x16x32_bf16 v[8:11], v[160:163], v[218:221], v[8:11]
	v_mfma_f32_16x16x32_bf16 v[60:63], v[156:159], v[194:197], v[60:63]
	v_mfma_f32_16x16x32_bf16 v[56:59], v[170:173], v[194:197], v[56:59]
	v_mfma_f32_16x16x32_bf16 v[44:47], v[156:159], v[206:209], v[44:47]
	v_mfma_f32_16x16x32_bf16 v[40:43], v[170:173], v[206:209], v[40:43]
	v_mfma_f32_16x16x32_bf16 v[28:31], v[156:159], v[214:217], v[28:31]
	v_mfma_f32_16x16x32_bf16 v[24:27], v[170:173], v[214:217], v[24:27]
	v_mfma_f32_16x16x32_bf16 v[12:15], v[156:159], v[222:225], v[12:15]
	v_mfma_f32_16x16x32_bf16 v[8:11], v[170:173], v[222:225], v[8:11]
	s_setprio 0
	s_setprio 1
	v_mfma_f32_16x16x32_bf16 v[52:55], v[174:177], v[190:193], v[52:55]
	v_mfma_f32_16x16x32_bf16 v[48:51], v[182:185], v[190:193], v[48:51]
	v_mfma_f32_16x16x32_bf16 v[36:39], v[174:177], v[202:205], v[36:39]
	v_mfma_f32_16x16x32_bf16 v[32:35], v[182:185], v[202:205], v[32:35]
	v_mfma_f32_16x16x32_bf16 v[20:23], v[174:177], v[210:213], v[20:23]
	v_mfma_f32_16x16x32_bf16 v[16:19], v[182:185], v[210:213], v[16:19]
	v_mfma_f32_16x16x32_bf16 v[4:7], v[174:177], v[218:221], v[4:7]
	v_mfma_f32_16x16x32_bf16 v[0:3], v[182:185], v[218:221], v[0:3]
	v_mfma_f32_16x16x32_bf16 v[52:55], v[178:181], v[194:197], v[52:55]
	v_mfma_f32_16x16x32_bf16 v[48:51], v[186:189], v[194:197], v[48:51]
	v_mfma_f32_16x16x32_bf16 v[36:39], v[178:181], v[206:209], v[36:39]
	v_mfma_f32_16x16x32_bf16 v[32:35], v[186:189], v[206:209], v[32:35]
	v_mfma_f32_16x16x32_bf16 v[20:23], v[178:181], v[214:217], v[20:23]
	v_mfma_f32_16x16x32_bf16 v[16:19], v[186:189], v[214:217], v[16:19]
	v_mfma_f32_16x16x32_bf16 v[4:7], v[178:181], v[222:225], v[4:7]
	v_mfma_f32_16x16x32_bf16 v[0:3], v[186:189], v[222:225], v[0:3]
	s_setprio 0
	s_barrier
	s_add_u32 s58, s58, 0x100
	s_addc_u32 s59, s59, 0
	s_add_u32 s95, s95, 0x100
	s_addc_u32 s96, s96, 0
	s_cmp_ge_i32 s97, s74
	s_mov_b32 s60, s97
	s_cbranch_scc1 .LBB0_536

; __device__ __forceinline__ void attn_phase(const Params& p, LAS unsigned char* lds) {
;     ...
;                 f32x16 p0 = (f32x16){}, p1 = (f32x16){};
;                 { const LAS unsigned char* kp = Ks + c * KS_STRIDE + hi * 16;
;                   bf16x8 a0 = *(const LAS bf16x8*)(kp), a1 = *(const LAS bf16x8*)(kp + 32 * KS_STRIDE);
; #pragma unroll
;                   for (int d = 0; d < 12; ++d) { bf16x8 n0 = a0, n1 = a1;
;                       if (d < 11) { n0 = *(const LAS bf16x8*)(kp + (d + 1) * 32); n1 = *(const LAS bf16x8*)(kp + 32 * KS_STRIDE + (d + 1) * 32); }
;                       p0 = __builtin_amdgcn_mfma_f32_32x32x16_bf16(a0, qf[d], p0, 0, 0, 0); p1 = __builtin_amdgcn_mfma_f32_32x32x16_bf16(a1, qf[d], p1, 0, 0, 0);
;                       a0 = n0; a1 = n1; } }
;                 const LAS unsigned char* vb = Vs + (4 * hi + ((lane & 15) >> 2)) * VS_STRIDE + (((lane >> 4) & 1) * 16 + 4 * (lane & 3)) * 2;
;                 s16x4 vlo[2][4], vhi[2][4];
; #pragma unroll
;                 for (int s = 0; s < 4; ++s) { vlo[0][s] = vtr(vb + (16 * s) * VS_STRIDE); vhi[0][s] = vtr(vb + (16 * s + 8) * VS_STRIDE); }
;                 if (jt == 0) {
; #pragma unroll
;                     for (int r = 0; r < 16; ++r) { if (crow(r, hi) >= NMETA) p0[r] = NEG; p1[r] = NEG; }
;                 } else if (jt - 1 >= 4 * qblk) {
;                     const int kb = 64 * (jt - 1);
; #pragma unroll
;                     for (int r = 0; r < 16; ++r) { const int key = kb + crow(r, hi); if (key > tq) p0[r] = NEG; if (key + 32 > tq) p1[r] = NEG; }
;                 }
;                 float rm = p0[0];
; #pragma unroll
;                 for (int r = 1; r < 16; ++r) rm = fmaxf(rm, p0[r]);
; #pragma unroll
;                 for (int r = 0; r < 16; ++r) rm = fmaxf(rm, p1[r]);
;                 rm = fmaxf(rm, __shfl_xor(rm, 32));
;                 const float mn = fmaxf(mrun, rm), alpha = __builtin_amdgcn_exp2f(mrun - mn); mrun = mn;
;                 float ps = 0.f;
; #pragma unroll
;                 for (int r = 0; r < 16; ++r) { p0[r] = __builtin_amdgcn_exp2f(p0[r] - mn); p1[r] = __builtin_amdgcn_exp2f(p1[r] - mn); ps += p0[r] + p1[r]; }
;                 lrun = lrun * alpha + ps;
;                 if (__any(alpha != 1.0f)) {
; #pragma unroll
;                     for (int d = 0; d < 4; ++d) o[d] *= alpha; }
;                 bf16x8 pf[4];
; #pragma unroll
.LBB0_641:
	s_or_b64 exec, exec, s[42:43]
	s_lshl_b32 s50, s50, 2
	s_xor_b64 s[42:43], s[44:45], -1
	s_mov_b32 s8, 2
	s_add_i32 s51, s50, 5
	ds_read_b128 v[0:3], v243
	ds_read_b128 v[16:19], v243 offset:32
	s_mov_b32 s53, 0
	v_mov_b64_e32 v[232:233], v[222:223]
	s_waitcnt lgkmcnt(1)
	v_mfma_f32_32x32x16_bf16 v[0:15], v[0:3], v[96:99], 0
	s_waitcnt lgkmcnt(0)
	v_mfma_f32_32x32x16_bf16 v[0:15], v[16:19], v[100:103], v[0:15]
	ds_read_b128 v[16:19], v243 offset:64
	ds_read_b128 v[20:23], v243 offset:96
	s_waitcnt lgkmcnt(1)
	v_mfma_f32_32x32x16_bf16 v[0:15], v[16:19], v[104:107], v[0:15]
	s_waitcnt lgkmcnt(0)
	v_mfma_f32_32x32x16_bf16 v[0:15], v[20:23], v[108:111], v[0:15]
	ds_read_b128 v[16:19], v243 offset:128
	ds_read_b128 v[20:23], v243 offset:160
	s_waitcnt lgkmcnt(1)
	v_mfma_f32_32x32x16_bf16 v[0:15], v[16:19], v[112:115], v[0:15]
	s_waitcnt lgkmcnt(0)
	v_mfma_f32_32x32x16_bf16 v[0:15], v[20:23], v[116:119], v[0:15]
	ds_read_b128 v[16:19], v243 offset:192
	ds_read_b128 v[20:23], v243 offset:224
	s_waitcnt lgkmcnt(1)
	v_mfma_f32_32x32x16_bf16 v[0:15], v[16:19], v[120:123], v[0:15]
	s_waitcnt lgkmcnt(0)
	v_mfma_f32_32x32x16_bf16 v[0:15], v[20:23], v[124:127], v[0:15]
	ds_read_b128 v[16:19], v243 offset:256
	ds_read_b128 v[20:23], v243 offset:288
	s_waitcnt lgkmcnt(1)
	v_mfma_f32_32x32x16_bf16 v[0:15], v[16:19], v[128:131], v[0:15]
	s_waitcnt lgkmcnt(0)
	v_mfma_f32_32x32x16_bf16 v[0:15], v[20:23], v[132:135], v[0:15]
	ds_read_b128 v[16:19], v243 offset:320
	ds_read_b128 v[20:23], v243 offset:352
	s_waitcnt lgkmcnt(1)
	v_mfma_f32_32x32x16_bf16 v[0:15], v[16:19], v[136:139], v[0:15]
	ds_read_b64_tr_b16 v[16:17], v244 offset:25600
	ds_read_b64_tr_b16 v[24:25], v244 offset:25664
	ds_read_b64_tr_b16 v[64:65], v244 offset:25728
	ds_read_b64_tr_b16 v[68:69], v244 offset:25792
	ds_read_b64_tr_b16 v[18:19], v244 offset:28160
	ds_read_b64_tr_b16 v[26:27], v244 offset:28224
	ds_read_b64_tr_b16 v[66:67], v244 offset:28288
	ds_read_b64_tr_b16 v[70:71], v244 offset:28352
	s_waitcnt lgkmcnt(8)
	v_mfma_f32_32x32x16_bf16 v[0:15], v[20:23], v[140:143], v[0:15]
	s_nop 11
	v_max3_f32 v8, v0, v1, v2
	v_max3_f32 v8, v8, v3, v4
	v_max3_f32 v8, v8, v5, v6
	v_max3_f32 v8, v8, v7, s46
	ds_bpermute_b32 v9, v241, v8
	s_waitcnt lgkmcnt(0)
	v_max3_f32 v182, v8, v9, s47
	v_sub_f32_e32 v8, 0xf149f2ca, v182
	v_exp_f32_e32 v176, v8
	v_sub_f32_e32 v0, v0, v182
	v_sub_f32_e32 v1, v1, v182
	v_sub_f32_e32 v2, v2, v182
	v_sub_f32_e32 v3, v3, v182
	v_sub_f32_e32 v4, v4, v182
	v_sub_f32_e32 v5, v5, v182
	v_sub_f32_e32 v6, v6, v182
	v_sub_f32_e32 v7, v7, v182
	v_exp_f32_e32 v177, v0
	v_exp_f32_e32 v178, v1
	v_exp_f32_e32 v179, v2
	v_exp_f32_e32 v229, v3
	v_exp_f32_e32 v230, v4
	v_exp_f32_e32 v173, v5
	v_exp_f32_e32 v172, v6
	v_exp_f32_e32 v175, v7
	v_cmp_neq_f32_e32 vcc, 1.0, v176
	s_cmp_lg_u64 vcc, 0
	v_mul_f32_e32 v0, 0, v176
	s_cselect_b64 vcc, -1, 0
	v_cndmask_b32_e32 v0, 0, v0, vcc
	v_cvt_pk_bf16_f32 v72, v177, v178
	v_cvt_pk_bf16_f32 v73, v179, v229
	v_cvt_pk_bf16_f32 v74, v230, v173
	v_cvt_pk_bf16_f32 v75, v172, v175
	v_mov_b32_e32 v1, v0
	v_mov_b32_e32 v2, v0
	v_mov_b32_e32 v3, v0
	v_mov_b32_e32 v4, v0
	v_mov_b32_e32 v5, v0
	v_mov_b32_e32 v6, v0
	v_mov_b32_e32 v7, v0
	v_mov_b32_e32 v8, v0
	v_mov_b32_e32 v9, v0
	v_mov_b32_e32 v10, v0
	v_mov_b32_e32 v11, v0
	v_mov_b32_e32 v12, v0
	v_mov_b32_e32 v13, v0
	v_mov_b32_e32 v14, v0
	v_mov_b32_e32 v15, v0
	v_sub_f32_e32 v22, 0xff800000, v182
	v_exp_f32_e32 v174, v22
	v_mfma_f32_32x32x16_bf16 v[48:63], v[16:19], v[72:75], v[0:15]
	ds_read_b64_tr_b16 v[18:19], v244 offset:33280
	ds_read_b64_tr_b16 v[16:17], v244 offset:30720
	ds_read_b64_tr_b16 v[20:21], v244 offset:30784
	ds_read_b64_tr_b16 v[76:77], v244 offset:30848
	ds_read_b64_tr_b16 v[80:81], v244 offset:30912
	ds_read_b64_tr_b16 v[22:23], v244 offset:33344
	ds_read_b64_tr_b16 v[78:79], v244 offset:33408
	ds_read_b64_tr_b16 v[82:83], v244 offset:33472
	v_cvt_pk_bf16_f32 v84, v174, v174
	v_mov_b32_e32 v85, v84
	v_mov_b32_e32 v86, v84
	v_mov_b32_e32 v87, v84
	s_addk_i32 s52, 0x100
	v_mfma_f32_32x32x16_bf16 v[32:47], v[24:27], v[72:75], v[0:15]
	s_waitcnt lgkmcnt(6)
	v_mfma_f32_32x32x16_bf16 v[48:63], v[16:19], v[84:87], v[48:63]
	ds_read_b64_tr_b16 v[16:17], v244 offset:35840
	ds_read_b64_tr_b16 v[18:19], v244 offset:38400
	s_waitcnt lgkmcnt(4)
	v_mfma_f32_32x32x16_bf16 v[32:47], v[20:23], v[84:87], v[32:47]
	ds_read_b64_tr_b16 v[20:21], v244 offset:43520
	ds_read_b64_tr_b16 v[22:23], v244 offset:35904
	ds_read_b64_tr_b16 v[88:89], v244 offset:35968
	ds_read_b64_tr_b16 v[92:93], v244 offset:36032
	ds_read_b64_tr_b16 v[24:25], v244 offset:38464
	ds_read_b64_tr_b16 v[90:91], v244 offset:38528
	ds_read_b64_tr_b16 v[94:95], v244 offset:38592
	s_waitcnt lgkmcnt(7)
	v_mfma_f32_32x32x16_bf16 v[48:63], v[16:19], v[84:87], v[48:63]
	ds_read_b64_tr_b16 v[18:19], v244 offset:40960
	ds_read_b64_tr_b16 v[26:27], v244 offset:41024
	ds_read_b64_tr_b16 v[164:165], v244 offset:41088
	ds_read_b64_tr_b16 v[168:169], v244 offset:41152
	ds_read_b64_tr_b16 v[28:29], v244 offset:43584
	ds_read_b64_tr_b16 v[166:167], v244 offset:43648
	ds_read_b64_tr_b16 v[170:171], v244 offset:43712
	s_waitcnt lgkmcnt(9)
	v_mfma_f32_32x32x16_bf16 v[32:47], v[22:25], v[84:87], v[32:47]
	s_waitcnt lgkmcnt(6)
	v_mfma_f32_32x32x16_bf16 v[48:63], v[18:21], v[84:87], v[48:63]
	s_waitcnt lgkmcnt(2)
	v_mfma_f32_32x32x16_bf16 v[32:47], v[26:29], v[84:87], v[32:47]
	v_mfma_f32_32x32x16_bf16 v[16:31], v[64:67], v[72:75], v[0:15]
	v_add_f32_e32 v64, v177, v174
	v_add_f32_e32 v64, 0, v64
	v_add_f32_e32 v65, v178, v174
	v_add_f32_e32 v64, v65, v64
	v_add_f32_e32 v65, v179, v174
	v_add_f32_e32 v64, v65, v64
	v_add_f32_e32 v65, v229, v174
	v_mfma_f32_32x32x16_bf16 v[0:15], v[68:71], v[72:75], v[0:15]
	v_add_f32_e32 v64, v65, v64
	v_add_f32_e32 v65, v230, v174
	v_add_f32_e32 v66, v65, v64
	v_add_f32_e64 v64, v172, v174
	v_add_f32_e64 v65, v173, v174
	v_mov_b64_e32 v[230:231], v[224:225]
	v_add_f32_e32 v65, v65, v66
	v_add_f32_e32 v66, v64, v65
	v_mfma_f32_32x32x16_bf16 v[16:31], v[76:79], v[84:87], v[16:31]
	v_add_f32_e64 v64, v174, v174
	v_add_f32_e64 v65, v175, v174
	v_add_f32_e32 v65, v65, v66
	v_add_f32_e32 v65, v64, v65
	v_add_f32_e32 v65, v64, v65
	v_add_f32_e32 v65, v64, v65
	v_add_f32_e32 v65, v64, v65
	v_mfma_f32_32x32x16_bf16 v[0:15], v[80:83], v[84:87], v[0:15]
	v_add_f32_e32 v65, v64, v65
	v_add_f32_e32 v65, v64, v65
	v_add_f32_e32 v65, v64, v65
	v_add_f32_e32 v229, v64, v65
	v_fmac_f32_e32 v229, 0, v176
	v_mfma_f32_32x32x16_bf16 v[16:31], v[88:91], v[84:87], v[16:31]
	v_mfma_f32_32x32x16_bf16 v[0:15], v[92:95], v[84:87], v[0:15]
	s_waitcnt lgkmcnt(1)
	v_mfma_f32_32x32x16_bf16 v[16:31], v[164:167], v[84:87], v[16:31]
	s_waitcnt lgkmcnt(0)
	v_mfma_f32_32x32x16_bf16 v[0:15], v[168:171], v[84:87], v[0:15]
	.p2alignl 6, 3212836864

; #define PG8_STAGE(bufoff, gbase, voff) do { _Pragma("unroll") for (int _i = 0; _i < 2; ++_i) \
;         __builtin_amdgcn_global_load_lds((const unsigned*)((const char*)(gbase) + (voff)[_i]), (PG8_LAS unsigned*)(lds + (bufoff) + ldsw + _i * 8192), 16, 0, 0); } while (0)
; #define PG8_LDA(dst, b, h) do { _Pragma("unroll") for (int m = 0; m < 4; ++m) _Pragma("unroll") for (int k = 0; k < 2; ++k) dst[m][k] = *(const PG8_LAS bf16x8*)(lds + PG8_SA(b, h) + aoff + m * 2048 + k * 1024); } while (0)
; #define PG8_LDB(dst, b, h) do { _Pragma("unroll") for (int n = 0; n < 2; ++n) _Pragma("unroll") for (int k = 0; k < 2; ++k) dst[n][k] = *(const PG8_LAS bf16x8*)(lds + PG8_SB(b, h) + boff + n * 2048 + k * 1024); } while (0)
; #define PG8_MMA(ai, bj, At, Bt) do { __builtin_amdgcn_s_setprio(1); _Pragma("unroll") for (int m = 0; m < 4; ++m) _Pragma("unroll") for (int n = 0; n < 2; ++n) _Pragma("unroll") for (int k = 0; k < 2; ++k) \
;         acc[ai][bj][m][n] = __builtin_amdgcn_mfma_f32_16x16x32_bf16(Bt[n][k], At[m][k], acc[ai][bj][m][n], 0, 0, 0); __builtin_amdgcn_s_setprio(0); } while (0)
; #define PG8_WAIT_V(n) asm volatile("s_waitcnt vmcnt(" #n ")" ::: "memory")
; #define PG8_WAIT_L(n) asm volatile("s_waitcnt lgkmcnt(" #n ")" ::: "memory")
; #define PG8_BAR __builtin_amdgcn_s_barrier()
; #define PG8_SCHED __builtin_amdgcn_sched_barrier(0)
; template <class Epi, class Sched, bool ALIGN_EPI = false, bool SP2 = false>
; __device__ __forceinline__ void gemm_phase(PG8_LAS unsigned char* lds, const Gemm g, const Sched& S, const Epi& E) {
;     ...
;             PG8_LDB(B0, 0, 0); PG8_LDB(B1, 0, 1); PG8_SCHED; PG8_LDA(At, 0, 0); PG8_STAGE(PG8_SA(1, 1), a1 + hstep, voffA);
;             PG8_WAIT_V(8); PG8_WAIT_L(0); PG8_BAR; PG8_MMA(0, 0, At, B0); PG8_MMA(0, 1, At, B1); PG8_BAR; PG8_SCHED;
;             PG8_LDA(At, 0, 1); PG8_STAGE(PG8_SB(0, 0), b2, voffB); PG8_STAGE(PG8_SB(0, 1), b2 + hstep, voffB); PG8_STAGE(PG8_SA(0, 0), a2, voffA);
;             PG8_WAIT_V(8); PG8_WAIT_L(0); PG8_BAR; PG8_MMA(1, 0, At, B0); PG8_MMA(1, 1, At, B1); PG8_BAR; PG8_SCHED;
.Lcz_go_728:
	s_add_u32 s6, s6, 0x80
	s_addc_u32 s7, s7, 0
	s_add_u32 s79, s52, 0x100
	s_addc_u32 s80, s53, 0
	s_mov_b32 s52, 0
	.p2alignl 6, 3212836864
	ds_read_b128 v[128:131], v169
	ds_read_b128 v[148:151], v169 offset:1024
	ds_read_b128 v[152:155], v169 offset:2048
	ds_read_b128 v[156:159], v169 offset:3072
	ds_read_b128 v[160:163], v170
	ds_read_b128 v[172:175], v170 offset:1024
	ds_read_b128 v[176:179], v170 offset:2048
	ds_read_b128 v[180:183], v170 offset:3072
	s_add_i32 s81, s52, 2
	s_add_u32 s16, s6, 0x80
	s_addc_u32 s17, s7, 0
	s_cmp_eq_u32 s69, s52
	s_cselect_b32 s52, s0, s16
	s_cselect_b32 s53, s1, s17
	s_cselect_b32 s83, s51, s80
	s_cselect_b32 s82, s50, s79
	v_lshl_add_u64 v[164:165], s[6:7], 0, v[140:141]
	s_add_i32 m0, s56, 0xc000
	ds_read_b128 v[184:187], v171
	ds_read_b128 v[188:191], v171 offset:1024
	ds_read_b128 v[192:195], v171 offset:2048
	ds_read_b128 v[196:199], v171 offset:3072
	ds_read_b128 v[202:205], v171 offset:4096
	ds_read_b128 v[206:209], v171 offset:5120
	ds_read_b128 v[210:213], v171 offset:6144
	ds_read_b128 v[214:217], v171 offset:7168
	global_load_lds_dwordx4 v[164:165], off
	v_lshl_add_u64 v[164:165], s[6:7], 0, v[142:143]
	s_add_i32 m0, s56, 0xe000
	s_nop 0
	global_load_lds_dwordx4 v[164:165], off
	s_waitcnt vmcnt(8)
	s_waitcnt lgkmcnt(0)
	s_barrier
	s_setprio 1
	s_waitcnt lgkmcnt(0)
	v_mfma_f32_16x16x32_bf16 v[120:123], v[128:131], v[184:187], 0
	v_mfma_f32_16x16x32_bf16 v[124:127], v[152:155], v[184:187], 0
	v_mfma_f32_16x16x32_bf16 v[108:111], v[128:131], v[192:195], 0
	v_mfma_f32_16x16x32_bf16 v[104:107], v[152:155], v[192:195], 0
	v_mfma_f32_16x16x32_bf16 v[92:95], v[128:131], v[202:205], 0
	v_mfma_f32_16x16x32_bf16 v[88:91], v[152:155], v[202:205], 0
	v_mfma_f32_16x16x32_bf16 v[76:79], v[128:131], v[210:213], 0
	v_mfma_f32_16x16x32_bf16 v[72:75], v[152:155], v[210:213], 0
	v_mfma_f32_16x16x32_bf16 v[120:123], v[148:151], v[188:191], v[120:123]
	v_mfma_f32_16x16x32_bf16 v[124:127], v[156:159], v[188:191], v[124:127]
	v_mfma_f32_16x16x32_bf16 v[108:111], v[148:151], v[196:199], v[108:111]
	v_mfma_f32_16x16x32_bf16 v[104:107], v[156:159], v[196:199], v[104:107]
	v_mfma_f32_16x16x32_bf16 v[92:95], v[148:151], v[206:209], v[92:95]
	v_mfma_f32_16x16x32_bf16 v[88:91], v[156:159], v[206:209], v[88:91]
	v_mfma_f32_16x16x32_bf16 v[76:79], v[148:151], v[214:217], v[76:79]
	v_mfma_f32_16x16x32_bf16 v[72:75], v[156:159], v[214:217], v[72:75]
	s_setprio 0
	s_setprio 1
	v_mfma_f32_16x16x32_bf16 v[116:119], v[160:163], v[184:187], 0
	v_mfma_f32_16x16x32_bf16 v[112:115], v[176:179], v[184:187], 0
	v_mfma_f32_16x16x32_bf16 v[100:103], v[160:163], v[192:195], 0
	v_mfma_f32_16x16x32_bf16 v[96:99], v[176:179], v[192:195], 0
	v_mfma_f32_16x16x32_bf16 v[84:87], v[160:163], v[202:205], 0
	v_mfma_f32_16x16x32_bf16 v[80:83], v[176:179], v[202:205], 0
	v_mfma_f32_16x16x32_bf16 v[68:71], v[160:163], v[210:213], 0
	v_mfma_f32_16x16x32_bf16 v[64:67], v[176:179], v[210:213], 0
	v_mfma_f32_16x16x32_bf16 v[116:119], v[172:175], v[188:191], v[116:119]
	v_mfma_f32_16x16x32_bf16 v[112:115], v[180:183], v[188:191], v[112:115]
	v_mfma_f32_16x16x32_bf16 v[100:103], v[172:175], v[196:199], v[100:103]
	v_mfma_f32_16x16x32_bf16 v[96:99], v[180:183], v[196:199], v[96:99]
	v_mfma_f32_16x16x32_bf16 v[84:87], v[172:175], v[206:209], v[84:87]
	v_mfma_f32_16x16x32_bf16 v[80:83], v[180:183], v[206:209], v[80:83]
	v_mfma_f32_16x16x32_bf16 v[68:71], v[172:175], v[214:217], v[68:71]
	v_mfma_f32_16x16x32_bf16 v[64:67], v[180:183], v[214:217], v[64:67]
	s_setprio 0
	s_barrier
	s_add_i32 s16, s71, s55
	v_lshl_add_u64 v[164:165], s[82:83], 0, v[134:135]
	s_mov_b32 m0, s16
	ds_read_b128 v[184:187], v171 offset:16384
	ds_read_b128 v[188:191], v171 offset:17408
	ds_read_b128 v[192:195], v171 offset:18432
	ds_read_b128 v[196:199], v171 offset:19456
	ds_read_b128 v[202:205], v171 offset:20480
	ds_read_b128 v[206:209], v171 offset:21504
	ds_read_b128 v[210:213], v171 offset:22528
	ds_read_b128 v[214:217], v171 offset:23552
	global_load_lds_dwordx4 v[164:165], off
	s_add_i32 m0, s16, 0x2000
	v_lshl_add_u64 v[218:219], s[82:83], 0, v[138:139]
	s_add_u32 s82, s82, s10
	s_addc_u32 s83, s83, s11
	s_add_i32 s16, s72, s55
	global_load_lds_dwordx4 v[218:219], off
	v_lshl_add_u64 v[220:221], s[82:83], 0, v[134:135]
	s_mov_b32 m0, s16
	v_lshl_add_u64 v[222:223], s[82:83], 0, v[138:139]
	global_load_lds_dwordx4 v[220:221], off
	s_add_i32 m0, s16, 0x2000
	v_lshl_add_u64 v[224:225], s[52:53], 0, v[132:133]
	global_load_lds_dwordx4 v[222:223], off
	s_mov_b32 m0, s56
	v_lshl_add_u64 v[226:227], s[52:53], 0, v[136:137]
	global_load_lds_dwordx4 v[224:225], off
	s_mov_b32 m0, s57
	s_nop 0
	global_load_lds_dwordx4 v[226:227], off
	s_waitcnt vmcnt(8)
	s_waitcnt lgkmcnt(0)
	s_barrier
; #define PG8_STAGE(bufoff, gbase, voff) do { _Pragma("unroll") for (int _i = 0; _i < 2; ++_i) \
;         __builtin_amdgcn_global_load_lds((const unsigned*)((const char*)(gbase) + (voff)[_i]), (PG8_LAS unsigned*)(lds + (bufoff) + ldsw + _i * 8192), 16, 0, 0); } while (0)
; #define PG8_LDA(dst, b, h) do { _Pragma("unroll") for (int m = 0; m < 4; ++m) _Pragma("unroll") for (int k = 0; k < 2; ++k) dst[m][k] = *(const PG8_LAS bf16x8*)(lds + PG8_SA(b, h) + aoff + m * 2048 + k * 1024); } while (0)
; #define PG8_LDB(dst, b, h) do { _Pragma("unroll") for (int n = 0; n < 2; ++n) _Pragma("unroll") for (int k = 0; k < 2; ++k) dst[n][k] = *(const PG8_LAS bf16x8*)(lds + PG8_SB(b, h) + boff + n * 2048 + k * 1024); } while (0)
; #define PG8_MMA(ai, bj, At, Bt) do { __builtin_amdgcn_s_setprio(1); _Pragma("unroll") for (int m = 0; m < 4; ++m) _Pragma("unroll") for (int n = 0; n < 2; ++n) _Pragma("unroll") for (int k = 0; k < 2; ++k) \
;         acc[ai][bj][m][n] = __builtin_amdgcn_mfma_f32_16x16x32_bf16(Bt[n][k], At[m][k], acc[ai][bj][m][n], 0, 0, 0); __builtin_amdgcn_s_setprio(0); } while (0)
; #define PG8_WAIT_V(n) asm volatile("s_waitcnt vmcnt(" #n ")" ::: "memory")
; #define PG8_WAIT_L(n) asm volatile("s_waitcnt lgkmcnt(" #n ")" ::: "memory")
; #define PG8_BAR __builtin_amdgcn_s_barrier()
; #define PG8_SCHED __builtin_amdgcn_sched_barrier(0)
; template <class Epi, class Sched, bool ALIGN_EPI = false, bool SP2 = false>
; __device__ __forceinline__ void gemm_phase(PG8_LAS unsigned char* lds, const Gemm g, const Sched& S, const Epi& E) {
;     ...
;             PG8_WAIT_V(8); PG8_WAIT_L(0); PG8_BAR; PG8_MMA(1, 0, At, B0); PG8_MMA(1, 1, At, B1); PG8_BAR; PG8_SCHED;
;             PG8_LDB(B0, 1, 0); PG8_LDB(B1, 1, 1); PG8_SCHED; PG8_LDA(At, 1, 0); PG8_STAGE(PG8_SA(0, 1), a2 + hstep, voffA);
;             PG8_WAIT_V(8); PG8_WAIT_L(0); PG8_BAR; PG8_MMA(0, 0, At, B0); PG8_MMA(0, 1, At, B1); PG8_BAR; PG8_SCHED;
	s_setprio 1
	s_waitcnt lgkmcnt(0)
	v_mfma_f32_16x16x32_bf16 v[60:63], v[128:131], v[184:187], 0
	v_mfma_f32_16x16x32_bf16 v[56:59], v[152:155], v[184:187], 0
	v_mfma_f32_16x16x32_bf16 v[44:47], v[128:131], v[192:195], 0
	v_mfma_f32_16x16x32_bf16 v[40:43], v[152:155], v[192:195], 0
	v_mfma_f32_16x16x32_bf16 v[28:31], v[128:131], v[202:205], 0
	v_mfma_f32_16x16x32_bf16 v[24:27], v[152:155], v[202:205], 0
	v_mfma_f32_16x16x32_bf16 v[12:15], v[128:131], v[210:213], 0
	v_mfma_f32_16x16x32_bf16 v[8:11], v[152:155], v[210:213], 0
	v_mfma_f32_16x16x32_bf16 v[60:63], v[148:151], v[188:191], v[60:63]
	v_mfma_f32_16x16x32_bf16 v[56:59], v[156:159], v[188:191], v[56:59]
	v_mfma_f32_16x16x32_bf16 v[44:47], v[148:151], v[196:199], v[44:47]
	v_mfma_f32_16x16x32_bf16 v[40:43], v[156:159], v[196:199], v[40:43]
	v_mfma_f32_16x16x32_bf16 v[28:31], v[148:151], v[206:209], v[28:31]
	v_mfma_f32_16x16x32_bf16 v[24:27], v[156:159], v[206:209], v[24:27]
	v_mfma_f32_16x16x32_bf16 v[12:15], v[148:151], v[214:217], v[12:15]
	v_mfma_f32_16x16x32_bf16 v[8:11], v[156:159], v[214:217], v[8:11]
	s_setprio 0
	s_setprio 1
	v_mfma_f32_16x16x32_bf16 v[52:55], v[160:163], v[184:187], 0
	v_mfma_f32_16x16x32_bf16 v[48:51], v[176:179], v[184:187], 0
	v_mfma_f32_16x16x32_bf16 v[36:39], v[160:163], v[192:195], 0
	v_mfma_f32_16x16x32_bf16 v[32:35], v[176:179], v[192:195], 0
	v_mfma_f32_16x16x32_bf16 v[20:23], v[160:163], v[202:205], 0
	v_mfma_f32_16x16x32_bf16 v[16:19], v[176:179], v[202:205], 0
	v_mfma_f32_16x16x32_bf16 v[4:7], v[160:163], v[210:213], 0
	v_mfma_f32_16x16x32_bf16 v[0:3], v[176:179], v[210:213], 0
	v_mfma_f32_16x16x32_bf16 v[52:55], v[172:175], v[188:191], v[52:55]
	v_mfma_f32_16x16x32_bf16 v[48:51], v[180:183], v[188:191], v[48:51]
	v_mfma_f32_16x16x32_bf16 v[36:39], v[172:175], v[196:199], v[36:39]
	v_mfma_f32_16x16x32_bf16 v[32:35], v[180:183], v[196:199], v[32:35]
	v_mfma_f32_16x16x32_bf16 v[20:23], v[172:175], v[206:209], v[20:23]
	v_mfma_f32_16x16x32_bf16 v[16:19], v[180:183], v[206:209], v[16:19]
	v_mfma_f32_16x16x32_bf16 v[4:7], v[172:175], v[214:217], v[4:7]
	v_mfma_f32_16x16x32_bf16 v[0:3], v[180:183], v[214:217], v[0:3]
	s_setprio 0
	s_barrier
	s_add_i32 s16, 0, 0x18000
	s_add_i32 s17, 0, 0x1c000
	v_add_u32_e32 v156, s16, v167
	v_add_u32_e32 v180, s17, v167
	ds_read_b128 v[128:131], v156
	ds_read_b128 v[148:151], v156 offset:1024
	ds_read_b128 v[152:155], v156 offset:2048
	ds_read_b128 v[156:159], v156 offset:3072
	ds_read_b128 v[160:163], v180
	ds_read_b128 v[172:175], v180 offset:1024
	ds_read_b128 v[176:179], v180 offset:2048
	ds_read_b128 v[180:183], v180 offset:3072
	s_add_u32 s52, s52, s10
	s_addc_u32 s53, s53, s11
	s_mov_b32 m0, s58
	v_lshl_add_u64 v[228:229], s[52:53], 0, v[132:133]
	ds_read_b128 v[184:187], v171 offset:32768
	ds_read_b128 v[188:191], v171 offset:33792
	ds_read_b128 v[192:195], v171 offset:34816
	ds_read_b128 v[196:199], v171 offset:35840
	ds_read_b128 v[202:205], v171 offset:36864
	ds_read_b128 v[206:209], v171 offset:37888
	ds_read_b128 v[210:213], v171 offset:38912
	ds_read_b128 v[214:217], v171 offset:39936
	global_load_lds_dwordx4 v[228:229], off
	v_lshl_add_u64 v[228:229], s[52:53], 0, v[136:137]
	s_mov_b32 m0, s59
	s_nop 0
	global_load_lds_dwordx4 v[228:229], off
	s_waitcnt vmcnt(8)
	s_waitcnt lgkmcnt(0)
	s_barrier
	s_setprio 1
	s_waitcnt lgkmcnt(0)
	v_mfma_f32_16x16x32_bf16 v[120:123], v[128:131], v[184:187], v[120:123]
	v_mfma_f32_16x16x32_bf16 v[124:127], v[152:155], v[184:187], v[124:127]
	v_mfma_f32_16x16x32_bf16 v[108:111], v[128:131], v[192:195], v[108:111]
	v_mfma_f32_16x16x32_bf16 v[104:107], v[152:155], v[192:195], v[104:107]
	v_mfma_f32_16x16x32_bf16 v[92:95], v[128:131], v[202:205], v[92:95]
	v_mfma_f32_16x16x32_bf16 v[88:91], v[152:155], v[202:205], v[88:91]
	v_mfma_f32_16x16x32_bf16 v[76:79], v[128:131], v[210:213], v[76:79]
	v_mfma_f32_16x16x32_bf16 v[72:75], v[152:155], v[210:213], v[72:75]
	v_mfma_f32_16x16x32_bf16 v[120:123], v[148:151], v[188:191], v[120:123]
	v_mfma_f32_16x16x32_bf16 v[124:127], v[156:159], v[188:191], v[124:127]
	v_mfma_f32_16x16x32_bf16 v[108:111], v[148:151], v[196:199], v[108:111]
	v_mfma_f32_16x16x32_bf16 v[104:107], v[156:159], v[196:199], v[104:107]
	v_mfma_f32_16x16x32_bf16 v[92:95], v[148:151], v[206:209], v[92:95]
	v_mfma_f32_16x16x32_bf16 v[88:91], v[156:159], v[206:209], v[88:91]
	v_mfma_f32_16x16x32_bf16 v[76:79], v[148:151], v[214:217], v[76:79]
	v_mfma_f32_16x16x32_bf16 v[72:75], v[156:159], v[214:217], v[72:75]
	s_setprio 0
	s_setprio 1
	v_mfma_f32_16x16x32_bf16 v[116:119], v[160:163], v[184:187], v[116:119]
	v_mfma_f32_16x16x32_bf16 v[112:115], v[176:179], v[184:187], v[112:115]
	v_mfma_f32_16x16x32_bf16 v[100:103], v[160:163], v[192:195], v[100:103]
	v_mfma_f32_16x16x32_bf16 v[96:99], v[176:179], v[192:195], v[96:99]
	v_mfma_f32_16x16x32_bf16 v[84:87], v[160:163], v[202:205], v[84:87]
	v_mfma_f32_16x16x32_bf16 v[80:83], v[176:179], v[202:205], v[80:83]
	v_mfma_f32_16x16x32_bf16 v[68:71], v[160:163], v[210:213], v[68:71]
	v_mfma_f32_16x16x32_bf16 v[64:67], v[176:179], v[210:213], v[64:67]
	v_mfma_f32_16x16x32_bf16 v[116:119], v[172:175], v[188:191], v[116:119]
	v_mfma_f32_16x16x32_bf16 v[112:115], v[180:183], v[188:191], v[112:115]
	v_mfma_f32_16x16x32_bf16 v[100:103], v[172:175], v[196:199], v[100:103]
	v_mfma_f32_16x16x32_bf16 v[96:99], v[180:183], v[196:199], v[96:99]
	v_mfma_f32_16x16x32_bf16 v[84:87], v[172:175], v[206:209], v[84:87]
	v_mfma_f32_16x16x32_bf16 v[80:83], v[180:183], v[206:209], v[80:83]
	v_mfma_f32_16x16x32_bf16 v[68:71], v[172:175], v[214:217], v[68:71]
	v_mfma_f32_16x16x32_bf16 v[64:67], v[180:183], v[214:217], v[64:67]
	s_setprio 0
	s_barrier
; #define PG8_STAGE(bufoff, gbase, voff) do { _Pragma("unroll") for (int _i = 0; _i < 2; ++_i) \
;         __builtin_amdgcn_global_load_lds((const unsigned*)((const char*)(gbase) + (voff)[_i]), (PG8_LAS unsigned*)(lds + (bufoff) + ldsw + _i * 8192), 16, 0, 0); } while (0)
; #define PG8_LDA(dst, b, h) do { _Pragma("unroll") for (int m = 0; m < 4; ++m) _Pragma("unroll") for (int k = 0; k < 2; ++k) dst[m][k] = *(const PG8_LAS bf16x8*)(lds + PG8_SA(b, h) + aoff + m * 2048 + k * 1024); } while (0)
; #define PG8_MMA(ai, bj, At, Bt) do { __builtin_amdgcn_s_setprio(1); _Pragma("unroll") for (int m = 0; m < 4; ++m) _Pragma("unroll") for (int n = 0; n < 2; ++n) _Pragma("unroll") for (int k = 0; k < 2; ++k) \
;         acc[ai][bj][m][n] = __builtin_amdgcn_mfma_f32_16x16x32_bf16(Bt[n][k], At[m][k], acc[ai][bj][m][n], 0, 0, 0); __builtin_amdgcn_s_setprio(0); } while (0)
; #define PG8_WAIT_V(n) asm volatile("s_waitcnt vmcnt(" #n ")" ::: "memory")
; #define PG8_WAIT_L(n) asm volatile("s_waitcnt lgkmcnt(" #n ")" ::: "memory")
; #define PG8_BAR __builtin_amdgcn_s_barrier()
; #define PG8_SCHED __builtin_amdgcn_sched_barrier(0)
; template <class Epi, class Sched, bool ALIGN_EPI = false, bool SP2 = false>
; __device__ __forceinline__ void gemm_phase(PG8_LAS unsigned char* lds, const Gemm g, const Sched& S, const Epi& E) {
;     ...
;         for (int t = 0; t < nt; t += 2) {
;             const bool last = (t == nt - 2);
;             const char* a1 = cA + (size_t)(t + 1) * kstep;
;             const char* a2 = last ? nA : cA + (size_t)(t + 2) * kstep; const char* b2 = last ? nB : cB + (size_t)(t + 2) * kstep;
;             const char* a3 = a2 + kstep; const char* b3 = b2 + kstep;
;     ...
;             PG8_LDA(At, 1, 1); PG8_STAGE(PG8_SB(1, 0), b3, voffB); PG8_STAGE(PG8_SB(1, 1), b3 + hstep, voffB); PG8_STAGE(PG8_SA(1, 0), a3, voffA);
;             PG8_WAIT_V(8); PG8_WAIT_L(0); PG8_BAR; PG8_MMA(1, 0, At, B0); PG8_MMA(1, 1, At, B1); PG8_BAR; PG8_SCHED;
	s_add_i32 s16, s16, s55
	v_lshl_add_u64 v[164:165], v[164:165], 0, s[44:45]
	s_mov_b32 m0, s16
	ds_read_b128 v[184:187], v171 offset:49152
	ds_read_b128 v[188:191], v171 offset:50176
	ds_read_b128 v[192:195], v171 offset:51200
	ds_read_b128 v[196:199], v171 offset:52224
	ds_read_b128 v[202:205], v171 offset:53248
	ds_read_b128 v[206:209], v171 offset:54272
	ds_read_b128 v[210:213], v171 offset:55296
	ds_read_b128 v[214:217], v171 offset:56320
	global_load_lds_dwordx4 v[164:165], off
	v_lshl_add_u64 v[164:165], v[218:219], 0, s[44:45]
	s_add_i32 m0, s16, 0x2000
	s_add_i32 s16, s17, s55
	global_load_lds_dwordx4 v[164:165], off
	v_lshl_add_u64 v[164:165], v[220:221], 0, s[44:45]
	s_mov_b32 m0, s16
	s_nop 0
	global_load_lds_dwordx4 v[164:165], off
	v_lshl_add_u64 v[164:165], v[222:223], 0, s[44:45]
	s_add_i32 m0, s16, 0x2000
	s_nop 0
	global_load_lds_dwordx4 v[164:165], off
	v_lshl_add_u64 v[164:165], v[224:225], 0, s[44:45]
	s_mov_b32 m0, s62
	s_nop 0
	global_load_lds_dwordx4 v[164:165], off
	v_lshl_add_u64 v[164:165], v[226:227], 0, s[44:45]
	s_mov_b32 m0, s63
	s_nop 0
	global_load_lds_dwordx4 v[164:165], off
	s_waitcnt vmcnt(8)
	s_waitcnt lgkmcnt(0)
	s_barrier
	s_setprio 1
	s_waitcnt lgkmcnt(0)
	v_mfma_f32_16x16x32_bf16 v[60:63], v[128:131], v[184:187], v[60:63]
	v_mfma_f32_16x16x32_bf16 v[56:59], v[152:155], v[184:187], v[56:59]
	v_mfma_f32_16x16x32_bf16 v[44:47], v[128:131], v[192:195], v[44:47]
	v_mfma_f32_16x16x32_bf16 v[40:43], v[152:155], v[192:195], v[40:43]
	v_mfma_f32_16x16x32_bf16 v[28:31], v[128:131], v[202:205], v[28:31]
	v_mfma_f32_16x16x32_bf16 v[24:27], v[152:155], v[202:205], v[24:27]
	v_mfma_f32_16x16x32_bf16 v[12:15], v[128:131], v[210:213], v[12:15]
	v_mfma_f32_16x16x32_bf16 v[8:11], v[152:155], v[210:213], v[8:11]
	v_mfma_f32_16x16x32_bf16 v[60:63], v[148:151], v[188:191], v[60:63]
	v_mfma_f32_16x16x32_bf16 v[56:59], v[156:159], v[188:191], v[56:59]
	v_mfma_f32_16x16x32_bf16 v[44:47], v[148:151], v[196:199], v[44:47]
	v_mfma_f32_16x16x32_bf16 v[40:43], v[156:159], v[196:199], v[40:43]
	v_mfma_f32_16x16x32_bf16 v[28:31], v[148:151], v[206:209], v[28:31]
	v_mfma_f32_16x16x32_bf16 v[24:27], v[156:159], v[206:209], v[24:27]
	v_mfma_f32_16x16x32_bf16 v[12:15], v[148:151], v[214:217], v[12:15]
	v_mfma_f32_16x16x32_bf16 v[8:11], v[156:159], v[214:217], v[8:11]
	s_setprio 0
	s_setprio 1
	v_mfma_f32_16x16x32_bf16 v[52:55], v[160:163], v[184:187], v[52:55]
	v_mfma_f32_16x16x32_bf16 v[48:51], v[176:179], v[184:187], v[48:51]
	v_mfma_f32_16x16x32_bf16 v[36:39], v[160:163], v[192:195], v[36:39]
	v_mfma_f32_16x16x32_bf16 v[32:35], v[176:179], v[192:195], v[32:35]
	v_mfma_f32_16x16x32_bf16 v[20:23], v[160:163], v[202:205], v[20:23]
	v_mfma_f32_16x16x32_bf16 v[16:19], v[176:179], v[202:205], v[16:19]
	v_mfma_f32_16x16x32_bf16 v[4:7], v[160:163], v[210:213], v[4:7]
	v_mfma_f32_16x16x32_bf16 v[0:3], v[176:179], v[210:213], v[0:3]
	v_mfma_f32_16x16x32_bf16 v[52:55], v[172:175], v[188:191], v[52:55]
	v_mfma_f32_16x16x32_bf16 v[48:51], v[180:183], v[188:191], v[48:51]
	v_mfma_f32_16x16x32_bf16 v[36:39], v[172:175], v[196:199], v[36:39]
	v_mfma_f32_16x16x32_bf16 v[32:35], v[180:183], v[196:199], v[32:35]
	v_mfma_f32_16x16x32_bf16 v[20:23], v[172:175], v[206:209], v[20:23]
	v_mfma_f32_16x16x32_bf16 v[16:19], v[180:183], v[206:209], v[16:19]
	v_mfma_f32_16x16x32_bf16 v[4:7], v[172:175], v[214:217], v[4:7]
	v_mfma_f32_16x16x32_bf16 v[0:3], v[180:183], v[214:217], v[0:3]
	s_setprio 0
	s_barrier
	s_add_u32 s6, s6, 0x100
	s_addc_u32 s7, s7, 0
	s_add_u32 s79, s79, 0x100
	s_addc_u32 s80, s80, 0
	s_cmp_ge_i32 s81, s68
	s_mov_b32 s52, s81
	s_cbranch_scc1 .LBB0_729

; #define PG8_STAGE(bufoff, gbase, voff) do { _Pragma("unroll") for (int _i = 0; _i < 2; ++_i) \
;         __builtin_amdgcn_global_load_lds((const unsigned*)((const char*)(gbase) + (voff)[_i]), (PG8_LAS unsigned*)(lds + (bufoff) + ldsw + _i * 8192), 16, 0, 0); } while (0)
; #define PG8_LDA(dst, b, h) do { _Pragma("unroll") for (int m = 0; m < 4; ++m) _Pragma("unroll") for (int k = 0; k < 2; ++k) dst[m][k] = *(const PG8_LAS bf16x8*)(lds + PG8_SA(b, h) + aoff + m * 2048 + k * 1024); } while (0)
; #define PG8_LDB(dst, b, h) do { _Pragma("unroll") for (int n = 0; n < 2; ++n) _Pragma("unroll") for (int k = 0; k < 2; ++k) dst[n][k] = *(const PG8_LAS bf16x8*)(lds + PG8_SB(b, h) + boff + n * 2048 + k * 1024); } while (0)
; #define PG8_MMA(ai, bj, At, Bt) do { __builtin_amdgcn_s_setprio(1); _Pragma("unroll") for (int m = 0; m < 4; ++m) _Pragma("unroll") for (int n = 0; n < 2; ++n) _Pragma("unroll") for (int k = 0; k < 2; ++k) \
;         acc[ai][bj][m][n] = __builtin_amdgcn_mfma_f32_16x16x32_bf16(Bt[n][k], At[m][k], acc[ai][bj][m][n], 0, 0, 0); __builtin_amdgcn_s_setprio(0); } while (0)
; #define PG8_WAIT_V(n) asm volatile("s_waitcnt vmcnt(" #n ")" ::: "memory")
; #define PG8_WAIT_L(n) asm volatile("s_waitcnt lgkmcnt(" #n ")" ::: "memory")
; #define PG8_BAR __builtin_amdgcn_s_barrier()
; #define PG8_SCHED __builtin_amdgcn_sched_barrier(0)
; template <class Epi, class Sched, bool ALIGN_EPI = false, bool SP2 = false>
; __device__ __forceinline__ void gemm_phase(PG8_LAS unsigned char* lds, const Gemm g, const Sched& S, const Epi& E) {
;     ...
;             PG8_LDB(B0, 0, 0); PG8_LDB(B1, 0, 1); PG8_SCHED; PG8_LDA(At, 0, 0); PG8_STAGE(PG8_SA(1, 1), a1 + hstep, voffA);
;             PG8_WAIT_V(8); PG8_WAIT_L(0); PG8_BAR; PG8_MMA(0, 0, At, B0); PG8_MMA(0, 1, At, B1); PG8_BAR; PG8_SCHED;
;             PG8_LDA(At, 0, 1); PG8_STAGE(PG8_SB(0, 0), b2, voffB); PG8_STAGE(PG8_SB(0, 1), b2 + hstep, voffB); PG8_STAGE(PG8_SA(0, 0), a2, voffA);
;             PG8_WAIT_V(8); PG8_WAIT_L(0); PG8_BAR; PG8_MMA(1, 0, At, B0); PG8_MMA(1, 1, At, B1); PG8_BAR; PG8_SCHED;
.Lcz_go_875:
	s_add_u32 s50, s50, 0x80
	s_addc_u32 s51, s51, 0
	s_add_u32 s78, s52, 0x100
	s_addc_u32 s79, s53, 0
	s_mov_b32 s52, 0
	.p2alignl 6, 3212836864
	ds_read_b128 v[144:147], v151
	ds_read_b128 v[156:159], v151 offset:1024
	ds_read_b128 v[160:163], v151 offset:2048
	ds_read_b128 v[164:167], v151 offset:3072
	ds_read_b128 v[168:171], v152
	ds_read_b128 v[172:175], v152 offset:1024
	ds_read_b128 v[176:179], v152 offset:2048
	ds_read_b128 v[180:183], v152 offset:3072
	s_add_i32 s80, s52, 2
	s_add_u32 s16, s50, 0x80
	s_addc_u32 s17, s51, 0
	s_cmp_eq_u32 s68, s52
	s_cselect_b32 s52, s0, s16
	s_cselect_b32 s53, s1, s17
	s_cselect_b32 s83, s49, s79
	s_cselect_b32 s82, s48, s78
	v_lshl_add_u64 v[218:219], s[50:51], 0, v[136:137]
	s_add_i32 m0, s56, 0xc000
	ds_read_b128 v[184:187], v153
	ds_read_b128 v[188:191], v153 offset:1024
	ds_read_b128 v[192:195], v153 offset:2048
	ds_read_b128 v[196:199], v153 offset:3072
	ds_read_b128 v[202:205], v153 offset:4096
	ds_read_b128 v[206:209], v153 offset:5120
	ds_read_b128 v[210:213], v153 offset:6144
	ds_read_b128 v[214:217], v153 offset:7168
	global_load_lds_dwordx4 v[218:219], off
	v_lshl_add_u64 v[218:219], s[50:51], 0, v[138:139]
	s_add_i32 m0, s56, 0xe000
	s_nop 0
	global_load_lds_dwordx4 v[218:219], off
	s_waitcnt vmcnt(8)
	s_waitcnt lgkmcnt(0)
	s_barrier
	s_setprio 1
	s_waitcnt lgkmcnt(0)
	v_mfma_f32_16x16x32_bf16 v[124:127], v[144:147], v[184:187], 0
	v_mfma_f32_16x16x32_bf16 v[120:123], v[160:163], v[184:187], 0
	v_mfma_f32_16x16x32_bf16 v[108:111], v[144:147], v[192:195], 0
	v_mfma_f32_16x16x32_bf16 v[104:107], v[160:163], v[192:195], 0
	v_mfma_f32_16x16x32_bf16 v[92:95], v[144:147], v[202:205], 0
	v_mfma_f32_16x16x32_bf16 v[88:91], v[160:163], v[202:205], 0
	v_mfma_f32_16x16x32_bf16 v[76:79], v[144:147], v[210:213], 0
	v_mfma_f32_16x16x32_bf16 v[72:75], v[160:163], v[210:213], 0
	v_mfma_f32_16x16x32_bf16 v[124:127], v[156:159], v[188:191], v[124:127]
	v_mfma_f32_16x16x32_bf16 v[120:123], v[164:167], v[188:191], v[120:123]
	v_mfma_f32_16x16x32_bf16 v[108:111], v[156:159], v[196:199], v[108:111]
	v_mfma_f32_16x16x32_bf16 v[104:107], v[164:167], v[196:199], v[104:107]
	v_mfma_f32_16x16x32_bf16 v[92:95], v[156:159], v[206:209], v[92:95]
	v_mfma_f32_16x16x32_bf16 v[88:91], v[164:167], v[206:209], v[88:91]
	v_mfma_f32_16x16x32_bf16 v[76:79], v[156:159], v[214:217], v[76:79]
	v_mfma_f32_16x16x32_bf16 v[72:75], v[164:167], v[214:217], v[72:75]
	s_setprio 0
	s_setprio 1
	v_mfma_f32_16x16x32_bf16 v[116:119], v[168:171], v[184:187], 0
	v_mfma_f32_16x16x32_bf16 v[112:115], v[176:179], v[184:187], 0
	v_mfma_f32_16x16x32_bf16 v[100:103], v[168:171], v[192:195], 0
	v_mfma_f32_16x16x32_bf16 v[96:99], v[176:179], v[192:195], 0
	v_mfma_f32_16x16x32_bf16 v[84:87], v[168:171], v[202:205], 0
	v_mfma_f32_16x16x32_bf16 v[80:83], v[176:179], v[202:205], 0
	v_mfma_f32_16x16x32_bf16 v[68:71], v[168:171], v[210:213], 0
	v_mfma_f32_16x16x32_bf16 v[64:67], v[176:179], v[210:213], 0
	v_mfma_f32_16x16x32_bf16 v[116:119], v[172:175], v[188:191], v[116:119]
	v_mfma_f32_16x16x32_bf16 v[112:115], v[180:183], v[188:191], v[112:115]
	v_mfma_f32_16x16x32_bf16 v[100:103], v[172:175], v[196:199], v[100:103]
	v_mfma_f32_16x16x32_bf16 v[96:99], v[180:183], v[196:199], v[96:99]
	v_mfma_f32_16x16x32_bf16 v[84:87], v[172:175], v[206:209], v[84:87]
	v_mfma_f32_16x16x32_bf16 v[80:83], v[180:183], v[206:209], v[80:83]
	v_mfma_f32_16x16x32_bf16 v[68:71], v[172:175], v[214:217], v[68:71]
	v_mfma_f32_16x16x32_bf16 v[64:67], v[180:183], v[214:217], v[64:67]
	s_setprio 0
	s_barrier
	s_add_i32 s16, s72, s55
	v_lshl_add_u64 v[218:219], s[82:83], 0, v[130:131]
	s_mov_b32 m0, s16
	ds_read_b128 v[184:187], v153 offset:16384
	ds_read_b128 v[188:191], v153 offset:17408
	ds_read_b128 v[192:195], v153 offset:18432
	ds_read_b128 v[196:199], v153 offset:19456
	ds_read_b128 v[202:205], v153 offset:20480
	ds_read_b128 v[206:209], v153 offset:21504
	ds_read_b128 v[210:213], v153 offset:22528
	ds_read_b128 v[214:217], v153 offset:23552
	global_load_lds_dwordx4 v[218:219], off
	s_add_i32 m0, s16, 0x2000
	v_lshl_add_u64 v[220:221], s[82:83], 0, v[134:135]
	s_add_u32 s82, s82, s12
	s_addc_u32 s83, s83, s13
	s_add_i32 s16, s73, s55
	global_load_lds_dwordx4 v[220:221], off
	v_lshl_add_u64 v[222:223], s[82:83], 0, v[130:131]
	s_mov_b32 m0, s16
	v_lshl_add_u64 v[224:225], s[82:83], 0, v[134:135]
	global_load_lds_dwordx4 v[222:223], off
	s_add_i32 m0, s16, 0x2000
	v_lshl_add_u64 v[226:227], s[52:53], 0, v[128:129]
	global_load_lds_dwordx4 v[224:225], off
	s_mov_b32 m0, s56
	v_lshl_add_u64 v[228:229], s[52:53], 0, v[132:133]
	global_load_lds_dwordx4 v[226:227], off
	s_mov_b32 m0, s57
	s_nop 0
	global_load_lds_dwordx4 v[228:229], off
	s_waitcnt vmcnt(8)
	s_waitcnt lgkmcnt(0)
	s_barrier
; #define PG8_STAGE(bufoff, gbase, voff) do { _Pragma("unroll") for (int _i = 0; _i < 2; ++_i) \
;         __builtin_amdgcn_global_load_lds((const unsigned*)((const char*)(gbase) + (voff)[_i]), (PG8_LAS unsigned*)(lds + (bufoff) + ldsw + _i * 8192), 16, 0, 0); } while (0)
; #define PG8_LDA(dst, b, h) do { _Pragma("unroll") for (int m = 0; m < 4; ++m) _Pragma("unroll") for (int k = 0; k < 2; ++k) dst[m][k] = *(const PG8_LAS bf16x8*)(lds + PG8_SA(b, h) + aoff + m * 2048 + k * 1024); } while (0)
; #define PG8_LDB(dst, b, h) do { _Pragma("unroll") for (int n = 0; n < 2; ++n) _Pragma("unroll") for (int k = 0; k < 2; ++k) dst[n][k] = *(const PG8_LAS bf16x8*)(lds + PG8_SB(b, h) + boff + n * 2048 + k * 1024); } while (0)
; #define PG8_MMA(ai, bj, At, Bt) do { __builtin_amdgcn_s_setprio(1); _Pragma("unroll") for (int m = 0; m < 4; ++m) _Pragma("unroll") for (int n = 0; n < 2; ++n) _Pragma("unroll") for (int k = 0; k < 2; ++k) \
;         acc[ai][bj][m][n] = __builtin_amdgcn_mfma_f32_16x16x32_bf16(Bt[n][k], At[m][k], acc[ai][bj][m][n], 0, 0, 0); __builtin_amdgcn_s_setprio(0); } while (0)
; #define PG8_WAIT_V(n) asm volatile("s_waitcnt vmcnt(" #n ")" ::: "memory")
; #define PG8_WAIT_L(n) asm volatile("s_waitcnt lgkmcnt(" #n ")" ::: "memory")
; #define PG8_BAR __builtin_amdgcn_s_barrier()
; #define PG8_SCHED __builtin_amdgcn_sched_barrier(0)
; template <class Epi, class Sched, bool ALIGN_EPI = false, bool SP2 = false>
; __device__ __forceinline__ void gemm_phase(PG8_LAS unsigned char* lds, const Gemm g, const Sched& S, const Epi& E) {
;     ...
;             PG8_WAIT_V(8); PG8_WAIT_L(0); PG8_BAR; PG8_MMA(1, 0, At, B0); PG8_MMA(1, 1, At, B1); PG8_BAR; PG8_SCHED;
;             PG8_LDB(B0, 1, 0); PG8_LDB(B1, 1, 1); PG8_SCHED; PG8_LDA(At, 1, 0); PG8_STAGE(PG8_SA(0, 1), a2 + hstep, voffA);
;             PG8_WAIT_V(8); PG8_WAIT_L(0); PG8_BAR; PG8_MMA(0, 0, At, B0); PG8_MMA(0, 1, At, B1); PG8_BAR; PG8_SCHED;
	s_setprio 1
	s_waitcnt lgkmcnt(0)
	v_mfma_f32_16x16x32_bf16 v[60:63], v[144:147], v[184:187], 0
	v_mfma_f32_16x16x32_bf16 v[56:59], v[160:163], v[184:187], 0
	v_mfma_f32_16x16x32_bf16 v[44:47], v[144:147], v[192:195], 0
	v_mfma_f32_16x16x32_bf16 v[40:43], v[160:163], v[192:195], 0
	v_mfma_f32_16x16x32_bf16 v[28:31], v[144:147], v[202:205], 0
	v_mfma_f32_16x16x32_bf16 v[24:27], v[160:163], v[202:205], 0
	v_mfma_f32_16x16x32_bf16 v[12:15], v[144:147], v[210:213], 0
	v_mfma_f32_16x16x32_bf16 v[8:11], v[160:163], v[210:213], 0
	v_mfma_f32_16x16x32_bf16 v[60:63], v[156:159], v[188:191], v[60:63]
	v_mfma_f32_16x16x32_bf16 v[56:59], v[164:167], v[188:191], v[56:59]
	v_mfma_f32_16x16x32_bf16 v[44:47], v[156:159], v[196:199], v[44:47]
	v_mfma_f32_16x16x32_bf16 v[40:43], v[164:167], v[196:199], v[40:43]
	v_mfma_f32_16x16x32_bf16 v[28:31], v[156:159], v[206:209], v[28:31]
	v_mfma_f32_16x16x32_bf16 v[24:27], v[164:167], v[206:209], v[24:27]
	v_mfma_f32_16x16x32_bf16 v[12:15], v[156:159], v[214:217], v[12:15]
	v_mfma_f32_16x16x32_bf16 v[8:11], v[164:167], v[214:217], v[8:11]
	s_setprio 0
	s_setprio 1
	v_mfma_f32_16x16x32_bf16 v[52:55], v[168:171], v[184:187], 0
	v_mfma_f32_16x16x32_bf16 v[48:51], v[176:179], v[184:187], 0
	v_mfma_f32_16x16x32_bf16 v[36:39], v[168:171], v[192:195], 0
	v_mfma_f32_16x16x32_bf16 v[32:35], v[176:179], v[192:195], 0
	v_mfma_f32_16x16x32_bf16 v[20:23], v[168:171], v[202:205], 0
	v_mfma_f32_16x16x32_bf16 v[16:19], v[176:179], v[202:205], 0
	v_mfma_f32_16x16x32_bf16 v[4:7], v[168:171], v[210:213], 0
	v_mfma_f32_16x16x32_bf16 v[0:3], v[176:179], v[210:213], 0
	v_mfma_f32_16x16x32_bf16 v[52:55], v[172:175], v[188:191], v[52:55]
	v_mfma_f32_16x16x32_bf16 v[48:51], v[180:183], v[188:191], v[48:51]
	v_mfma_f32_16x16x32_bf16 v[36:39], v[172:175], v[196:199], v[36:39]
	v_mfma_f32_16x16x32_bf16 v[32:35], v[180:183], v[196:199], v[32:35]
	v_mfma_f32_16x16x32_bf16 v[20:23], v[172:175], v[206:209], v[20:23]
	v_mfma_f32_16x16x32_bf16 v[16:19], v[180:183], v[206:209], v[16:19]
	v_mfma_f32_16x16x32_bf16 v[4:7], v[172:175], v[214:217], v[4:7]
	v_mfma_f32_16x16x32_bf16 v[0:3], v[180:183], v[214:217], v[0:3]
	s_setprio 0
	s_barrier
	s_add_i32 s16, 0, 0x18000
	v_add_u32_e32 v155, s16, v149
	s_add_i32 s17, 0, 0x1c000
	ds_read_b128 v[144:147], v155
	ds_read_b128 v[156:159], v155 offset:1024
	ds_read_b128 v[160:163], v155 offset:2048
	ds_read_b128 v[164:167], v155 offset:3072
	v_add_u32_e32 v155, s17, v149
	ds_read_b128 v[168:171], v155
	ds_read_b128 v[172:175], v155 offset:1024
	ds_read_b128 v[176:179], v155 offset:2048
	ds_read_b128 v[180:183], v155 offset:3072
	s_add_u32 s52, s52, s12
	s_addc_u32 s53, s53, s13
	s_mov_b32 m0, s58
	v_lshl_add_u64 v[230:231], s[52:53], 0, v[128:129]
	ds_read_b128 v[184:187], v153 offset:32768
	ds_read_b128 v[188:191], v153 offset:33792
	ds_read_b128 v[192:195], v153 offset:34816
	ds_read_b128 v[196:199], v153 offset:35840
	ds_read_b128 v[202:205], v153 offset:36864
	ds_read_b128 v[206:209], v153 offset:37888
	ds_read_b128 v[210:213], v153 offset:38912
	ds_read_b128 v[214:217], v153 offset:39936
	global_load_lds_dwordx4 v[230:231], off
	v_lshl_add_u64 v[230:231], s[52:53], 0, v[132:133]
	s_mov_b32 m0, s59
	s_nop 0
	global_load_lds_dwordx4 v[230:231], off
	s_waitcnt vmcnt(8)
	s_waitcnt lgkmcnt(0)
	s_barrier
	s_setprio 1
	s_waitcnt lgkmcnt(0)
	v_mfma_f32_16x16x32_bf16 v[124:127], v[144:147], v[184:187], v[124:127]
	v_mfma_f32_16x16x32_bf16 v[120:123], v[160:163], v[184:187], v[120:123]
	v_mfma_f32_16x16x32_bf16 v[108:111], v[144:147], v[192:195], v[108:111]
	v_mfma_f32_16x16x32_bf16 v[104:107], v[160:163], v[192:195], v[104:107]
	v_mfma_f32_16x16x32_bf16 v[92:95], v[144:147], v[202:205], v[92:95]
	v_mfma_f32_16x16x32_bf16 v[88:91], v[160:163], v[202:205], v[88:91]
	v_mfma_f32_16x16x32_bf16 v[76:79], v[144:147], v[210:213], v[76:79]
	v_mfma_f32_16x16x32_bf16 v[72:75], v[160:163], v[210:213], v[72:75]
	v_mfma_f32_16x16x32_bf16 v[124:127], v[156:159], v[188:191], v[124:127]
	v_mfma_f32_16x16x32_bf16 v[120:123], v[164:167], v[188:191], v[120:123]
	v_mfma_f32_16x16x32_bf16 v[108:111], v[156:159], v[196:199], v[108:111]
	v_mfma_f32_16x16x32_bf16 v[104:107], v[164:167], v[196:199], v[104:107]
	v_mfma_f32_16x16x32_bf16 v[92:95], v[156:159], v[206:209], v[92:95]
	v_mfma_f32_16x16x32_bf16 v[88:91], v[164:167], v[206:209], v[88:91]
	v_mfma_f32_16x16x32_bf16 v[76:79], v[156:159], v[214:217], v[76:79]
	v_mfma_f32_16x16x32_bf16 v[72:75], v[164:167], v[214:217], v[72:75]
	s_setprio 0
	s_setprio 1
	v_mfma_f32_16x16x32_bf16 v[116:119], v[168:171], v[184:187], v[116:119]
	v_mfma_f32_16x16x32_bf16 v[112:115], v[176:179], v[184:187], v[112:115]
	v_mfma_f32_16x16x32_bf16 v[100:103], v[168:171], v[192:195], v[100:103]
	v_mfma_f32_16x16x32_bf16 v[96:99], v[176:179], v[192:195], v[96:99]
	v_mfma_f32_16x16x32_bf16 v[84:87], v[168:171], v[202:205], v[84:87]
	v_mfma_f32_16x16x32_bf16 v[80:83], v[176:179], v[202:205], v[80:83]
	v_mfma_f32_16x16x32_bf16 v[68:71], v[168:171], v[210:213], v[68:71]
	v_mfma_f32_16x16x32_bf16 v[64:67], v[176:179], v[210:213], v[64:67]
	v_mfma_f32_16x16x32_bf16 v[116:119], v[172:175], v[188:191], v[116:119]
	v_mfma_f32_16x16x32_bf16 v[112:115], v[180:183], v[188:191], v[112:115]
	v_mfma_f32_16x16x32_bf16 v[100:103], v[172:175], v[196:199], v[100:103]
	v_mfma_f32_16x16x32_bf16 v[96:99], v[180:183], v[196:199], v[96:99]
	v_mfma_f32_16x16x32_bf16 v[84:87], v[172:175], v[206:209], v[84:87]
	v_mfma_f32_16x16x32_bf16 v[80:83], v[180:183], v[206:209], v[80:83]
	v_mfma_f32_16x16x32_bf16 v[68:71], v[172:175], v[214:217], v[68:71]
	v_mfma_f32_16x16x32_bf16 v[64:67], v[180:183], v[214:217], v[64:67]
	s_setprio 0
	s_barrier
; #define PG8_STAGE(bufoff, gbase, voff) do { _Pragma("unroll") for (int _i = 0; _i < 2; ++_i) \
;         __builtin_amdgcn_global_load_lds((const unsigned*)((const char*)(gbase) + (voff)[_i]), (PG8_LAS unsigned*)(lds + (bufoff) + ldsw + _i * 8192), 16, 0, 0); } while (0)
; #define PG8_LDA(dst, b, h) do { _Pragma("unroll") for (int m = 0; m < 4; ++m) _Pragma("unroll") for (int k = 0; k < 2; ++k) dst[m][k] = *(const PG8_LAS bf16x8*)(lds + PG8_SA(b, h) + aoff + m * 2048 + k * 1024); } while (0)
; #define PG8_MMA(ai, bj, At, Bt) do { __builtin_amdgcn_s_setprio(1); _Pragma("unroll") for (int m = 0; m < 4; ++m) _Pragma("unroll") for (int n = 0; n < 2; ++n) _Pragma("unroll") for (int k = 0; k < 2; ++k) \
;         acc[ai][bj][m][n] = __builtin_amdgcn_mfma_f32_16x16x32_bf16(Bt[n][k], At[m][k], acc[ai][bj][m][n], 0, 0, 0); __builtin_amdgcn_s_setprio(0); } while (0)
; #define PG8_WAIT_V(n) asm volatile("s_waitcnt vmcnt(" #n ")" ::: "memory")
; #define PG8_WAIT_L(n) asm volatile("s_waitcnt lgkmcnt(" #n ")" ::: "memory")
; #define PG8_BAR __builtin_amdgcn_s_barrier()
; #define PG8_SCHED __builtin_amdgcn_sched_barrier(0)
; template <class Epi, class Sched, bool ALIGN_EPI = false, bool SP2 = false>
; __device__ __forceinline__ void gemm_phase(PG8_LAS unsigned char* lds, const Gemm g, const Sched& S, const Epi& E) {
;     ...
;         for (int t = 0; t < nt; t += 2) {
;             const bool last = (t == nt - 2);
;             const char* a1 = cA + (size_t)(t + 1) * kstep;
;             const char* a2 = last ? nA : cA + (size_t)(t + 2) * kstep; const char* b2 = last ? nB : cB + (size_t)(t + 2) * kstep;
;             const char* a3 = a2 + kstep; const char* b3 = b2 + kstep;
;     ...
;             PG8_LDA(At, 1, 1); PG8_STAGE(PG8_SB(1, 0), b3, voffB); PG8_STAGE(PG8_SB(1, 1), b3 + hstep, voffB); PG8_STAGE(PG8_SA(1, 0), a3, voffA);
;             PG8_WAIT_V(8); PG8_WAIT_L(0); PG8_BAR; PG8_MMA(1, 0, At, B0); PG8_MMA(1, 1, At, B1); PG8_BAR; PG8_SCHED;
	s_add_i32 s16, s16, s55
	v_lshl_add_u64 v[218:219], v[218:219], 0, s[42:43]
	s_mov_b32 m0, s16
	ds_read_b128 v[184:187], v153 offset:49152
	ds_read_b128 v[188:191], v153 offset:50176
	ds_read_b128 v[192:195], v153 offset:51200
	ds_read_b128 v[196:199], v153 offset:52224
	ds_read_b128 v[202:205], v153 offset:53248
	ds_read_b128 v[206:209], v153 offset:54272
	ds_read_b128 v[210:213], v153 offset:55296
	ds_read_b128 v[214:217], v153 offset:56320
	global_load_lds_dwordx4 v[218:219], off
	v_lshl_add_u64 v[218:219], v[220:221], 0, s[42:43]
	s_add_i32 m0, s16, 0x2000
	s_add_i32 s16, s17, s55
	global_load_lds_dwordx4 v[218:219], off
	v_lshl_add_u64 v[218:219], v[222:223], 0, s[42:43]
	s_mov_b32 m0, s16
	s_nop 0
	global_load_lds_dwordx4 v[218:219], off
	v_lshl_add_u64 v[218:219], v[224:225], 0, s[42:43]
	s_add_i32 m0, s16, 0x2000
	s_nop 0
	global_load_lds_dwordx4 v[218:219], off
	v_lshl_add_u64 v[218:219], v[226:227], 0, s[42:43]
	s_mov_b32 m0, s60
	s_nop 0
	global_load_lds_dwordx4 v[218:219], off
	v_lshl_add_u64 v[218:219], v[228:229], 0, s[42:43]
	s_mov_b32 m0, s61
	s_nop 0
	global_load_lds_dwordx4 v[218:219], off
	s_waitcnt vmcnt(8)
	s_waitcnt lgkmcnt(0)
	s_barrier
	s_setprio 1
	s_waitcnt lgkmcnt(0)
	v_mfma_f32_16x16x32_bf16 v[60:63], v[144:147], v[184:187], v[60:63]
	v_mfma_f32_16x16x32_bf16 v[56:59], v[160:163], v[184:187], v[56:59]
	v_mfma_f32_16x16x32_bf16 v[44:47], v[144:147], v[192:195], v[44:47]
	v_mfma_f32_16x16x32_bf16 v[40:43], v[160:163], v[192:195], v[40:43]
	v_mfma_f32_16x16x32_bf16 v[28:31], v[144:147], v[202:205], v[28:31]
	v_mfma_f32_16x16x32_bf16 v[24:27], v[160:163], v[202:205], v[24:27]
	v_mfma_f32_16x16x32_bf16 v[12:15], v[144:147], v[210:213], v[12:15]
	v_mfma_f32_16x16x32_bf16 v[8:11], v[160:163], v[210:213], v[8:11]
	v_mfma_f32_16x16x32_bf16 v[60:63], v[156:159], v[188:191], v[60:63]
	v_mfma_f32_16x16x32_bf16 v[56:59], v[164:167], v[188:191], v[56:59]
	v_mfma_f32_16x16x32_bf16 v[44:47], v[156:159], v[196:199], v[44:47]
	v_mfma_f32_16x16x32_bf16 v[40:43], v[164:167], v[196:199], v[40:43]
	v_mfma_f32_16x16x32_bf16 v[28:31], v[156:159], v[206:209], v[28:31]
	v_mfma_f32_16x16x32_bf16 v[24:27], v[164:167], v[206:209], v[24:27]
	v_mfma_f32_16x16x32_bf16 v[12:15], v[156:159], v[214:217], v[12:15]
	v_mfma_f32_16x16x32_bf16 v[8:11], v[164:167], v[214:217], v[8:11]
	s_setprio 0
	s_setprio 1
	v_mfma_f32_16x16x32_bf16 v[52:55], v[168:171], v[184:187], v[52:55]
	v_mfma_f32_16x16x32_bf16 v[48:51], v[176:179], v[184:187], v[48:51]
	v_mfma_f32_16x16x32_bf16 v[36:39], v[168:171], v[192:195], v[36:39]
	v_mfma_f32_16x16x32_bf16 v[32:35], v[176:179], v[192:195], v[32:35]
	v_mfma_f32_16x16x32_bf16 v[20:23], v[168:171], v[202:205], v[20:23]
	v_mfma_f32_16x16x32_bf16 v[16:19], v[176:179], v[202:205], v[16:19]
	v_mfma_f32_16x16x32_bf16 v[4:7], v[168:171], v[210:213], v[4:7]
	v_mfma_f32_16x16x32_bf16 v[0:3], v[176:179], v[210:213], v[0:3]
	v_mfma_f32_16x16x32_bf16 v[52:55], v[172:175], v[188:191], v[52:55]
	v_mfma_f32_16x16x32_bf16 v[48:51], v[180:183], v[188:191], v[48:51]
	v_mfma_f32_16x16x32_bf16 v[36:39], v[172:175], v[196:199], v[36:39]
	v_mfma_f32_16x16x32_bf16 v[32:35], v[180:183], v[196:199], v[32:35]
	v_mfma_f32_16x16x32_bf16 v[20:23], v[172:175], v[206:209], v[20:23]
	v_mfma_f32_16x16x32_bf16 v[16:19], v[180:183], v[206:209], v[16:19]
	v_mfma_f32_16x16x32_bf16 v[4:7], v[172:175], v[214:217], v[4:7]
	v_mfma_f32_16x16x32_bf16 v[0:3], v[180:183], v[214:217], v[0:3]
	s_setprio 0
	s_barrier
	s_add_u32 s50, s50, 0x100
	s_addc_u32 s51, s51, 0
	s_add_u32 s78, s78, 0x100
	s_addc_u32 s79, s79, 0
	s_cmp_ge_i32 s80, s63
	s_mov_b32 s52, s80
	s_cbranch_scc1 .LBB0_876

; #define PG8_STAGE(bufoff, gbase, voff) do { _Pragma("unroll") for (int _i = 0; _i < 2; ++_i) \
;         __builtin_amdgcn_global_load_lds((const unsigned*)((const char*)(gbase) + (voff)[_i]), (PG8_LAS unsigned*)(lds + (bufoff) + ldsw + _i * 8192), 16, 0, 0); } while (0)
; #define PG8_LDA(dst, b, h) do { _Pragma("unroll") for (int m = 0; m < 4; ++m) _Pragma("unroll") for (int k = 0; k < 2; ++k) dst[m][k] = *(const PG8_LAS bf16x8*)(lds + PG8_SA(b, h) + aoff + m * 2048 + k * 1024); } while (0)
; #define PG8_LDB(dst, b, h) do { _Pragma("unroll") for (int n = 0; n < 2; ++n) _Pragma("unroll") for (int k = 0; k < 2; ++k) dst[n][k] = *(const PG8_LAS bf16x8*)(lds + PG8_SB(b, h) + boff + n * 2048 + k * 1024); } while (0)
; #define PG8_MMA(ai, bj, At, Bt) do { __builtin_amdgcn_s_setprio(1); _Pragma("unroll") for (int m = 0; m < 4; ++m) _Pragma("unroll") for (int n = 0; n < 2; ++n) _Pragma("unroll") for (int k = 0; k < 2; ++k) \
;         acc[ai][bj][m][n] = __builtin_amdgcn_mfma_f32_16x16x32_bf16(Bt[n][k], At[m][k], acc[ai][bj][m][n], 0, 0, 0); __builtin_amdgcn_s_setprio(0); } while (0)
; #define PG8_WAIT_V(n) asm volatile("s_waitcnt vmcnt(" #n ")" ::: "memory")
; #define PG8_WAIT_L(n) asm volatile("s_waitcnt lgkmcnt(" #n ")" ::: "memory")
; #define PG8_BAR __builtin_amdgcn_s_barrier()
; #define PG8_SCHED __builtin_amdgcn_sched_barrier(0)
; template <class Epi, class Sched, bool ALIGN_EPI = false, bool SP2 = false>
; __device__ __forceinline__ void gemm_phase(PG8_LAS unsigned char* lds, const Gemm g, const Sched& S, const Epi& E) {
;     ...
;             PG8_LDB(B0, 0, 0); PG8_LDB(B1, 0, 1); PG8_SCHED; PG8_LDA(At, 0, 0); PG8_STAGE(PG8_SA(1, 1), a1 + hstep, voffA);
;             PG8_WAIT_V(8); PG8_WAIT_L(0); PG8_BAR; PG8_MMA(0, 0, At, B0); PG8_MMA(0, 1, At, B1); PG8_BAR; PG8_SCHED;
;             PG8_LDA(At, 0, 1); PG8_STAGE(PG8_SB(0, 0), b2, voffB); PG8_STAGE(PG8_SB(0, 1), b2 + hstep, voffB); PG8_STAGE(PG8_SA(0, 0), a2, voffA);
;             PG8_WAIT_V(8); PG8_WAIT_L(0); PG8_BAR; PG8_MMA(1, 0, At, B0); PG8_MMA(1, 1, At, B1); PG8_BAR; PG8_SCHED;
.Lcz_go_1021:
	s_add_u32 s42, s42, 0x80
	s_addc_u32 s43, s43, 0
	s_add_u32 s68, s44, 0x100
	s_addc_u32 s69, s45, 0
	s_mov_b32 s44, 0
	.p2alignl 6, 3212836864
	ds_read_b128 v[150:153], v147
	ds_read_b128 v[154:157], v147 offset:1024
	ds_read_b128 v[158:161], v147 offset:2048
	ds_read_b128 v[162:165], v147 offset:3072
	ds_read_b128 v[166:169], v148
	ds_read_b128 v[170:173], v148 offset:1024
	ds_read_b128 v[174:177], v148 offset:2048
	ds_read_b128 v[178:181], v148 offset:3072
	s_add_i32 s70, s44, 2
	s_add_u32 s16, s42, 0x80
	s_addc_u32 s17, s43, 0
	s_cmp_eq_u32 s58, s44
	s_cselect_b32 s44, s0, s16
	s_cselect_b32 s45, s1, s17
	s_cselect_b32 s73, s41, s69
	s_cselect_b32 s72, s40, s68
	v_lshl_add_u64 v[198:199], s[42:43], 0, v[136:137]
	s_add_i32 m0, s50, 0xc000
	ds_read_b128 v[182:185], v149
	ds_read_b128 v[186:189], v149 offset:1024
	ds_read_b128 v[190:193], v149 offset:2048
	ds_read_b128 v[194:197], v149 offset:3072
	ds_read_b128 v[202:205], v149 offset:4096
	ds_read_b128 v[206:209], v149 offset:5120
	ds_read_b128 v[210:213], v149 offset:6144
	ds_read_b128 v[214:217], v149 offset:7168
	global_load_lds_dwordx4 v[198:199], off
	v_lshl_add_u64 v[198:199], s[42:43], 0, v[138:139]
	s_add_i32 m0, s50, 0xe000
	s_nop 0
	global_load_lds_dwordx4 v[198:199], off
	s_waitcnt vmcnt(8)
	s_waitcnt lgkmcnt(0)
	s_barrier
	s_setprio 1
	s_waitcnt lgkmcnt(0)
	v_mfma_f32_16x16x32_bf16 v[124:127], v[150:153], v[182:185], 0
	v_mfma_f32_16x16x32_bf16 v[116:119], v[158:161], v[182:185], 0
	v_mfma_f32_16x16x32_bf16 v[108:111], v[150:153], v[190:193], 0
	v_mfma_f32_16x16x32_bf16 v[100:103], v[158:161], v[190:193], 0
	v_mfma_f32_16x16x32_bf16 v[92:95], v[150:153], v[202:205], 0
	v_mfma_f32_16x16x32_bf16 v[84:87], v[158:161], v[202:205], 0
	v_mfma_f32_16x16x32_bf16 v[76:79], v[150:153], v[210:213], 0
	v_mfma_f32_16x16x32_bf16 v[68:71], v[158:161], v[210:213], 0
	v_mfma_f32_16x16x32_bf16 v[124:127], v[154:157], v[186:189], v[124:127]
	v_mfma_f32_16x16x32_bf16 v[116:119], v[162:165], v[186:189], v[116:119]
	v_mfma_f32_16x16x32_bf16 v[108:111], v[154:157], v[194:197], v[108:111]
	v_mfma_f32_16x16x32_bf16 v[100:103], v[162:165], v[194:197], v[100:103]
	v_mfma_f32_16x16x32_bf16 v[92:95], v[154:157], v[206:209], v[92:95]
	v_mfma_f32_16x16x32_bf16 v[84:87], v[162:165], v[206:209], v[84:87]
	v_mfma_f32_16x16x32_bf16 v[76:79], v[154:157], v[214:217], v[76:79]
	v_mfma_f32_16x16x32_bf16 v[68:71], v[162:165], v[214:217], v[68:71]
	s_setprio 0
	s_setprio 1
	v_mfma_f32_16x16x32_bf16 v[120:123], v[166:169], v[182:185], 0
	v_mfma_f32_16x16x32_bf16 v[112:115], v[174:177], v[182:185], 0
	v_mfma_f32_16x16x32_bf16 v[104:107], v[166:169], v[190:193], 0
	v_mfma_f32_16x16x32_bf16 v[96:99], v[174:177], v[190:193], 0
	v_mfma_f32_16x16x32_bf16 v[88:91], v[166:169], v[202:205], 0
	v_mfma_f32_16x16x32_bf16 v[80:83], v[174:177], v[202:205], 0
	v_mfma_f32_16x16x32_bf16 v[72:75], v[166:169], v[210:213], 0
	v_mfma_f32_16x16x32_bf16 v[64:67], v[174:177], v[210:213], 0
	v_mfma_f32_16x16x32_bf16 v[120:123], v[170:173], v[186:189], v[120:123]
	v_mfma_f32_16x16x32_bf16 v[112:115], v[178:181], v[186:189], v[112:115]
	v_mfma_f32_16x16x32_bf16 v[104:107], v[170:173], v[194:197], v[104:107]
	v_mfma_f32_16x16x32_bf16 v[96:99], v[178:181], v[194:197], v[96:99]
	v_mfma_f32_16x16x32_bf16 v[88:91], v[170:173], v[206:209], v[88:91]
	v_mfma_f32_16x16x32_bf16 v[80:83], v[178:181], v[206:209], v[80:83]
	v_mfma_f32_16x16x32_bf16 v[72:75], v[170:173], v[214:217], v[72:75]
	v_mfma_f32_16x16x32_bf16 v[64:67], v[178:181], v[214:217], v[64:67]
	s_setprio 0
	s_barrier
	s_add_i32 s16, s61, s47
	v_lshl_add_u64 v[198:199], s[72:73], 0, v[132:133]
	s_mov_b32 m0, s16
	ds_read_b128 v[182:185], v149 offset:16384
	ds_read_b128 v[186:189], v149 offset:17408
	ds_read_b128 v[190:193], v149 offset:18432
	ds_read_b128 v[194:197], v149 offset:19456
	ds_read_b128 v[202:205], v149 offset:20480
	ds_read_b128 v[206:209], v149 offset:21504
	ds_read_b128 v[210:213], v149 offset:22528
	ds_read_b128 v[214:217], v149 offset:23552
	global_load_lds_dwordx4 v[198:199], off
	s_add_i32 m0, s16, 0x2000
	v_lshl_add_u64 v[218:219], s[72:73], 0, v[128:129]
	s_add_u32 s72, s72, s10
	s_addc_u32 s73, s73, s11
	s_add_i32 s16, s62, s47
	global_load_lds_dwordx4 v[218:219], off
	v_lshl_add_u64 v[220:221], s[72:73], 0, v[132:133]
	s_mov_b32 m0, s16
	v_lshl_add_u64 v[222:223], s[72:73], 0, v[128:129]
	global_load_lds_dwordx4 v[220:221], off
	s_add_i32 m0, s16, 0x2000
	v_lshl_add_u64 v[224:225], s[44:45], 0, v[134:135]
	global_load_lds_dwordx4 v[222:223], off
	s_mov_b32 m0, s50
	v_lshl_add_u64 v[226:227], s[44:45], 0, v[130:131]
	global_load_lds_dwordx4 v[224:225], off
	s_mov_b32 m0, s51
	s_nop 0
	global_load_lds_dwordx4 v[226:227], off
	s_waitcnt vmcnt(8)
	s_waitcnt lgkmcnt(0)
	s_barrier
; #define PG8_STAGE(bufoff, gbase, voff) do { _Pragma("unroll") for (int _i = 0; _i < 2; ++_i) \
;         __builtin_amdgcn_global_load_lds((const unsigned*)((const char*)(gbase) + (voff)[_i]), (PG8_LAS unsigned*)(lds + (bufoff) + ldsw + _i * 8192), 16, 0, 0); } while (0)
; #define PG8_LDA(dst, b, h) do { _Pragma("unroll") for (int m = 0; m < 4; ++m) _Pragma("unroll") for (int k = 0; k < 2; ++k) dst[m][k] = *(const PG8_LAS bf16x8*)(lds + PG8_SA(b, h) + aoff + m * 2048 + k * 1024); } while (0)
; #define PG8_LDB(dst, b, h) do { _Pragma("unroll") for (int n = 0; n < 2; ++n) _Pragma("unroll") for (int k = 0; k < 2; ++k) dst[n][k] = *(const PG8_LAS bf16x8*)(lds + PG8_SB(b, h) + boff + n * 2048 + k * 1024); } while (0)
; #define PG8_MMA(ai, bj, At, Bt) do { __builtin_amdgcn_s_setprio(1); _Pragma("unroll") for (int m = 0; m < 4; ++m) _Pragma("unroll") for (int n = 0; n < 2; ++n) _Pragma("unroll") for (int k = 0; k < 2; ++k) \
;         acc[ai][bj][m][n] = __builtin_amdgcn_mfma_f32_16x16x32_bf16(Bt[n][k], At[m][k], acc[ai][bj][m][n], 0, 0, 0); __builtin_amdgcn_s_setprio(0); } while (0)
; #define PG8_WAIT_V(n) asm volatile("s_waitcnt vmcnt(" #n ")" ::: "memory")
; #define PG8_WAIT_L(n) asm volatile("s_waitcnt lgkmcnt(" #n ")" ::: "memory")
; #define PG8_BAR __builtin_amdgcn_s_barrier()
; #define PG8_SCHED __builtin_amdgcn_sched_barrier(0)
; template <class Epi, class Sched, bool ALIGN_EPI = false, bool SP2 = false>
; __device__ __forceinline__ void gemm_phase(PG8_LAS unsigned char* lds, const Gemm g, const Sched& S, const Epi& E) {
;     ...
;             PG8_WAIT_V(8); PG8_WAIT_L(0); PG8_BAR; PG8_MMA(1, 0, At, B0); PG8_MMA(1, 1, At, B1); PG8_BAR; PG8_SCHED;
;             PG8_LDB(B0, 1, 0); PG8_LDB(B1, 1, 1); PG8_SCHED; PG8_LDA(At, 1, 0); PG8_STAGE(PG8_SA(0, 1), a2 + hstep, voffA);
;             PG8_WAIT_V(8); PG8_WAIT_L(0); PG8_BAR; PG8_MMA(0, 0, At, B0); PG8_MMA(0, 1, At, B1); PG8_BAR; PG8_SCHED;
	s_setprio 1
	s_waitcnt lgkmcnt(0)
	v_mfma_f32_16x16x32_bf16 v[60:63], v[150:153], v[182:185], 0
	v_mfma_f32_16x16x32_bf16 v[52:55], v[158:161], v[182:185], 0
	v_mfma_f32_16x16x32_bf16 v[44:47], v[150:153], v[190:193], 0
	v_mfma_f32_16x16x32_bf16 v[36:39], v[158:161], v[190:193], 0
	v_mfma_f32_16x16x32_bf16 v[28:31], v[150:153], v[202:205], 0
	v_mfma_f32_16x16x32_bf16 v[20:23], v[158:161], v[202:205], 0
	v_mfma_f32_16x16x32_bf16 v[12:15], v[150:153], v[210:213], 0
	v_mfma_f32_16x16x32_bf16 v[4:7], v[158:161], v[210:213], 0
	v_mfma_f32_16x16x32_bf16 v[60:63], v[154:157], v[186:189], v[60:63]
	v_mfma_f32_16x16x32_bf16 v[52:55], v[162:165], v[186:189], v[52:55]
	v_mfma_f32_16x16x32_bf16 v[44:47], v[154:157], v[194:197], v[44:47]
	v_mfma_f32_16x16x32_bf16 v[36:39], v[162:165], v[194:197], v[36:39]
	v_mfma_f32_16x16x32_bf16 v[28:31], v[154:157], v[206:209], v[28:31]
	v_mfma_f32_16x16x32_bf16 v[20:23], v[162:165], v[206:209], v[20:23]
	v_mfma_f32_16x16x32_bf16 v[12:15], v[154:157], v[214:217], v[12:15]
	v_mfma_f32_16x16x32_bf16 v[4:7], v[162:165], v[214:217], v[4:7]
	s_setprio 0
	s_setprio 1
	v_mfma_f32_16x16x32_bf16 v[56:59], v[166:169], v[182:185], 0
	v_mfma_f32_16x16x32_bf16 v[48:51], v[174:177], v[182:185], 0
	v_mfma_f32_16x16x32_bf16 v[40:43], v[166:169], v[190:193], 0
	v_mfma_f32_16x16x32_bf16 v[32:35], v[174:177], v[190:193], 0
	v_mfma_f32_16x16x32_bf16 v[24:27], v[166:169], v[202:205], 0
	v_mfma_f32_16x16x32_bf16 v[16:19], v[174:177], v[202:205], 0
	v_mfma_f32_16x16x32_bf16 v[8:11], v[166:169], v[210:213], 0
	v_mfma_f32_16x16x32_bf16 v[0:3], v[174:177], v[210:213], 0
	v_mfma_f32_16x16x32_bf16 v[56:59], v[170:173], v[186:189], v[56:59]
	v_mfma_f32_16x16x32_bf16 v[48:51], v[178:181], v[186:189], v[48:51]
	v_mfma_f32_16x16x32_bf16 v[40:43], v[170:173], v[194:197], v[40:43]
	v_mfma_f32_16x16x32_bf16 v[32:35], v[178:181], v[194:197], v[32:35]
	v_mfma_f32_16x16x32_bf16 v[24:27], v[170:173], v[206:209], v[24:27]
	v_mfma_f32_16x16x32_bf16 v[16:19], v[178:181], v[206:209], v[16:19]
	v_mfma_f32_16x16x32_bf16 v[8:11], v[170:173], v[214:217], v[8:11]
	v_mfma_f32_16x16x32_bf16 v[0:3], v[178:181], v[214:217], v[0:3]
	s_setprio 0
	s_barrier
	s_add_i32 s16, 0, 0x18000
	s_add_i32 s17, 0, 0x1c000
	v_add_u32_e32 v162, s16, v145
	v_add_u32_e32 v178, s17, v145
	ds_read_b128 v[150:153], v162
	ds_read_b128 v[154:157], v162 offset:1024
	ds_read_b128 v[158:161], v162 offset:2048
	ds_read_b128 v[162:165], v162 offset:3072
	ds_read_b128 v[166:169], v178
	ds_read_b128 v[170:173], v178 offset:1024
	ds_read_b128 v[174:177], v178 offset:2048
	ds_read_b128 v[178:181], v178 offset:3072
	s_add_u32 s44, s44, s10
	s_addc_u32 s45, s45, s11
	s_mov_b32 m0, s52
	v_lshl_add_u64 v[228:229], s[44:45], 0, v[134:135]
	ds_read_b128 v[182:185], v149 offset:32768
	ds_read_b128 v[186:189], v149 offset:33792
	ds_read_b128 v[190:193], v149 offset:34816
	ds_read_b128 v[194:197], v149 offset:35840
	ds_read_b128 v[202:205], v149 offset:36864
	ds_read_b128 v[206:209], v149 offset:37888
	ds_read_b128 v[210:213], v149 offset:38912
	ds_read_b128 v[214:217], v149 offset:39936
	global_load_lds_dwordx4 v[228:229], off
	v_lshl_add_u64 v[228:229], s[44:45], 0, v[130:131]
	s_mov_b32 m0, s53
	s_nop 0
	global_load_lds_dwordx4 v[228:229], off
	s_waitcnt vmcnt(8)
	s_waitcnt lgkmcnt(0)
	s_barrier
	s_setprio 1
	s_waitcnt lgkmcnt(0)
	v_mfma_f32_16x16x32_bf16 v[124:127], v[150:153], v[182:185], v[124:127]
	v_mfma_f32_16x16x32_bf16 v[116:119], v[158:161], v[182:185], v[116:119]
	v_mfma_f32_16x16x32_bf16 v[108:111], v[150:153], v[190:193], v[108:111]
	v_mfma_f32_16x16x32_bf16 v[100:103], v[158:161], v[190:193], v[100:103]
	v_mfma_f32_16x16x32_bf16 v[92:95], v[150:153], v[202:205], v[92:95]
	v_mfma_f32_16x16x32_bf16 v[84:87], v[158:161], v[202:205], v[84:87]
	v_mfma_f32_16x16x32_bf16 v[76:79], v[150:153], v[210:213], v[76:79]
	v_mfma_f32_16x16x32_bf16 v[68:71], v[158:161], v[210:213], v[68:71]
	v_mfma_f32_16x16x32_bf16 v[124:127], v[154:157], v[186:189], v[124:127]
	v_mfma_f32_16x16x32_bf16 v[116:119], v[162:165], v[186:189], v[116:119]
	v_mfma_f32_16x16x32_bf16 v[108:111], v[154:157], v[194:197], v[108:111]
	v_mfma_f32_16x16x32_bf16 v[100:103], v[162:165], v[194:197], v[100:103]
	v_mfma_f32_16x16x32_bf16 v[92:95], v[154:157], v[206:209], v[92:95]
	v_mfma_f32_16x16x32_bf16 v[84:87], v[162:165], v[206:209], v[84:87]
	v_mfma_f32_16x16x32_bf16 v[76:79], v[154:157], v[214:217], v[76:79]
	v_mfma_f32_16x16x32_bf16 v[68:71], v[162:165], v[214:217], v[68:71]
	s_setprio 0
	s_setprio 1
	v_mfma_f32_16x16x32_bf16 v[120:123], v[166:169], v[182:185], v[120:123]
	v_mfma_f32_16x16x32_bf16 v[112:115], v[174:177], v[182:185], v[112:115]
	v_mfma_f32_16x16x32_bf16 v[104:107], v[166:169], v[190:193], v[104:107]
	v_mfma_f32_16x16x32_bf16 v[96:99], v[174:177], v[190:193], v[96:99]
	v_mfma_f32_16x16x32_bf16 v[88:91], v[166:169], v[202:205], v[88:91]
	v_mfma_f32_16x16x32_bf16 v[80:83], v[174:177], v[202:205], v[80:83]
	v_mfma_f32_16x16x32_bf16 v[72:75], v[166:169], v[210:213], v[72:75]
	v_mfma_f32_16x16x32_bf16 v[64:67], v[174:177], v[210:213], v[64:67]
	v_mfma_f32_16x16x32_bf16 v[120:123], v[170:173], v[186:189], v[120:123]
	v_mfma_f32_16x16x32_bf16 v[112:115], v[178:181], v[186:189], v[112:115]
	v_mfma_f32_16x16x32_bf16 v[104:107], v[170:173], v[194:197], v[104:107]
	v_mfma_f32_16x16x32_bf16 v[96:99], v[178:181], v[194:197], v[96:99]
	v_mfma_f32_16x16x32_bf16 v[88:91], v[170:173], v[206:209], v[88:91]
	v_mfma_f32_16x16x32_bf16 v[80:83], v[178:181], v[206:209], v[80:83]
	v_mfma_f32_16x16x32_bf16 v[72:75], v[170:173], v[214:217], v[72:75]
	v_mfma_f32_16x16x32_bf16 v[64:67], v[178:181], v[214:217], v[64:67]
	s_setprio 0
	s_barrier
; #define PG8_STAGE(bufoff, gbase, voff) do { _Pragma("unroll") for (int _i = 0; _i < 2; ++_i) \
;         __builtin_amdgcn_global_load_lds((const unsigned*)((const char*)(gbase) + (voff)[_i]), (PG8_LAS unsigned*)(lds + (bufoff) + ldsw + _i * 8192), 16, 0, 0); } while (0)
; #define PG8_LDA(dst, b, h) do { _Pragma("unroll") for (int m = 0; m < 4; ++m) _Pragma("unroll") for (int k = 0; k < 2; ++k) dst[m][k] = *(const PG8_LAS bf16x8*)(lds + PG8_SA(b, h) + aoff + m * 2048 + k * 1024); } while (0)
; #define PG8_MMA(ai, bj, At, Bt) do { __builtin_amdgcn_s_setprio(1); _Pragma("unroll") for (int m = 0; m < 4; ++m) _Pragma("unroll") for (int n = 0; n < 2; ++n) _Pragma("unroll") for (int k = 0; k < 2; ++k) \
;         acc[ai][bj][m][n] = __builtin_amdgcn_mfma_f32_16x16x32_bf16(Bt[n][k], At[m][k], acc[ai][bj][m][n], 0, 0, 0); __builtin_amdgcn_s_setprio(0); } while (0)
; #define PG8_WAIT_V(n) asm volatile("s_waitcnt vmcnt(" #n ")" ::: "memory")
; #define PG8_WAIT_L(n) asm volatile("s_waitcnt lgkmcnt(" #n ")" ::: "memory")
; #define PG8_BAR __builtin_amdgcn_s_barrier()
; #define PG8_SCHED __builtin_amdgcn_sched_barrier(0)
; template <class Epi, class Sched, bool ALIGN_EPI = false, bool SP2 = false>
; __device__ __forceinline__ void gemm_phase(PG8_LAS unsigned char* lds, const Gemm g, const Sched& S, const Epi& E) {
;     ...
;         for (int t = 0; t < nt; t += 2) {
;             const bool last = (t == nt - 2);
;             const char* a1 = cA + (size_t)(t + 1) * kstep;
;             const char* a2 = last ? nA : cA + (size_t)(t + 2) * kstep; const char* b2 = last ? nB : cB + (size_t)(t + 2) * kstep;
;             const char* a3 = a2 + kstep; const char* b3 = b2 + kstep;
;     ...
;             PG8_LDA(At, 1, 1); PG8_STAGE(PG8_SB(1, 0), b3, voffB); PG8_STAGE(PG8_SB(1, 1), b3 + hstep, voffB); PG8_STAGE(PG8_SA(1, 0), a3, voffA);
;             PG8_WAIT_V(8); PG8_WAIT_L(0); PG8_BAR; PG8_MMA(1, 0, At, B0); PG8_MMA(1, 1, At, B1); PG8_BAR; PG8_SCHED;
	s_add_i32 s16, s16, s47
	v_lshl_add_u64 v[198:199], v[198:199], 0, s[36:37]
	s_mov_b32 m0, s16
	ds_read_b128 v[182:185], v149 offset:49152
	ds_read_b128 v[186:189], v149 offset:50176
	ds_read_b128 v[190:193], v149 offset:51200
	ds_read_b128 v[194:197], v149 offset:52224
	ds_read_b128 v[202:205], v149 offset:53248
	ds_read_b128 v[206:209], v149 offset:54272
	ds_read_b128 v[210:213], v149 offset:55296
	ds_read_b128 v[214:217], v149 offset:56320
	global_load_lds_dwordx4 v[198:199], off
	v_lshl_add_u64 v[198:199], v[218:219], 0, s[36:37]
	s_add_i32 m0, s16, 0x2000
	s_add_i32 s16, s17, s47
	global_load_lds_dwordx4 v[198:199], off
	v_lshl_add_u64 v[198:199], v[220:221], 0, s[36:37]
	s_mov_b32 m0, s16
	s_nop 0
	global_load_lds_dwordx4 v[198:199], off
	v_lshl_add_u64 v[198:199], v[222:223], 0, s[36:37]
	s_add_i32 m0, s16, 0x2000
	s_nop 0
	global_load_lds_dwordx4 v[198:199], off
	v_lshl_add_u64 v[198:199], v[224:225], 0, s[36:37]
	s_mov_b32 m0, s55
	s_nop 0
	global_load_lds_dwordx4 v[198:199], off
	v_lshl_add_u64 v[198:199], v[226:227], 0, s[36:37]
	s_mov_b32 m0, s56
	s_nop 0
	global_load_lds_dwordx4 v[198:199], off
	s_waitcnt vmcnt(8)
	s_waitcnt lgkmcnt(0)
	s_barrier
	s_setprio 1
	s_waitcnt lgkmcnt(0)
	v_mfma_f32_16x16x32_bf16 v[60:63], v[150:153], v[182:185], v[60:63]
	v_mfma_f32_16x16x32_bf16 v[52:55], v[158:161], v[182:185], v[52:55]
	v_mfma_f32_16x16x32_bf16 v[44:47], v[150:153], v[190:193], v[44:47]
	v_mfma_f32_16x16x32_bf16 v[36:39], v[158:161], v[190:193], v[36:39]
	v_mfma_f32_16x16x32_bf16 v[28:31], v[150:153], v[202:205], v[28:31]
	v_mfma_f32_16x16x32_bf16 v[20:23], v[158:161], v[202:205], v[20:23]
	v_mfma_f32_16x16x32_bf16 v[12:15], v[150:153], v[210:213], v[12:15]
	v_mfma_f32_16x16x32_bf16 v[4:7], v[158:161], v[210:213], v[4:7]
	v_mfma_f32_16x16x32_bf16 v[60:63], v[154:157], v[186:189], v[60:63]
	v_mfma_f32_16x16x32_bf16 v[52:55], v[162:165], v[186:189], v[52:55]
	v_mfma_f32_16x16x32_bf16 v[44:47], v[154:157], v[194:197], v[44:47]
	v_mfma_f32_16x16x32_bf16 v[36:39], v[162:165], v[194:197], v[36:39]
	v_mfma_f32_16x16x32_bf16 v[28:31], v[154:157], v[206:209], v[28:31]
	v_mfma_f32_16x16x32_bf16 v[20:23], v[162:165], v[206:209], v[20:23]
	v_mfma_f32_16x16x32_bf16 v[12:15], v[154:157], v[214:217], v[12:15]
	v_mfma_f32_16x16x32_bf16 v[4:7], v[162:165], v[214:217], v[4:7]
	s_setprio 0
	s_setprio 1
	v_mfma_f32_16x16x32_bf16 v[56:59], v[166:169], v[182:185], v[56:59]
	v_mfma_f32_16x16x32_bf16 v[48:51], v[174:177], v[182:185], v[48:51]
	v_mfma_f32_16x16x32_bf16 v[40:43], v[166:169], v[190:193], v[40:43]
	v_mfma_f32_16x16x32_bf16 v[32:35], v[174:177], v[190:193], v[32:35]
	v_mfma_f32_16x16x32_bf16 v[24:27], v[166:169], v[202:205], v[24:27]
	v_mfma_f32_16x16x32_bf16 v[16:19], v[174:177], v[202:205], v[16:19]
	v_mfma_f32_16x16x32_bf16 v[8:11], v[166:169], v[210:213], v[8:11]
	v_mfma_f32_16x16x32_bf16 v[0:3], v[174:177], v[210:213], v[0:3]
	v_mfma_f32_16x16x32_bf16 v[56:59], v[170:173], v[186:189], v[56:59]
	v_mfma_f32_16x16x32_bf16 v[48:51], v[178:181], v[186:189], v[48:51]
	v_mfma_f32_16x16x32_bf16 v[40:43], v[170:173], v[194:197], v[40:43]
	v_mfma_f32_16x16x32_bf16 v[32:35], v[178:181], v[194:197], v[32:35]
	v_mfma_f32_16x16x32_bf16 v[24:27], v[170:173], v[206:209], v[24:27]
	v_mfma_f32_16x16x32_bf16 v[16:19], v[178:181], v[206:209], v[16:19]
	v_mfma_f32_16x16x32_bf16 v[8:11], v[170:173], v[214:217], v[8:11]
	v_mfma_f32_16x16x32_bf16 v[0:3], v[178:181], v[214:217], v[0:3]
	s_setprio 0
	s_barrier
	s_add_u32 s42, s42, 0x100
	s_addc_u32 s43, s43, 0
	s_add_u32 s68, s68, 0x100
	s_addc_u32 s69, s69, 0
	s_cmp_ge_i32 s70, s57
	s_mov_b32 s44, s70
	s_cbranch_scc1 .LBB0_1022

; #define PG8_STAGE(bufoff, gbase, voff) do { _Pragma("unroll") for (int _i = 0; _i < 2; ++_i) \
;         __builtin_amdgcn_global_load_lds((const unsigned*)((const char*)(gbase) + (voff)[_i]), (PG8_LAS unsigned*)(lds + (bufoff) + ldsw + _i * 8192), 16, 0, 0); } while (0)
; #define PG8_LDA(dst, b, h) do { _Pragma("unroll") for (int m = 0; m < 4; ++m) _Pragma("unroll") for (int k = 0; k < 2; ++k) dst[m][k] = *(const PG8_LAS bf16x8*)(lds + PG8_SA(b, h) + aoff + m * 2048 + k * 1024); } while (0)
; #define PG8_LDB(dst, b, h) do { _Pragma("unroll") for (int n = 0; n < 2; ++n) _Pragma("unroll") for (int k = 0; k < 2; ++k) dst[n][k] = *(const PG8_LAS bf16x8*)(lds + PG8_SB(b, h) + boff + n * 2048 + k * 1024); } while (0)
; #define PG8_MMA(ai, bj, At, Bt) do { __builtin_amdgcn_s_setprio(1); _Pragma("unroll") for (int m = 0; m < 4; ++m) _Pragma("unroll") for (int n = 0; n < 2; ++n) _Pragma("unroll") for (int k = 0; k < 2; ++k) \
;         acc[ai][bj][m][n] = __builtin_amdgcn_mfma_f32_16x16x32_bf16(Bt[n][k], At[m][k], acc[ai][bj][m][n], 0, 0, 0); __builtin_amdgcn_s_setprio(0); } while (0)
; #define PG8_WAIT_V(n) asm volatile("s_waitcnt vmcnt(" #n ")" ::: "memory")
; #define PG8_WAIT_L(n) asm volatile("s_waitcnt lgkmcnt(" #n ")" ::: "memory")
; #define PG8_BAR __builtin_amdgcn_s_barrier()
; #define PG8_SCHED __builtin_amdgcn_sched_barrier(0)
; template <class Epi, class Sched, bool ALIGN_EPI = false, bool SP2 = false>
; __device__ __forceinline__ void gemm_phase(PG8_LAS unsigned char* lds, const Gemm g, const Sched& S, const Epi& E) {
;     ...
;             PG8_LDB(B0, 0, 0); PG8_LDB(B1, 0, 1); PG8_SCHED; PG8_LDA(At, 0, 0); PG8_STAGE(PG8_SA(1, 1), a1 + hstep, voffA);
;             PG8_WAIT_V(8); PG8_WAIT_L(0); PG8_BAR; PG8_MMA(0, 0, At, B0); PG8_MMA(0, 1, At, B1); PG8_BAR; PG8_SCHED;
;             PG8_LDA(At, 0, 1); PG8_STAGE(PG8_SB(0, 0), b2, voffB); PG8_STAGE(PG8_SB(0, 1), b2 + hstep, voffB); PG8_STAGE(PG8_SA(0, 0), a2, voffA);
;             PG8_WAIT_V(8); PG8_WAIT_L(0); PG8_BAR; PG8_MMA(1, 0, At, B0); PG8_MMA(1, 1, At, B1); PG8_BAR; PG8_SCHED;
.Lcz_go_1104:
	s_add_u32 s44, s44, 0x8000
	s_addc_u32 s45, s45, 0
	s_add_u32 s68, s46, 0x100
	s_addc_u32 s69, s47, 0
	s_mov_b32 s46, 0
	.p2alignl 6, 3212836864
	ds_read_b128 v[144:147], v151
	ds_read_b128 v[156:159], v151 offset:1024
	ds_read_b128 v[160:163], v151 offset:2048
	ds_read_b128 v[164:167], v151 offset:3072
	ds_read_b128 v[168:171], v152
	ds_read_b128 v[172:175], v152 offset:1024
	ds_read_b128 v[176:179], v152 offset:2048
	ds_read_b128 v[180:183], v152 offset:3072
	s_add_i32 s70, s46, 2
	s_add_u32 s16, s44, 0x8000
	s_addc_u32 s17, s45, 0
	s_cmp_eq_u32 s58, s46
	s_cselect_b32 s46, s0, s16
	s_cselect_b32 s47, s1, s17
	s_cselect_b32 s73, s43, s69
	s_cselect_b32 s72, s42, s68
	v_lshl_add_u64 v[218:219], s[44:45], 0, v[136:137]
	s_add_i32 m0, s50, 0xc000
	ds_read_b128 v[184:187], v153
	ds_read_b128 v[188:191], v153 offset:1024
	ds_read_b128 v[192:195], v153 offset:2048
	ds_read_b128 v[196:199], v153 offset:3072
	ds_read_b128 v[202:205], v153 offset:4096
	ds_read_b128 v[206:209], v153 offset:5120
	ds_read_b128 v[210:213], v153 offset:6144
	ds_read_b128 v[214:217], v153 offset:7168
	global_load_lds_dwordx4 v[218:219], off
	v_lshl_add_u64 v[218:219], s[44:45], 0, v[138:139]
	s_add_i32 m0, s50, 0xe000
	s_nop 0
	global_load_lds_dwordx4 v[218:219], off
	s_waitcnt vmcnt(8)
	s_waitcnt lgkmcnt(0)
	s_barrier
	s_setprio 1
	s_waitcnt lgkmcnt(0)
	v_mfma_f32_16x16x32_bf16 v[124:127], v[144:147], v[184:187], 0
	v_mfma_f32_16x16x32_bf16 v[120:123], v[160:163], v[184:187], 0
	v_mfma_f32_16x16x32_bf16 v[108:111], v[144:147], v[192:195], 0
	v_mfma_f32_16x16x32_bf16 v[104:107], v[160:163], v[192:195], 0
	v_mfma_f32_16x16x32_bf16 v[92:95], v[144:147], v[202:205], 0
	v_mfma_f32_16x16x32_bf16 v[88:91], v[160:163], v[202:205], 0
	v_mfma_f32_16x16x32_bf16 v[76:79], v[144:147], v[210:213], 0
	v_mfma_f32_16x16x32_bf16 v[72:75], v[160:163], v[210:213], 0
	v_mfma_f32_16x16x32_bf16 v[124:127], v[156:159], v[188:191], v[124:127]
	v_mfma_f32_16x16x32_bf16 v[120:123], v[164:167], v[188:191], v[120:123]
	v_mfma_f32_16x16x32_bf16 v[108:111], v[156:159], v[196:199], v[108:111]
	v_mfma_f32_16x16x32_bf16 v[104:107], v[164:167], v[196:199], v[104:107]
	v_mfma_f32_16x16x32_bf16 v[92:95], v[156:159], v[206:209], v[92:95]
	v_mfma_f32_16x16x32_bf16 v[88:91], v[164:167], v[206:209], v[88:91]
	v_mfma_f32_16x16x32_bf16 v[76:79], v[156:159], v[214:217], v[76:79]
	v_mfma_f32_16x16x32_bf16 v[72:75], v[164:167], v[214:217], v[72:75]
	s_setprio 0
	s_setprio 1
	v_mfma_f32_16x16x32_bf16 v[116:119], v[168:171], v[184:187], 0
	v_mfma_f32_16x16x32_bf16 v[112:115], v[176:179], v[184:187], 0
	v_mfma_f32_16x16x32_bf16 v[100:103], v[168:171], v[192:195], 0
	v_mfma_f32_16x16x32_bf16 v[96:99], v[176:179], v[192:195], 0
	v_mfma_f32_16x16x32_bf16 v[84:87], v[168:171], v[202:205], 0
	v_mfma_f32_16x16x32_bf16 v[80:83], v[176:179], v[202:205], 0
	v_mfma_f32_16x16x32_bf16 v[68:71], v[168:171], v[210:213], 0
	v_mfma_f32_16x16x32_bf16 v[64:67], v[176:179], v[210:213], 0
	v_mfma_f32_16x16x32_bf16 v[116:119], v[172:175], v[188:191], v[116:119]
	v_mfma_f32_16x16x32_bf16 v[112:115], v[180:183], v[188:191], v[112:115]
	v_mfma_f32_16x16x32_bf16 v[100:103], v[172:175], v[196:199], v[100:103]
	v_mfma_f32_16x16x32_bf16 v[96:99], v[180:183], v[196:199], v[96:99]
	v_mfma_f32_16x16x32_bf16 v[84:87], v[172:175], v[206:209], v[84:87]
	v_mfma_f32_16x16x32_bf16 v[80:83], v[180:183], v[206:209], v[80:83]
	v_mfma_f32_16x16x32_bf16 v[68:71], v[172:175], v[214:217], v[68:71]
	v_mfma_f32_16x16x32_bf16 v[64:67], v[180:183], v[214:217], v[64:67]
	s_setprio 0
	s_barrier
	s_add_i32 s16, s62, s49
	v_lshl_add_u64 v[218:219], s[72:73], 0, v[130:131]
	s_mov_b32 m0, s16
	ds_read_b128 v[184:187], v153 offset:16384
	ds_read_b128 v[188:191], v153 offset:17408
	ds_read_b128 v[192:195], v153 offset:18432
	ds_read_b128 v[196:199], v153 offset:19456
	ds_read_b128 v[202:205], v153 offset:20480
	ds_read_b128 v[206:209], v153 offset:21504
	ds_read_b128 v[210:213], v153 offset:22528
	ds_read_b128 v[214:217], v153 offset:23552
	global_load_lds_dwordx4 v[218:219], off
	s_add_i32 m0, s16, 0x2000
	v_lshl_add_u64 v[220:221], s[72:73], 0, v[134:135]
	s_add_u32 s72, s72, s8
	s_addc_u32 s73, s73, s9
	s_add_i32 s16, s63, s49
	global_load_lds_dwordx4 v[220:221], off
	v_lshl_add_u64 v[222:223], s[72:73], 0, v[130:131]
	s_mov_b32 m0, s16
	v_lshl_add_u64 v[224:225], s[72:73], 0, v[134:135]
	global_load_lds_dwordx4 v[222:223], off
	s_add_i32 m0, s16, 0x2000
	v_lshl_add_u64 v[226:227], s[46:47], 0, v[128:129]
	global_load_lds_dwordx4 v[224:225], off
	s_mov_b32 m0, s50
	v_lshl_add_u64 v[228:229], s[46:47], 0, v[132:133]
	global_load_lds_dwordx4 v[226:227], off
	s_mov_b32 m0, s51
	s_nop 0
	global_load_lds_dwordx4 v[228:229], off
	s_waitcnt vmcnt(8)
	s_waitcnt lgkmcnt(0)
	s_barrier
; #define PG8_STAGE(bufoff, gbase, voff) do { _Pragma("unroll") for (int _i = 0; _i < 2; ++_i) \
;         __builtin_amdgcn_global_load_lds((const unsigned*)((const char*)(gbase) + (voff)[_i]), (PG8_LAS unsigned*)(lds + (bufoff) + ldsw + _i * 8192), 16, 0, 0); } while (0)
; #define PG8_LDA(dst, b, h) do { _Pragma("unroll") for (int m = 0; m < 4; ++m) _Pragma("unroll") for (int k = 0; k < 2; ++k) dst[m][k] = *(const PG8_LAS bf16x8*)(lds + PG8_SA(b, h) + aoff + m * 2048 + k * 1024); } while (0)
; #define PG8_LDB(dst, b, h) do { _Pragma("unroll") for (int n = 0; n < 2; ++n) _Pragma("unroll") for (int k = 0; k < 2; ++k) dst[n][k] = *(const PG8_LAS bf16x8*)(lds + PG8_SB(b, h) + boff + n * 2048 + k * 1024); } while (0)
; #define PG8_MMA(ai, bj, At, Bt) do { __builtin_amdgcn_s_setprio(1); _Pragma("unroll") for (int m = 0; m < 4; ++m) _Pragma("unroll") for (int n = 0; n < 2; ++n) _Pragma("unroll") for (int k = 0; k < 2; ++k) \
;         acc[ai][bj][m][n] = __builtin_amdgcn_mfma_f32_16x16x32_bf16(Bt[n][k], At[m][k], acc[ai][bj][m][n], 0, 0, 0); __builtin_amdgcn_s_setprio(0); } while (0)
; #define PG8_WAIT_V(n) asm volatile("s_waitcnt vmcnt(" #n ")" ::: "memory")
; #define PG8_WAIT_L(n) asm volatile("s_waitcnt lgkmcnt(" #n ")" ::: "memory")
; #define PG8_BAR __builtin_amdgcn_s_barrier()
; #define PG8_SCHED __builtin_amdgcn_sched_barrier(0)
; template <class Epi, class Sched, bool ALIGN_EPI = false, bool SP2 = false>
; __device__ __forceinline__ void gemm_phase(PG8_LAS unsigned char* lds, const Gemm g, const Sched& S, const Epi& E) {
;     ...
;             PG8_WAIT_V(8); PG8_WAIT_L(0); PG8_BAR; PG8_MMA(1, 0, At, B0); PG8_MMA(1, 1, At, B1); PG8_BAR; PG8_SCHED;
;             PG8_LDB(B0, 1, 0); PG8_LDB(B1, 1, 1); PG8_SCHED; PG8_LDA(At, 1, 0); PG8_STAGE(PG8_SA(0, 1), a2 + hstep, voffA);
;             PG8_WAIT_V(8); PG8_WAIT_L(0); PG8_BAR; PG8_MMA(0, 0, At, B0); PG8_MMA(0, 1, At, B1); PG8_BAR; PG8_SCHED;
	s_setprio 1
	s_waitcnt lgkmcnt(0)
	v_mfma_f32_16x16x32_bf16 v[60:63], v[144:147], v[184:187], 0
	v_mfma_f32_16x16x32_bf16 v[56:59], v[160:163], v[184:187], 0
	v_mfma_f32_16x16x32_bf16 v[44:47], v[144:147], v[192:195], 0
	v_mfma_f32_16x16x32_bf16 v[40:43], v[160:163], v[192:195], 0
	v_mfma_f32_16x16x32_bf16 v[28:31], v[144:147], v[202:205], 0
	v_mfma_f32_16x16x32_bf16 v[24:27], v[160:163], v[202:205], 0
	v_mfma_f32_16x16x32_bf16 v[12:15], v[144:147], v[210:213], 0
	v_mfma_f32_16x16x32_bf16 v[8:11], v[160:163], v[210:213], 0
	v_mfma_f32_16x16x32_bf16 v[60:63], v[156:159], v[188:191], v[60:63]
	v_mfma_f32_16x16x32_bf16 v[56:59], v[164:167], v[188:191], v[56:59]
	v_mfma_f32_16x16x32_bf16 v[44:47], v[156:159], v[196:199], v[44:47]
	v_mfma_f32_16x16x32_bf16 v[40:43], v[164:167], v[196:199], v[40:43]
	v_mfma_f32_16x16x32_bf16 v[28:31], v[156:159], v[206:209], v[28:31]
	v_mfma_f32_16x16x32_bf16 v[24:27], v[164:167], v[206:209], v[24:27]
	v_mfma_f32_16x16x32_bf16 v[12:15], v[156:159], v[214:217], v[12:15]
	v_mfma_f32_16x16x32_bf16 v[8:11], v[164:167], v[214:217], v[8:11]
	s_setprio 0
	s_setprio 1
	v_mfma_f32_16x16x32_bf16 v[52:55], v[168:171], v[184:187], 0
	v_mfma_f32_16x16x32_bf16 v[48:51], v[176:179], v[184:187], 0
	v_mfma_f32_16x16x32_bf16 v[36:39], v[168:171], v[192:195], 0
	v_mfma_f32_16x16x32_bf16 v[32:35], v[176:179], v[192:195], 0
	v_mfma_f32_16x16x32_bf16 v[20:23], v[168:171], v[202:205], 0
	v_mfma_f32_16x16x32_bf16 v[16:19], v[176:179], v[202:205], 0
	v_mfma_f32_16x16x32_bf16 v[4:7], v[168:171], v[210:213], 0
	v_mfma_f32_16x16x32_bf16 v[0:3], v[176:179], v[210:213], 0
	v_mfma_f32_16x16x32_bf16 v[52:55], v[172:175], v[188:191], v[52:55]
	v_mfma_f32_16x16x32_bf16 v[48:51], v[180:183], v[188:191], v[48:51]
	v_mfma_f32_16x16x32_bf16 v[36:39], v[172:175], v[196:199], v[36:39]
	v_mfma_f32_16x16x32_bf16 v[32:35], v[180:183], v[196:199], v[32:35]
	v_mfma_f32_16x16x32_bf16 v[20:23], v[172:175], v[206:209], v[20:23]
	v_mfma_f32_16x16x32_bf16 v[16:19], v[180:183], v[206:209], v[16:19]
	v_mfma_f32_16x16x32_bf16 v[4:7], v[172:175], v[214:217], v[4:7]
	v_mfma_f32_16x16x32_bf16 v[0:3], v[180:183], v[214:217], v[0:3]
	s_setprio 0
	s_barrier
	s_add_i32 s16, 0, 0x18000
	v_add_u32_e32 v155, s16, v149
	s_add_i32 s17, 0, 0x1c000
	ds_read_b128 v[144:147], v155
	ds_read_b128 v[156:159], v155 offset:1024
	ds_read_b128 v[160:163], v155 offset:2048
	ds_read_b128 v[164:167], v155 offset:3072
	v_add_u32_e32 v155, s17, v149
	ds_read_b128 v[168:171], v155
	ds_read_b128 v[172:175], v155 offset:1024
	ds_read_b128 v[176:179], v155 offset:2048
	ds_read_b128 v[180:183], v155 offset:3072
	s_add_u32 s46, s46, 0x2000
	s_addc_u32 s47, s47, 0
	s_mov_b32 m0, s52
	v_lshl_add_u64 v[230:231], s[46:47], 0, v[128:129]
	ds_read_b128 v[184:187], v153 offset:32768
	ds_read_b128 v[188:191], v153 offset:33792
	ds_read_b128 v[192:195], v153 offset:34816
	ds_read_b128 v[196:199], v153 offset:35840
	ds_read_b128 v[202:205], v153 offset:36864
	ds_read_b128 v[206:209], v153 offset:37888
	ds_read_b128 v[210:213], v153 offset:38912
	ds_read_b128 v[214:217], v153 offset:39936
	global_load_lds_dwordx4 v[230:231], off
	v_lshl_add_u64 v[230:231], s[46:47], 0, v[132:133]
	s_mov_b32 m0, s53
	s_nop 0
	global_load_lds_dwordx4 v[230:231], off
	s_waitcnt vmcnt(8)
	s_waitcnt lgkmcnt(0)
	s_barrier
	s_setprio 1
	s_waitcnt lgkmcnt(0)
	v_mfma_f32_16x16x32_bf16 v[124:127], v[144:147], v[184:187], v[124:127]
	v_mfma_f32_16x16x32_bf16 v[120:123], v[160:163], v[184:187], v[120:123]
	v_mfma_f32_16x16x32_bf16 v[108:111], v[144:147], v[192:195], v[108:111]
	v_mfma_f32_16x16x32_bf16 v[104:107], v[160:163], v[192:195], v[104:107]
	v_mfma_f32_16x16x32_bf16 v[92:95], v[144:147], v[202:205], v[92:95]
	v_mfma_f32_16x16x32_bf16 v[88:91], v[160:163], v[202:205], v[88:91]
	v_mfma_f32_16x16x32_bf16 v[76:79], v[144:147], v[210:213], v[76:79]
	v_mfma_f32_16x16x32_bf16 v[72:75], v[160:163], v[210:213], v[72:75]
	v_mfma_f32_16x16x32_bf16 v[124:127], v[156:159], v[188:191], v[124:127]
	v_mfma_f32_16x16x32_bf16 v[120:123], v[164:167], v[188:191], v[120:123]
	v_mfma_f32_16x16x32_bf16 v[108:111], v[156:159], v[196:199], v[108:111]
	v_mfma_f32_16x16x32_bf16 v[104:107], v[164:167], v[196:199], v[104:107]
	v_mfma_f32_16x16x32_bf16 v[92:95], v[156:159], v[206:209], v[92:95]
	v_mfma_f32_16x16x32_bf16 v[88:91], v[164:167], v[206:209], v[88:91]
	v_mfma_f32_16x16x32_bf16 v[76:79], v[156:159], v[214:217], v[76:79]
	v_mfma_f32_16x16x32_bf16 v[72:75], v[164:167], v[214:217], v[72:75]
	s_setprio 0
	s_setprio 1
	v_mfma_f32_16x16x32_bf16 v[116:119], v[168:171], v[184:187], v[116:119]
	v_mfma_f32_16x16x32_bf16 v[112:115], v[176:179], v[184:187], v[112:115]
	v_mfma_f32_16x16x32_bf16 v[100:103], v[168:171], v[192:195], v[100:103]
	v_mfma_f32_16x16x32_bf16 v[96:99], v[176:179], v[192:195], v[96:99]
	v_mfma_f32_16x16x32_bf16 v[84:87], v[168:171], v[202:205], v[84:87]
	v_mfma_f32_16x16x32_bf16 v[80:83], v[176:179], v[202:205], v[80:83]
	v_mfma_f32_16x16x32_bf16 v[68:71], v[168:171], v[210:213], v[68:71]
	v_mfma_f32_16x16x32_bf16 v[64:67], v[176:179], v[210:213], v[64:67]
	v_mfma_f32_16x16x32_bf16 v[116:119], v[172:175], v[188:191], v[116:119]
	v_mfma_f32_16x16x32_bf16 v[112:115], v[180:183], v[188:191], v[112:115]
	v_mfma_f32_16x16x32_bf16 v[100:103], v[172:175], v[196:199], v[100:103]
	v_mfma_f32_16x16x32_bf16 v[96:99], v[180:183], v[196:199], v[96:99]
	v_mfma_f32_16x16x32_bf16 v[84:87], v[172:175], v[206:209], v[84:87]
	v_mfma_f32_16x16x32_bf16 v[80:83], v[180:183], v[206:209], v[80:83]
	v_mfma_f32_16x16x32_bf16 v[68:71], v[172:175], v[214:217], v[68:71]
	v_mfma_f32_16x16x32_bf16 v[64:67], v[180:183], v[214:217], v[64:67]
	s_setprio 0
	s_barrier
; #define PG8_STAGE(bufoff, gbase, voff) do { _Pragma("unroll") for (int _i = 0; _i < 2; ++_i) \
;         __builtin_amdgcn_global_load_lds((const unsigned*)((const char*)(gbase) + (voff)[_i]), (PG8_LAS unsigned*)(lds + (bufoff) + ldsw + _i * 8192), 16, 0, 0); } while (0)
; #define PG8_LDA(dst, b, h) do { _Pragma("unroll") for (int m = 0; m < 4; ++m) _Pragma("unroll") for (int k = 0; k < 2; ++k) dst[m][k] = *(const PG8_LAS bf16x8*)(lds + PG8_SA(b, h) + aoff + m * 2048 + k * 1024); } while (0)
; #define PG8_MMA(ai, bj, At, Bt) do { __builtin_amdgcn_s_setprio(1); _Pragma("unroll") for (int m = 0; m < 4; ++m) _Pragma("unroll") for (int n = 0; n < 2; ++n) _Pragma("unroll") for (int k = 0; k < 2; ++k) \
;         acc[ai][bj][m][n] = __builtin_amdgcn_mfma_f32_16x16x32_bf16(Bt[n][k], At[m][k], acc[ai][bj][m][n], 0, 0, 0); __builtin_amdgcn_s_setprio(0); } while (0)
; #define PG8_WAIT_V(n) asm volatile("s_waitcnt vmcnt(" #n ")" ::: "memory")
; #define PG8_WAIT_L(n) asm volatile("s_waitcnt lgkmcnt(" #n ")" ::: "memory")
; #define PG8_BAR __builtin_amdgcn_s_barrier()
; #define PG8_SCHED __builtin_amdgcn_sched_barrier(0)
; template <class Epi, class Sched, bool ALIGN_EPI = false, bool SP2 = false>
; __device__ __forceinline__ void gemm_phase(PG8_LAS unsigned char* lds, const Gemm g, const Sched& S, const Epi& E) {
;     ...
;         for (int t = 0; t < nt; t += 2) {
;             const bool last = (t == nt - 2);
;             const char* a1 = cA + (size_t)(t + 1) * kstep;
;             const char* a2 = last ? nA : cA + (size_t)(t + 2) * kstep; const char* b2 = last ? nB : cB + (size_t)(t + 2) * kstep;
;             const char* a3 = a2 + kstep; const char* b3 = b2 + kstep;
;     ...
;             PG8_LDA(At, 1, 1); PG8_STAGE(PG8_SB(1, 0), b3, voffB); PG8_STAGE(PG8_SB(1, 1), b3 + hstep, voffB); PG8_STAGE(PG8_SA(1, 0), a3, voffA);
;             PG8_WAIT_V(8); PG8_WAIT_L(0); PG8_BAR; PG8_MMA(1, 0, At, B0); PG8_MMA(1, 1, At, B1); PG8_BAR; PG8_SCHED;
	s_add_i32 s16, s16, s49
	v_lshl_add_u64 v[218:219], v[218:219], 0, s[36:37]
	s_mov_b32 m0, s16
	ds_read_b128 v[184:187], v153 offset:49152
	ds_read_b128 v[188:191], v153 offset:50176
	ds_read_b128 v[192:195], v153 offset:51200
	ds_read_b128 v[196:199], v153 offset:52224
	ds_read_b128 v[202:205], v153 offset:53248
	ds_read_b128 v[206:209], v153 offset:54272
	ds_read_b128 v[210:213], v153 offset:55296
	ds_read_b128 v[214:217], v153 offset:56320
	global_load_lds_dwordx4 v[218:219], off
	v_lshl_add_u64 v[218:219], v[220:221], 0, s[36:37]
	s_add_i32 m0, s16, 0x2000
	s_add_i32 s16, s17, s49
	global_load_lds_dwordx4 v[218:219], off
	v_lshl_add_u64 v[218:219], v[222:223], 0, s[36:37]
	s_mov_b32 m0, s16
	s_nop 0
	global_load_lds_dwordx4 v[218:219], off
	v_lshl_add_u64 v[218:219], v[224:225], 0, s[36:37]
	s_add_i32 m0, s16, 0x2000
	s_nop 0
	global_load_lds_dwordx4 v[218:219], off
	v_lshl_add_u64 v[218:219], v[226:227], 0, s[100:101]
	s_mov_b32 m0, s54
	s_nop 0
	global_load_lds_dwordx4 v[218:219], off
	v_lshl_add_u64 v[218:219], v[228:229], 0, s[100:101]
	s_mov_b32 m0, s55
	s_nop 0
	global_load_lds_dwordx4 v[218:219], off
	s_waitcnt vmcnt(8)
	s_waitcnt lgkmcnt(0)
	s_barrier
	s_setprio 1
	s_waitcnt lgkmcnt(0)
	v_mfma_f32_16x16x32_bf16 v[60:63], v[144:147], v[184:187], v[60:63]
	v_mfma_f32_16x16x32_bf16 v[56:59], v[160:163], v[184:187], v[56:59]
	v_mfma_f32_16x16x32_bf16 v[44:47], v[144:147], v[192:195], v[44:47]
	v_mfma_f32_16x16x32_bf16 v[40:43], v[160:163], v[192:195], v[40:43]
	v_mfma_f32_16x16x32_bf16 v[28:31], v[144:147], v[202:205], v[28:31]
	v_mfma_f32_16x16x32_bf16 v[24:27], v[160:163], v[202:205], v[24:27]
	v_mfma_f32_16x16x32_bf16 v[12:15], v[144:147], v[210:213], v[12:15]
	v_mfma_f32_16x16x32_bf16 v[8:11], v[160:163], v[210:213], v[8:11]
	v_mfma_f32_16x16x32_bf16 v[60:63], v[156:159], v[188:191], v[60:63]
	v_mfma_f32_16x16x32_bf16 v[56:59], v[164:167], v[188:191], v[56:59]
	v_mfma_f32_16x16x32_bf16 v[44:47], v[156:159], v[196:199], v[44:47]
	v_mfma_f32_16x16x32_bf16 v[40:43], v[164:167], v[196:199], v[40:43]
	v_mfma_f32_16x16x32_bf16 v[28:31], v[156:159], v[206:209], v[28:31]
	v_mfma_f32_16x16x32_bf16 v[24:27], v[164:167], v[206:209], v[24:27]
	v_mfma_f32_16x16x32_bf16 v[12:15], v[156:159], v[214:217], v[12:15]
	v_mfma_f32_16x16x32_bf16 v[8:11], v[164:167], v[214:217], v[8:11]
	s_setprio 0
	s_setprio 1
	v_mfma_f32_16x16x32_bf16 v[52:55], v[168:171], v[184:187], v[52:55]
	v_mfma_f32_16x16x32_bf16 v[48:51], v[176:179], v[184:187], v[48:51]
	v_mfma_f32_16x16x32_bf16 v[36:39], v[168:171], v[192:195], v[36:39]
	v_mfma_f32_16x16x32_bf16 v[32:35], v[176:179], v[192:195], v[32:35]
	v_mfma_f32_16x16x32_bf16 v[20:23], v[168:171], v[202:205], v[20:23]
	v_mfma_f32_16x16x32_bf16 v[16:19], v[176:179], v[202:205], v[16:19]
	v_mfma_f32_16x16x32_bf16 v[4:7], v[168:171], v[210:213], v[4:7]
	v_mfma_f32_16x16x32_bf16 v[0:3], v[176:179], v[210:213], v[0:3]
	v_mfma_f32_16x16x32_bf16 v[52:55], v[172:175], v[188:191], v[52:55]
	v_mfma_f32_16x16x32_bf16 v[48:51], v[180:183], v[188:191], v[48:51]
	v_mfma_f32_16x16x32_bf16 v[36:39], v[172:175], v[196:199], v[36:39]
	v_mfma_f32_16x16x32_bf16 v[32:35], v[180:183], v[196:199], v[32:35]
	v_mfma_f32_16x16x32_bf16 v[20:23], v[172:175], v[206:209], v[20:23]
	v_mfma_f32_16x16x32_bf16 v[16:19], v[180:183], v[206:209], v[16:19]
	v_mfma_f32_16x16x32_bf16 v[4:7], v[172:175], v[214:217], v[4:7]
	v_mfma_f32_16x16x32_bf16 v[0:3], v[180:183], v[214:217], v[0:3]
	s_setprio 0
	s_barrier
	s_add_u32 s44, s44, 0x10000
	s_addc_u32 s45, s45, 0
	s_add_u32 s68, s68, 0x100
	s_addc_u32 s69, s69, 0
	s_cmp_ge_i32 s70, s57
	s_mov_b32 s46, s70
	s_cbranch_scc1 .LBB0_1105
